# row2: group fetched once + prefetch rings, per-workgroup aggregation of routing atomics
# speedup vs baseline: 1.1031x; 1.0414x over previous
; #define TIDX tid_opaque()
; DI void row2_phase(const Params& P, int l, int r_begin, char* smem) {
;   const int tid = TIDX, lane = tid & 63, wave = tid >> 6, fr = lane & 15, fq = lane >> 4;
;   float* lg = (float*)smem + wave * 16 * 48;
;   const half_t* Whi = P.WrH + (size_t)(l * 2) * 49152; const half_t* Wlo = Whi + 49152;
;   const int ngroups = (TA - r_begin) >> 4, gw = blockIdx.x * 4 + wave, nw = gridDim.x * 4;
;   const float* gam = P.norm2_g + l * 1024;
;   const int gper = (ngroups + nw - 1) / nw;
; #pragma unroll 1
;   for (int grp = gw * gper; grp < min((gw + 1) * gper, ngroups); grp++) {
.LBB0_542:
	s_or_b64 exec, exec, s[0:1]
	v_readlane_b32 s0, v255, 48
	v_readlane_b32 s1, v255, 49
	s_and_b64 s[0:1], s[0:1], exec
	s_cselect_b32 s22, 0, 0x800
	v_mov_b32_e32 v1, v172
	s_lshr_b32 s0, s22, 4
	s_barrier
	v_accvgpr_write_b32 a255, v104
	v_and_b32_e32 v104, 0xff, v172
	v_lshlrev_b32_e32 v104, 4, v104
	v_add_u32_e32 v104, 0x4000, v104
	ds_write_b128 v104, v[84:87] offset:0
	ds_write_b128 v104, v[88:91] offset:4096
	ds_write_b128 v104, v[92:95] offset:8192
	ds_write_b128 v104, v[96:99] offset:12288
	ds_write_b128 v104, v[100:103] offset:16384
	s_waitcnt lgkmcnt(0)
	v_accvgpr_read_b32 v104, a255
	v_mov_b32_e32 v84, 0
	v_lshlrev_b32_e32 v85, 2, v172
	v_add_u32_e32 v85, 0x3000, v85
	ds_write_b32 v85, v84
	s_waitcnt lgkmcnt(0)
	s_barrier
	s_xor_b32 s1, s0, 0x1080
	v_ashrrev_i32_e32 v2, 6, v1
	v_readlane_b32 s0, v254, 20
	v_readlane_b32 s3, v254, 22
	v_readlane_b32 s6, v254, 25
	v_add_u32_e32 v0, s0, v2
	v_readlane_b32 s0, v254, 21
	s_add_i32 s0, s0, s1
	s_ashr_i32 s2, s0, 31
	s_xor_b32 s2, s2, s3
	s_abs_i32 s0, s0
	v_readlane_b32 s3, v254, 26
	s_mul_hi_u32 s3, s0, s3
	s_mul_i32 s4, s3, s6
	s_sub_i32 s0, s0, s4
	s_add_i32 s4, s3, 1
	s_sub_i32 s5, s0, s6
	s_cmp_ge_u32 s0, s6
	s_cselect_b32 s3, s4, s3
	s_cselect_b32 s0, s5, s0
	s_add_i32 s4, s3, 1
	s_cmp_ge_u32 s0, s6
	s_cselect_b32 s0, s4, s3
	s_xor_b32 s0, s0, s2
	s_sub_i32 s0, s0, s2
	v_mul_lo_u32 v17, v0, s0
	v_add_u32_e32 v3, s0, v17
	v_min_i32_e32 v52, s1, v3
	v_cmp_lt_i32_e32 vcc, v17, v52
	s_and_saveexec_b64 s[10:11], vcc
	s_cbranch_execz .LBB0_551
	v_readlane_b32 s2, v254, 39
	v_readlane_b32 s48, v255, 3
	v_readlane_b32 s3, v254, 40
	v_readlane_b32 s56, v255, 11
	v_readlane_b32 s57, v255, 12
	v_readlane_b32 s58, v255, 13
	v_readlane_b32 s59, v255, 14
	v_readlane_b32 s60, v255, 15
	v_readlane_b32 s61, v255, 16
	s_mov_b32 s3, s85
	v_readlane_b32 s62, v255, 17
	v_readlane_b32 s63, v255, 18
	s_mov_b64 s[56:57], s[60:61]
	s_lshl_b64 s[2:3], s[2:3], 2
	s_mov_b64 s[58:59], s[62:63]
	v_readlane_b32 s49, v255, 4
	v_readlane_b32 s50, v255, 5
	v_readlane_b32 s51, v255, 6
	v_readlane_b32 s52, v255, 7
	v_readlane_b32 s53, v255, 8
	v_readlane_b32 s54, v255, 9
	v_readlane_b32 s55, v255, 10
	s_add_u32 s2, s58, s2
	s_addc_u32 s3, s59, s3
	s_movk_i32 s1, 0xc00
	v_bfe_u32 v4, v1, 4, 2
	v_readlane_b32 s4, v255, 26
	v_readlane_b32 s48, v253, 35
	v_and_b32_e32 v53, 63, v1
	v_and_b32_e32 v54, 15, v1
	v_mul_lo_u32 v3, v2, s1
	v_lshlrev_b32_e32 v12, 5, v4
	v_mov_b32_e32 v13, v149
	s_movk_i32 s1, 0xc0
	s_lshl_b32 s23, s4, 5
	v_readlane_b32 s50, v253, 37
	v_readlane_b32 s6, v254, 41
	v_mul_lo_u32 v0, v0, s0
	v_lshlrev_b32_e32 v2, 3, v4
	v_lshl_add_u64 v[14:15], s[2:3], 0, v[12:13]
	v_lshl_or_b32 v5, v54, 2, v3
	v_mad_u32_u24 v13, v53, s1, v3
	v_mul_u32_u24_e32 v3, 0x300, v4
	v_readlane_b32 s51, v253, 38
	v_readlane_b32 s7, v254, 42
	s_add_u32 s8, s50, s6
	s_mul_hi_u32 s1, s4, 0x30000
	s_mul_i32 s4, s4, 0x30000
	v_lshlrev_b32_e32 v4, 11, v54
	v_and_b32_e32 v16, 48, v1
	v_lshlrev_b32_e32 v0, 4, v0
	v_cmp_gt_u32_e64 s[2:3], 16, v53
	s_addc_u32 s9, s51, s7
	v_or3_b32 v18, s4, v4, v16
	v_mov_b32_e32 v19, s1
	v_add3_u32 v20, s22, v0, v54
	s_mov_b64 s[20:21], 0
	v_lshlrev_b32_e32 v148, 2, v2
	v_add_u32_e32 v55, v5, v3
	v_readlane_b32 s5, v255, 27
	v_readlane_b32 s49, v253, 36
	v_readlane_b32 s52, v253, 39
	v_readlane_b32 s53, v253, 40
	v_readlane_b32 s54, v253, 41
	v_readlane_b32 s55, v253, 42
	v_readlane_b32 s56, v253, 43
	v_readlane_b32 s57, v253, 44
	v_readlane_b32 s58, v253, 45
	v_readlane_b32 s59, v253, 46
	v_readlane_b32 s60, v253, 47
	v_readlane_b32 s61, v253, 48
	v_readlane_b32 s62, v253, 49
	v_readlane_b32 s63, v253, 50
	s_branch .LBB0_545

; DI void row2_phase(const Params& P, int l, int r_begin, char* smem) {
;     ...
;     float ss = 0.f;
; #pragma unroll 16
;     for (int kk = 0; kk < 32; kk++) {
;       const float4 a = *(const float4*)(xm + kk * 32), b = *(const float4*)(xm + kk * 32 + 4);
;       ss += a.x * a.x + a.y * a.y + a.z * a.z + a.w * a.w + b.x * b.x + b.y * b.y + b.z * b.z + b.w * b.w;
;     }
.LBB0_546:
	global_load_dwordx4 a[0:3], v[22:23], off offset:0
	global_load_dwordx4 a[4:7], v[22:23], off offset:16
	global_load_dwordx4 a[8:11], v[22:23], off offset:128
	global_load_dwordx4 a[12:15], v[22:23], off offset:144
	global_load_dwordx4 a[16:19], v[22:23], off offset:256
	global_load_dwordx4 a[20:23], v[22:23], off offset:272
	global_load_dwordx4 a[24:27], v[22:23], off offset:384
	global_load_dwordx4 a[28:31], v[22:23], off offset:400
	global_load_dwordx4 a[32:35], v[22:23], off offset:512
	global_load_dwordx4 a[36:39], v[22:23], off offset:528
	global_load_dwordx4 a[40:43], v[22:23], off offset:640
	global_load_dwordx4 a[44:47], v[22:23], off offset:656
	global_load_dwordx4 a[48:51], v[22:23], off offset:768
	global_load_dwordx4 a[52:55], v[22:23], off offset:784
	global_load_dwordx4 a[56:59], v[22:23], off offset:896
	global_load_dwordx4 a[60:63], v[22:23], off offset:912
	global_load_dwordx4 a[64:67], v[22:23], off offset:1024
	global_load_dwordx4 a[68:71], v[22:23], off offset:1040
	global_load_dwordx4 a[72:75], v[22:23], off offset:1152
	global_load_dwordx4 a[76:79], v[22:23], off offset:1168
	global_load_dwordx4 a[80:83], v[22:23], off offset:1280
	global_load_dwordx4 a[84:87], v[22:23], off offset:1296
	global_load_dwordx4 a[88:91], v[22:23], off offset:1408
	global_load_dwordx4 a[92:95], v[22:23], off offset:1424
	global_load_dwordx4 a[96:99], v[22:23], off offset:1536
	global_load_dwordx4 a[100:103], v[22:23], off offset:1552
	global_load_dwordx4 a[104:107], v[22:23], off offset:1664
	global_load_dwordx4 a[108:111], v[22:23], off offset:1680
	global_load_dwordx4 a[112:115], v[22:23], off offset:1792
	global_load_dwordx4 a[116:119], v[22:23], off offset:1808
	global_load_dwordx4 a[120:123], v[22:23], off offset:1920
	global_load_dwordx4 a[124:127], v[22:23], off offset:1936
	global_load_dwordx4 a[128:131], v[22:23], off offset:2048
	global_load_dwordx4 a[132:135], v[22:23], off offset:2064
	global_load_dwordx4 a[136:139], v[22:23], off offset:2176
	global_load_dwordx4 a[140:143], v[22:23], off offset:2192
	global_load_dwordx4 a[144:147], v[22:23], off offset:2304
	global_load_dwordx4 a[148:151], v[22:23], off offset:2320
	global_load_dwordx4 a[152:155], v[22:23], off offset:2432
	global_load_dwordx4 a[156:159], v[22:23], off offset:2448
	global_load_dwordx4 a[160:163], v[22:23], off offset:2560
	global_load_dwordx4 a[164:167], v[22:23], off offset:2576
	global_load_dwordx4 a[168:171], v[22:23], off offset:2688
	global_load_dwordx4 a[172:175], v[22:23], off offset:2704
	global_load_dwordx4 a[180:183], v[22:23], off offset:2816
	global_load_dwordx4 a[184:187], v[22:23], off offset:2832
	global_load_dwordx4 a[188:191], v[22:23], off offset:2944
	global_load_dwordx4 a[196:199], v[22:23], off offset:2960
	global_load_dwordx4 a[200:203], v[22:23], off offset:3072
	global_load_dwordx4 a[204:207], v[22:23], off offset:3088
	global_load_dwordx4 a[208:211], v[22:23], off offset:3200
	global_load_dwordx4 a[212:215], v[22:23], off offset:3216
	global_load_dwordx4 a[216:219], v[22:23], off offset:3328
	global_load_dwordx4 a[220:223], v[22:23], off offset:3344
	global_load_dwordx4 a[224:227], v[22:23], off offset:3456
	global_load_dwordx4 a[228:231], v[22:23], off offset:3472
	global_load_dwordx4 a[232:235], v[22:23], off offset:3584
	global_load_dwordx4 a[236:239], v[22:23], off offset:3600
	global_load_dwordx4 a[240:243], v[22:23], off offset:3712
	global_load_dwordx4 a[244:247], v[22:23], off offset:3728
	global_load_dwordx4 a[248:251], v[22:23], off offset:3840
	global_load_dwordx4 a[252:255], v[22:23], off offset:3856
	global_load_dwordx4 v[84:87], v[22:23], off offset:3968
	global_load_dwordx4 v[88:91], v[22:23], off offset:3984
	v_mov_b32_e32 v0, 0
	s_waitcnt vmcnt(62)
	v_accvgpr_read_b32 v2, a0
	v_accvgpr_read_b32 v3, a1
	v_accvgpr_read_b32 v4, a2
	v_accvgpr_read_b32 v5, a3
	v_accvgpr_read_b32 v6, a4
	v_accvgpr_read_b32 v7, a5
	v_accvgpr_read_b32 v8, a6
	v_accvgpr_read_b32 v9, a7
	v_mul_f32_e32 v2, v2, v2
	v_mul_f32_e32 v3, v3, v3
	v_mul_f32_e32 v4, v4, v4
	v_mul_f32_e32 v5, v5, v5
	v_mul_f32_e32 v6, v6, v6
	v_mul_f32_e32 v7, v7, v7
	v_mul_f32_e32 v8, v8, v8
	v_mul_f32_e32 v9, v9, v9
	v_add_f32_e32 v1, v2, v3
	v_add_f32_e32 v1, v1, v4
	v_add_f32_e32 v1, v1, v5
	v_add_f32_e32 v1, v1, v6
	v_add_f32_e32 v1, v1, v7
	v_add_f32_e32 v1, v1, v8
	v_add_f32_e32 v1, v1, v9
	v_add_f32_e32 v0, v0, v1
	s_waitcnt vmcnt(60)
	v_accvgpr_read_b32 v2, a8
	v_accvgpr_read_b32 v3, a9
	v_accvgpr_read_b32 v4, a10
	v_accvgpr_read_b32 v5, a11
	v_accvgpr_read_b32 v6, a12
	v_accvgpr_read_b32 v7, a13
	v_accvgpr_read_b32 v8, a14
	v_accvgpr_read_b32 v9, a15
	v_mul_f32_e32 v2, v2, v2
	v_mul_f32_e32 v3, v3, v3
	v_mul_f32_e32 v4, v4, v4
	v_mul_f32_e32 v5, v5, v5
	v_mul_f32_e32 v6, v6, v6
	v_mul_f32_e32 v7, v7, v7
	v_mul_f32_e32 v8, v8, v8
	v_mul_f32_e32 v9, v9, v9
	v_add_f32_e32 v1, v2, v3
	v_add_f32_e32 v1, v1, v4
	v_add_f32_e32 v1, v1, v5
	v_add_f32_e32 v1, v1, v6
	v_add_f32_e32 v1, v1, v7
	v_add_f32_e32 v1, v1, v8
	v_add_f32_e32 v1, v1, v9
	v_add_f32_e32 v0, v0, v1
	s_waitcnt vmcnt(58)
	v_accvgpr_read_b32 v2, a16
	v_accvgpr_read_b32 v3, a17
	v_accvgpr_read_b32 v4, a18
	v_accvgpr_read_b32 v5, a19
	v_accvgpr_read_b32 v6, a20
	v_accvgpr_read_b32 v7, a21
	v_accvgpr_read_b32 v8, a22
	v_accvgpr_read_b32 v9, a23
	v_mul_f32_e32 v2, v2, v2
	v_mul_f32_e32 v3, v3, v3
	v_mul_f32_e32 v4, v4, v4
	v_mul_f32_e32 v5, v5, v5
	v_mul_f32_e32 v6, v6, v6
	v_mul_f32_e32 v7, v7, v7
	v_mul_f32_e32 v8, v8, v8
	v_mul_f32_e32 v9, v9, v9
	v_add_f32_e32 v1, v2, v3
	v_add_f32_e32 v1, v1, v4
	v_add_f32_e32 v1, v1, v5
	v_add_f32_e32 v1, v1, v6
	v_add_f32_e32 v1, v1, v7
	v_add_f32_e32 v1, v1, v8
	v_add_f32_e32 v1, v1, v9
	v_add_f32_e32 v0, v0, v1
	s_waitcnt vmcnt(56)
; DI void row2_phase(const Params& P, int l, int r_begin, char* smem) {
;     ...
; #pragma unroll 16
;     for (int kk = 0; kk < 32; kk++) {
;       const float4 a = *(const float4*)(xm + kk * 32), b = *(const float4*)(xm + kk * 32 + 4);
;       ss += a.x * a.x + a.y * a.y + a.z * a.z + a.w * a.w + b.x * b.x + b.y * b.y + b.z * b.z + b.w * b.w;
;     }
	v_accvgpr_read_b32 v2, a24
	v_accvgpr_read_b32 v3, a25
	v_accvgpr_read_b32 v4, a26
	v_accvgpr_read_b32 v5, a27
	v_accvgpr_read_b32 v6, a28
	v_accvgpr_read_b32 v7, a29
	v_accvgpr_read_b32 v8, a30
	v_accvgpr_read_b32 v9, a31
	v_mul_f32_e32 v2, v2, v2
	v_mul_f32_e32 v3, v3, v3
	v_mul_f32_e32 v4, v4, v4
	v_mul_f32_e32 v5, v5, v5
	v_mul_f32_e32 v6, v6, v6
	v_mul_f32_e32 v7, v7, v7
	v_mul_f32_e32 v8, v8, v8
	v_mul_f32_e32 v9, v9, v9
	v_add_f32_e32 v1, v2, v3
	v_add_f32_e32 v1, v1, v4
	v_add_f32_e32 v1, v1, v5
	v_add_f32_e32 v1, v1, v6
	v_add_f32_e32 v1, v1, v7
	v_add_f32_e32 v1, v1, v8
	v_add_f32_e32 v1, v1, v9
	v_add_f32_e32 v0, v0, v1
	s_waitcnt vmcnt(54)
	v_accvgpr_read_b32 v2, a32
	v_accvgpr_read_b32 v3, a33
	v_accvgpr_read_b32 v4, a34
	v_accvgpr_read_b32 v5, a35
	v_accvgpr_read_b32 v6, a36
	v_accvgpr_read_b32 v7, a37
	v_accvgpr_read_b32 v8, a38
	v_accvgpr_read_b32 v9, a39
	v_mul_f32_e32 v2, v2, v2
	v_mul_f32_e32 v3, v3, v3
	v_mul_f32_e32 v4, v4, v4
	v_mul_f32_e32 v5, v5, v5
	v_mul_f32_e32 v6, v6, v6
	v_mul_f32_e32 v7, v7, v7
	v_mul_f32_e32 v8, v8, v8
	v_mul_f32_e32 v9, v9, v9
	v_add_f32_e32 v1, v2, v3
	v_add_f32_e32 v1, v1, v4
	v_add_f32_e32 v1, v1, v5
	v_add_f32_e32 v1, v1, v6
	v_add_f32_e32 v1, v1, v7
	v_add_f32_e32 v1, v1, v8
	v_add_f32_e32 v1, v1, v9
	v_add_f32_e32 v0, v0, v1
	s_waitcnt vmcnt(52)
	v_accvgpr_read_b32 v2, a40
	v_accvgpr_read_b32 v3, a41
	v_accvgpr_read_b32 v4, a42
	v_accvgpr_read_b32 v5, a43
	v_accvgpr_read_b32 v6, a44
	v_accvgpr_read_b32 v7, a45
	v_accvgpr_read_b32 v8, a46
	v_accvgpr_read_b32 v9, a47
	v_mul_f32_e32 v2, v2, v2
	v_mul_f32_e32 v3, v3, v3
	v_mul_f32_e32 v4, v4, v4
	v_mul_f32_e32 v5, v5, v5
	v_mul_f32_e32 v6, v6, v6
	v_mul_f32_e32 v7, v7, v7
	v_mul_f32_e32 v8, v8, v8
	v_mul_f32_e32 v9, v9, v9
	v_add_f32_e32 v1, v2, v3
	v_add_f32_e32 v1, v1, v4
	v_add_f32_e32 v1, v1, v5
	v_add_f32_e32 v1, v1, v6
	v_add_f32_e32 v1, v1, v7
	v_add_f32_e32 v1, v1, v8
	v_add_f32_e32 v1, v1, v9
	v_add_f32_e32 v0, v0, v1
	s_waitcnt vmcnt(50)
	v_accvgpr_read_b32 v2, a48
	v_accvgpr_read_b32 v3, a49
	v_accvgpr_read_b32 v4, a50
	v_accvgpr_read_b32 v5, a51
	v_accvgpr_read_b32 v6, a52
	v_accvgpr_read_b32 v7, a53
	v_accvgpr_read_b32 v8, a54
	v_accvgpr_read_b32 v9, a55
	v_mul_f32_e32 v2, v2, v2
	v_mul_f32_e32 v3, v3, v3
	v_mul_f32_e32 v4, v4, v4
	v_mul_f32_e32 v5, v5, v5
	v_mul_f32_e32 v6, v6, v6
	v_mul_f32_e32 v7, v7, v7
	v_mul_f32_e32 v8, v8, v8
	v_mul_f32_e32 v9, v9, v9
	v_add_f32_e32 v1, v2, v3
	v_add_f32_e32 v1, v1, v4
	v_add_f32_e32 v1, v1, v5
	v_add_f32_e32 v1, v1, v6
	v_add_f32_e32 v1, v1, v7
	v_add_f32_e32 v1, v1, v8
	v_add_f32_e32 v1, v1, v9
	v_add_f32_e32 v0, v0, v1
	s_waitcnt vmcnt(48)
	v_accvgpr_read_b32 v2, a56
	v_accvgpr_read_b32 v3, a57
	v_accvgpr_read_b32 v4, a58
	v_accvgpr_read_b32 v5, a59
	v_accvgpr_read_b32 v6, a60
	v_accvgpr_read_b32 v7, a61
	v_accvgpr_read_b32 v8, a62
	v_accvgpr_read_b32 v9, a63
	v_mul_f32_e32 v2, v2, v2
	v_mul_f32_e32 v3, v3, v3
	v_mul_f32_e32 v4, v4, v4
	v_mul_f32_e32 v5, v5, v5
	v_mul_f32_e32 v6, v6, v6
	v_mul_f32_e32 v7, v7, v7
	v_mul_f32_e32 v8, v8, v8
	v_mul_f32_e32 v9, v9, v9
	v_add_f32_e32 v1, v2, v3
	v_add_f32_e32 v1, v1, v4
	v_add_f32_e32 v1, v1, v5
	v_add_f32_e32 v1, v1, v6
	v_add_f32_e32 v1, v1, v7
	v_add_f32_e32 v1, v1, v8
	v_add_f32_e32 v1, v1, v9
	v_add_f32_e32 v0, v0, v1
	s_waitcnt vmcnt(46)
	v_accvgpr_read_b32 v2, a64
	v_accvgpr_read_b32 v3, a65
	v_accvgpr_read_b32 v4, a66
	v_accvgpr_read_b32 v5, a67
	v_accvgpr_read_b32 v6, a68
	v_accvgpr_read_b32 v7, a69
	v_accvgpr_read_b32 v8, a70
	v_accvgpr_read_b32 v9, a71
	v_mul_f32_e32 v2, v2, v2
	v_mul_f32_e32 v3, v3, v3
	v_mul_f32_e32 v4, v4, v4
	v_mul_f32_e32 v5, v5, v5
	v_mul_f32_e32 v6, v6, v6
	v_mul_f32_e32 v7, v7, v7
	v_mul_f32_e32 v8, v8, v8
	v_mul_f32_e32 v9, v9, v9
	v_add_f32_e32 v1, v2, v3
	v_add_f32_e32 v1, v1, v4
	v_add_f32_e32 v1, v1, v5
	v_add_f32_e32 v1, v1, v6
	v_add_f32_e32 v1, v1, v7
	v_add_f32_e32 v1, v1, v8
	v_add_f32_e32 v1, v1, v9
	v_add_f32_e32 v0, v0, v1
	s_waitcnt vmcnt(44)
	v_accvgpr_read_b32 v2, a72
	v_accvgpr_read_b32 v3, a73
	v_accvgpr_read_b32 v4, a74
	v_accvgpr_read_b32 v5, a75
	v_accvgpr_read_b32 v6, a76
	v_accvgpr_read_b32 v7, a77
	v_accvgpr_read_b32 v8, a78
	v_accvgpr_read_b32 v9, a79
	v_mul_f32_e32 v2, v2, v2
	v_mul_f32_e32 v3, v3, v3
	v_mul_f32_e32 v4, v4, v4
	v_mul_f32_e32 v5, v5, v5
	v_mul_f32_e32 v6, v6, v6
	v_mul_f32_e32 v7, v7, v7
	v_mul_f32_e32 v8, v8, v8
	v_mul_f32_e32 v9, v9, v9
	v_add_f32_e32 v1, v2, v3
	v_add_f32_e32 v1, v1, v4
	v_add_f32_e32 v1, v1, v5
	v_add_f32_e32 v1, v1, v6
	v_add_f32_e32 v1, v1, v7
	v_add_f32_e32 v1, v1, v8
	v_add_f32_e32 v1, v1, v9
	v_add_f32_e32 v0, v0, v1
	s_waitcnt vmcnt(42)
	v_accvgpr_read_b32 v2, a80
	v_accvgpr_read_b32 v3, a81
	v_accvgpr_read_b32 v4, a82
	v_accvgpr_read_b32 v5, a83
	v_accvgpr_read_b32 v6, a84
	v_accvgpr_read_b32 v7, a85
	v_accvgpr_read_b32 v8, a86
	v_accvgpr_read_b32 v9, a87
	v_mul_f32_e32 v2, v2, v2
	v_mul_f32_e32 v3, v3, v3
	v_mul_f32_e32 v4, v4, v4
	v_mul_f32_e32 v5, v5, v5
	v_mul_f32_e32 v6, v6, v6
	v_mul_f32_e32 v7, v7, v7
	v_mul_f32_e32 v8, v8, v8
	v_mul_f32_e32 v9, v9, v9
	v_add_f32_e32 v1, v2, v3
	v_add_f32_e32 v1, v1, v4
	v_add_f32_e32 v1, v1, v5
	v_add_f32_e32 v1, v1, v6
	v_add_f32_e32 v1, v1, v7
	v_add_f32_e32 v1, v1, v8
	v_add_f32_e32 v1, v1, v9
	v_add_f32_e32 v0, v0, v1
	s_waitcnt vmcnt(40)
	v_accvgpr_read_b32 v2, a88
	v_accvgpr_read_b32 v3, a89
	v_accvgpr_read_b32 v4, a90
	v_accvgpr_read_b32 v5, a91
	v_accvgpr_read_b32 v6, a92
	v_accvgpr_read_b32 v7, a93
	v_accvgpr_read_b32 v8, a94
	v_accvgpr_read_b32 v9, a95
	v_mul_f32_e32 v2, v2, v2
	v_mul_f32_e32 v3, v3, v3
	v_mul_f32_e32 v4, v4, v4
	v_mul_f32_e32 v5, v5, v5
	v_mul_f32_e32 v6, v6, v6
	v_mul_f32_e32 v7, v7, v7
	v_mul_f32_e32 v8, v8, v8
	v_mul_f32_e32 v9, v9, v9
	v_add_f32_e32 v1, v2, v3
	v_add_f32_e32 v1, v1, v4
	v_add_f32_e32 v1, v1, v5
	v_add_f32_e32 v1, v1, v6
	v_add_f32_e32 v1, v1, v7
	v_add_f32_e32 v1, v1, v8
	v_add_f32_e32 v1, v1, v9
	v_add_f32_e32 v0, v0, v1
	s_waitcnt vmcnt(38)
; DI void row2_phase(const Params& P, int l, int r_begin, char* smem) {
;     ...
; #pragma unroll 16
;     for (int kk = 0; kk < 32; kk++) {
;       const float4 a = *(const float4*)(xm + kk * 32), b = *(const float4*)(xm + kk * 32 + 4);
;       ss += a.x * a.x + a.y * a.y + a.z * a.z + a.w * a.w + b.x * b.x + b.y * b.y + b.z * b.z + b.w * b.w;
;     }
	v_accvgpr_read_b32 v2, a96
	v_accvgpr_read_b32 v3, a97
	v_accvgpr_read_b32 v4, a98
	v_accvgpr_read_b32 v5, a99
	v_accvgpr_read_b32 v6, a100
	v_accvgpr_read_b32 v7, a101
	v_accvgpr_read_b32 v8, a102
	v_accvgpr_read_b32 v9, a103
	v_mul_f32_e32 v2, v2, v2
	v_mul_f32_e32 v3, v3, v3
	v_mul_f32_e32 v4, v4, v4
	v_mul_f32_e32 v5, v5, v5
	v_mul_f32_e32 v6, v6, v6
	v_mul_f32_e32 v7, v7, v7
	v_mul_f32_e32 v8, v8, v8
	v_mul_f32_e32 v9, v9, v9
	v_add_f32_e32 v1, v2, v3
	v_add_f32_e32 v1, v1, v4
	v_add_f32_e32 v1, v1, v5
	v_add_f32_e32 v1, v1, v6
	v_add_f32_e32 v1, v1, v7
	v_add_f32_e32 v1, v1, v8
	v_add_f32_e32 v1, v1, v9
	v_add_f32_e32 v0, v0, v1
	s_waitcnt vmcnt(36)
	v_accvgpr_read_b32 v2, a104
	v_accvgpr_read_b32 v3, a105
	v_accvgpr_read_b32 v4, a106
	v_accvgpr_read_b32 v5, a107
	v_accvgpr_read_b32 v6, a108
	v_accvgpr_read_b32 v7, a109
	v_accvgpr_read_b32 v8, a110
	v_accvgpr_read_b32 v9, a111
	v_mul_f32_e32 v2, v2, v2
	v_mul_f32_e32 v3, v3, v3
	v_mul_f32_e32 v4, v4, v4
	v_mul_f32_e32 v5, v5, v5
	v_mul_f32_e32 v6, v6, v6
	v_mul_f32_e32 v7, v7, v7
	v_mul_f32_e32 v8, v8, v8
	v_mul_f32_e32 v9, v9, v9
	v_add_f32_e32 v1, v2, v3
	v_add_f32_e32 v1, v1, v4
	v_add_f32_e32 v1, v1, v5
	v_add_f32_e32 v1, v1, v6
	v_add_f32_e32 v1, v1, v7
	v_add_f32_e32 v1, v1, v8
	v_add_f32_e32 v1, v1, v9
	v_add_f32_e32 v0, v0, v1
	s_waitcnt vmcnt(34)
	v_accvgpr_read_b32 v2, a112
	v_accvgpr_read_b32 v3, a113
	v_accvgpr_read_b32 v4, a114
	v_accvgpr_read_b32 v5, a115
	v_accvgpr_read_b32 v6, a116
	v_accvgpr_read_b32 v7, a117
	v_accvgpr_read_b32 v8, a118
	v_accvgpr_read_b32 v9, a119
	v_mul_f32_e32 v2, v2, v2
	v_mul_f32_e32 v3, v3, v3
	v_mul_f32_e32 v4, v4, v4
	v_mul_f32_e32 v5, v5, v5
	v_mul_f32_e32 v6, v6, v6
	v_mul_f32_e32 v7, v7, v7
	v_mul_f32_e32 v8, v8, v8
	v_mul_f32_e32 v9, v9, v9
	v_add_f32_e32 v1, v2, v3
	v_add_f32_e32 v1, v1, v4
	v_add_f32_e32 v1, v1, v5
	v_add_f32_e32 v1, v1, v6
	v_add_f32_e32 v1, v1, v7
	v_add_f32_e32 v1, v1, v8
	v_add_f32_e32 v1, v1, v9
	v_add_f32_e32 v0, v0, v1
	s_waitcnt vmcnt(32)
	v_accvgpr_read_b32 v2, a120
	v_accvgpr_read_b32 v3, a121
	v_accvgpr_read_b32 v4, a122
	v_accvgpr_read_b32 v5, a123
	v_accvgpr_read_b32 v6, a124
	v_accvgpr_read_b32 v7, a125
	v_accvgpr_read_b32 v8, a126
	v_accvgpr_read_b32 v9, a127
	v_mul_f32_e32 v2, v2, v2
	v_mul_f32_e32 v3, v3, v3
	v_mul_f32_e32 v4, v4, v4
	v_mul_f32_e32 v5, v5, v5
	v_mul_f32_e32 v6, v6, v6
	v_mul_f32_e32 v7, v7, v7
	v_mul_f32_e32 v8, v8, v8
	v_mul_f32_e32 v9, v9, v9
	v_add_f32_e32 v1, v2, v3
	v_add_f32_e32 v1, v1, v4
	v_add_f32_e32 v1, v1, v5
	v_add_f32_e32 v1, v1, v6
	v_add_f32_e32 v1, v1, v7
	v_add_f32_e32 v1, v1, v8
	v_add_f32_e32 v1, v1, v9
	v_add_f32_e32 v0, v0, v1
	s_waitcnt vmcnt(30)
	v_accvgpr_read_b32 v2, a128
	v_accvgpr_read_b32 v3, a129
	v_accvgpr_read_b32 v4, a130
	v_accvgpr_read_b32 v5, a131
	v_accvgpr_read_b32 v6, a132
	v_accvgpr_read_b32 v7, a133
	v_accvgpr_read_b32 v8, a134
	v_accvgpr_read_b32 v9, a135
	v_mul_f32_e32 v2, v2, v2
	v_mul_f32_e32 v3, v3, v3
	v_mul_f32_e32 v4, v4, v4
	v_mul_f32_e32 v5, v5, v5
	v_mul_f32_e32 v6, v6, v6
	v_mul_f32_e32 v7, v7, v7
	v_mul_f32_e32 v8, v8, v8
	v_mul_f32_e32 v9, v9, v9
	v_add_f32_e32 v1, v2, v3
	v_add_f32_e32 v1, v1, v4
	v_add_f32_e32 v1, v1, v5
	v_add_f32_e32 v1, v1, v6
	v_add_f32_e32 v1, v1, v7
	v_add_f32_e32 v1, v1, v8
	v_add_f32_e32 v1, v1, v9
	v_add_f32_e32 v0, v0, v1
	s_waitcnt vmcnt(28)
	v_accvgpr_read_b32 v2, a136
	v_accvgpr_read_b32 v3, a137
	v_accvgpr_read_b32 v4, a138
	v_accvgpr_read_b32 v5, a139
	v_accvgpr_read_b32 v6, a140
	v_accvgpr_read_b32 v7, a141
	v_accvgpr_read_b32 v8, a142
	v_accvgpr_read_b32 v9, a143
	v_mul_f32_e32 v2, v2, v2
	v_mul_f32_e32 v3, v3, v3
	v_mul_f32_e32 v4, v4, v4
	v_mul_f32_e32 v5, v5, v5
	v_mul_f32_e32 v6, v6, v6
	v_mul_f32_e32 v7, v7, v7
	v_mul_f32_e32 v8, v8, v8
	v_mul_f32_e32 v9, v9, v9
	v_add_f32_e32 v1, v2, v3
	v_add_f32_e32 v1, v1, v4
	v_add_f32_e32 v1, v1, v5
	v_add_f32_e32 v1, v1, v6
	v_add_f32_e32 v1, v1, v7
	v_add_f32_e32 v1, v1, v8
	v_add_f32_e32 v1, v1, v9
	v_add_f32_e32 v0, v0, v1
	s_waitcnt vmcnt(26)
	v_accvgpr_read_b32 v2, a144
	v_accvgpr_read_b32 v3, a145
	v_accvgpr_read_b32 v4, a146
	v_accvgpr_read_b32 v5, a147
	v_accvgpr_read_b32 v6, a148
	v_accvgpr_read_b32 v7, a149
	v_accvgpr_read_b32 v8, a150
	v_accvgpr_read_b32 v9, a151
	v_mul_f32_e32 v2, v2, v2
	v_mul_f32_e32 v3, v3, v3
	v_mul_f32_e32 v4, v4, v4
	v_mul_f32_e32 v5, v5, v5
	v_mul_f32_e32 v6, v6, v6
	v_mul_f32_e32 v7, v7, v7
	v_mul_f32_e32 v8, v8, v8
	v_mul_f32_e32 v9, v9, v9
	v_add_f32_e32 v1, v2, v3
	v_add_f32_e32 v1, v1, v4
	v_add_f32_e32 v1, v1, v5
	v_add_f32_e32 v1, v1, v6
	v_add_f32_e32 v1, v1, v7
	v_add_f32_e32 v1, v1, v8
	v_add_f32_e32 v1, v1, v9
	v_add_f32_e32 v0, v0, v1
	s_waitcnt vmcnt(24)
	v_accvgpr_read_b32 v2, a152
	v_accvgpr_read_b32 v3, a153
	v_accvgpr_read_b32 v4, a154
	v_accvgpr_read_b32 v5, a155
	v_accvgpr_read_b32 v6, a156
	v_accvgpr_read_b32 v7, a157
	v_accvgpr_read_b32 v8, a158
	v_accvgpr_read_b32 v9, a159
	v_mul_f32_e32 v2, v2, v2
	v_mul_f32_e32 v3, v3, v3
	v_mul_f32_e32 v4, v4, v4
	v_mul_f32_e32 v5, v5, v5
	v_mul_f32_e32 v6, v6, v6
	v_mul_f32_e32 v7, v7, v7
	v_mul_f32_e32 v8, v8, v8
	v_mul_f32_e32 v9, v9, v9
	v_add_f32_e32 v1, v2, v3
	v_add_f32_e32 v1, v1, v4
	v_add_f32_e32 v1, v1, v5
	v_add_f32_e32 v1, v1, v6
	v_add_f32_e32 v1, v1, v7
	v_add_f32_e32 v1, v1, v8
	v_add_f32_e32 v1, v1, v9
	v_add_f32_e32 v0, v0, v1
	s_waitcnt vmcnt(22)
; DI void row2_phase(const Params& P, int l, int r_begin, char* smem) {
;     ...
; #pragma unroll 16
;     for (int kk = 0; kk < 32; kk++) {
;       const float4 a = *(const float4*)(xm + kk * 32), b = *(const float4*)(xm + kk * 32 + 4);
;       ss += a.x * a.x + a.y * a.y + a.z * a.z + a.w * a.w + b.x * b.x + b.y * b.y + b.z * b.z + b.w * b.w;
;     }
	v_accvgpr_read_b32 v2, a160
	v_accvgpr_read_b32 v3, a161
	v_accvgpr_read_b32 v4, a162
	v_accvgpr_read_b32 v5, a163
	v_accvgpr_read_b32 v6, a164
	v_accvgpr_read_b32 v7, a165
	v_accvgpr_read_b32 v8, a166
	v_accvgpr_read_b32 v9, a167
	v_mul_f32_e32 v2, v2, v2
	v_mul_f32_e32 v3, v3, v3
	v_mul_f32_e32 v4, v4, v4
	v_mul_f32_e32 v5, v5, v5
	v_mul_f32_e32 v6, v6, v6
	v_mul_f32_e32 v7, v7, v7
	v_mul_f32_e32 v8, v8, v8
	v_mul_f32_e32 v9, v9, v9
	v_add_f32_e32 v1, v2, v3
	v_add_f32_e32 v1, v1, v4
	v_add_f32_e32 v1, v1, v5
	v_add_f32_e32 v1, v1, v6
	v_add_f32_e32 v1, v1, v7
	v_add_f32_e32 v1, v1, v8
	v_add_f32_e32 v1, v1, v9
	v_add_f32_e32 v0, v0, v1
	s_waitcnt vmcnt(20)
	v_accvgpr_read_b32 v2, a168
	v_accvgpr_read_b32 v3, a169
	v_accvgpr_read_b32 v4, a170
	v_accvgpr_read_b32 v5, a171
	v_accvgpr_read_b32 v6, a172
	v_accvgpr_read_b32 v7, a173
	v_accvgpr_read_b32 v8, a174
	v_accvgpr_read_b32 v9, a175
	v_mul_f32_e32 v2, v2, v2
	v_mul_f32_e32 v3, v3, v3
	v_mul_f32_e32 v4, v4, v4
	v_mul_f32_e32 v5, v5, v5
	v_mul_f32_e32 v6, v6, v6
	v_mul_f32_e32 v7, v7, v7
	v_mul_f32_e32 v8, v8, v8
	v_mul_f32_e32 v9, v9, v9
	v_add_f32_e32 v1, v2, v3
	v_add_f32_e32 v1, v1, v4
	v_add_f32_e32 v1, v1, v5
	v_add_f32_e32 v1, v1, v6
	v_add_f32_e32 v1, v1, v7
	v_add_f32_e32 v1, v1, v8
	v_add_f32_e32 v1, v1, v9
	v_add_f32_e32 v0, v0, v1
	s_waitcnt vmcnt(18)
	v_accvgpr_read_b32 v2, a180
	v_accvgpr_read_b32 v3, a181
	v_accvgpr_read_b32 v4, a182
	v_accvgpr_read_b32 v5, a183
	v_accvgpr_read_b32 v6, a184
	v_accvgpr_read_b32 v7, a185
	v_accvgpr_read_b32 v8, a186
	v_accvgpr_read_b32 v9, a187
	v_mul_f32_e32 v2, v2, v2
	v_mul_f32_e32 v3, v3, v3
	v_mul_f32_e32 v4, v4, v4
	v_mul_f32_e32 v5, v5, v5
	v_mul_f32_e32 v6, v6, v6
	v_mul_f32_e32 v7, v7, v7
	v_mul_f32_e32 v8, v8, v8
	v_mul_f32_e32 v9, v9, v9
	v_add_f32_e32 v1, v2, v3
	v_add_f32_e32 v1, v1, v4
	v_add_f32_e32 v1, v1, v5
	v_add_f32_e32 v1, v1, v6
	v_add_f32_e32 v1, v1, v7
	v_add_f32_e32 v1, v1, v8
	v_add_f32_e32 v1, v1, v9
	v_add_f32_e32 v0, v0, v1
	s_waitcnt vmcnt(16)
	v_accvgpr_read_b32 v2, a188
	v_accvgpr_read_b32 v3, a189
	v_accvgpr_read_b32 v4, a190
	v_accvgpr_read_b32 v5, a191
	v_accvgpr_read_b32 v6, a196
	v_accvgpr_read_b32 v7, a197
	v_accvgpr_read_b32 v8, a198
	v_accvgpr_read_b32 v9, a199
	v_mul_f32_e32 v2, v2, v2
	v_mul_f32_e32 v3, v3, v3
	v_mul_f32_e32 v4, v4, v4
	v_mul_f32_e32 v5, v5, v5
	v_mul_f32_e32 v6, v6, v6
	v_mul_f32_e32 v7, v7, v7
	v_mul_f32_e32 v8, v8, v8
	v_mul_f32_e32 v9, v9, v9
	v_add_f32_e32 v1, v2, v3
	v_add_f32_e32 v1, v1, v4
	v_add_f32_e32 v1, v1, v5
	v_add_f32_e32 v1, v1, v6
	v_add_f32_e32 v1, v1, v7
	v_add_f32_e32 v1, v1, v8
	v_add_f32_e32 v1, v1, v9
	v_add_f32_e32 v0, v0, v1
	s_waitcnt vmcnt(14)
	v_accvgpr_read_b32 v2, a200
	v_accvgpr_read_b32 v3, a201
	v_accvgpr_read_b32 v4, a202
	v_accvgpr_read_b32 v5, a203
	v_accvgpr_read_b32 v6, a204
	v_accvgpr_read_b32 v7, a205
	v_accvgpr_read_b32 v8, a206
	v_accvgpr_read_b32 v9, a207
	v_mul_f32_e32 v2, v2, v2
	v_mul_f32_e32 v3, v3, v3
	v_mul_f32_e32 v4, v4, v4
	v_mul_f32_e32 v5, v5, v5
	v_mul_f32_e32 v6, v6, v6
	v_mul_f32_e32 v7, v7, v7
	v_mul_f32_e32 v8, v8, v8
	v_mul_f32_e32 v9, v9, v9
	v_add_f32_e32 v1, v2, v3
	v_add_f32_e32 v1, v1, v4
	v_add_f32_e32 v1, v1, v5
	v_add_f32_e32 v1, v1, v6
	v_add_f32_e32 v1, v1, v7
	v_add_f32_e32 v1, v1, v8
	v_add_f32_e32 v1, v1, v9
	v_add_f32_e32 v0, v0, v1
	s_waitcnt vmcnt(12)
	v_accvgpr_read_b32 v2, a208
	v_accvgpr_read_b32 v3, a209
	v_accvgpr_read_b32 v4, a210
	v_accvgpr_read_b32 v5, a211
	v_accvgpr_read_b32 v6, a212
	v_accvgpr_read_b32 v7, a213
	v_accvgpr_read_b32 v8, a214
	v_accvgpr_read_b32 v9, a215
	v_mul_f32_e32 v2, v2, v2
	v_mul_f32_e32 v3, v3, v3
	v_mul_f32_e32 v4, v4, v4
	v_mul_f32_e32 v5, v5, v5
	v_mul_f32_e32 v6, v6, v6
	v_mul_f32_e32 v7, v7, v7
	v_mul_f32_e32 v8, v8, v8
	v_mul_f32_e32 v9, v9, v9
	v_add_f32_e32 v1, v2, v3
	v_add_f32_e32 v1, v1, v4
	v_add_f32_e32 v1, v1, v5
	v_add_f32_e32 v1, v1, v6
	v_add_f32_e32 v1, v1, v7
	v_add_f32_e32 v1, v1, v8
	v_add_f32_e32 v1, v1, v9
	v_add_f32_e32 v0, v0, v1
	s_waitcnt vmcnt(10)
	v_accvgpr_read_b32 v2, a216
	v_accvgpr_read_b32 v3, a217
	v_accvgpr_read_b32 v4, a218
	v_accvgpr_read_b32 v5, a219
	v_accvgpr_read_b32 v6, a220
	v_accvgpr_read_b32 v7, a221
	v_accvgpr_read_b32 v8, a222
	v_accvgpr_read_b32 v9, a223
	v_mul_f32_e32 v2, v2, v2
	v_mul_f32_e32 v3, v3, v3
	v_mul_f32_e32 v4, v4, v4
	v_mul_f32_e32 v5, v5, v5
	v_mul_f32_e32 v6, v6, v6
	v_mul_f32_e32 v7, v7, v7
	v_mul_f32_e32 v8, v8, v8
	v_mul_f32_e32 v9, v9, v9
	v_add_f32_e32 v1, v2, v3
	v_add_f32_e32 v1, v1, v4
	v_add_f32_e32 v1, v1, v5
	v_add_f32_e32 v1, v1, v6
	v_add_f32_e32 v1, v1, v7
	v_add_f32_e32 v1, v1, v8
	v_add_f32_e32 v1, v1, v9
	v_add_f32_e32 v0, v0, v1
	s_waitcnt vmcnt(8)
	v_accvgpr_read_b32 v2, a224
	v_accvgpr_read_b32 v3, a225
	v_accvgpr_read_b32 v4, a226
	v_accvgpr_read_b32 v5, a227
	v_accvgpr_read_b32 v6, a228
	v_accvgpr_read_b32 v7, a229
	v_accvgpr_read_b32 v8, a230
	v_accvgpr_read_b32 v9, a231
	v_mul_f32_e32 v2, v2, v2
	v_mul_f32_e32 v3, v3, v3
	v_mul_f32_e32 v4, v4, v4
	v_mul_f32_e32 v5, v5, v5
	v_mul_f32_e32 v6, v6, v6
	v_mul_f32_e32 v7, v7, v7
	v_mul_f32_e32 v8, v8, v8
	v_mul_f32_e32 v9, v9, v9
	v_add_f32_e32 v1, v2, v3
	v_add_f32_e32 v1, v1, v4
	v_add_f32_e32 v1, v1, v5
	v_add_f32_e32 v1, v1, v6
	v_add_f32_e32 v1, v1, v7
	v_add_f32_e32 v1, v1, v8
	v_add_f32_e32 v1, v1, v9
	v_add_f32_e32 v0, v0, v1
	s_waitcnt vmcnt(6)
; DI float shx(float v, int o) { int ln = TIDX & 63; return __builtin_bit_cast(float, __builtin_amdgcn_ds_bpermute((ln ^ o) << 2, __builtin_bit_cast(int, v))); }
; DI void row2_phase(const Params& P, int l, int r_begin, char* smem) {
;     ...
;     const float* xm = (row < TC ? P.xcbuf + (size_t)row * D : P.out + (size_t)(row - TC) * D) + fq * 8;
;     float ss = 0.f;
; #pragma unroll 16
;     for (int kk = 0; kk < 32; kk++) {
;       const float4 a = *(const float4*)(xm + kk * 32), b = *(const float4*)(xm + kk * 32 + 4);
;       ss += a.x * a.x + a.y * a.y + a.z * a.z + a.w * a.w + b.x * b.x + b.y * b.y + b.z * b.z + b.w * b.w;
;     }
;     ss += shx(ss, 16); ss += shx(ss, 32);
;     const float rstd = rsqrtf(ss * (1.f / 1024.f) + EPS);
;     const float* sh = P.mod + (size_t)(l * 9 + n) * 6144 + 3 * 1024 + fq * 8; const float* sc = sh + 1024;
;     f4 acc[3];
; #pragma unroll
;     for (int i = 0; i < 3; i++) acc[i] = (f4){0.f, 0.f, 0.f, 0.f};
;     half_t* hxo = P.hx + (size_t)row * D + fq * 8;
; #pragma unroll 4
;     for (int kk = 0; kk < 32; kk++) {
;       const int k0 = kk * 32;
;       float x[8], g[8], s1[8], s0[8];
;       *(float4*)&x[0] = *(const float4*)(xm + k0); *(float4*)&x[4] = *(const float4*)(xm + k0 + 4);
;       *(float4*)&g[0] = *(const float4*)(gam + fq * 8 + k0); *(float4*)&g[4] = *(const float4*)(gam + fq * 8 + k0 + 4);
;       *(float4*)&s1[0] = *(const float4*)(sc + k0); *(float4*)&s1[4] = *(const float4*)(sc + k0 + 4);
;       *(float4*)&s0[0] = *(const float4*)(sh + k0); *(float4*)&s0[4] = *(const float4*)(sh + k0 + 4);
	v_accvgpr_read_b32 v2, a232
	v_accvgpr_read_b32 v3, a233
	v_accvgpr_read_b32 v4, a234
	v_accvgpr_read_b32 v5, a235
	v_accvgpr_read_b32 v6, a236
	v_accvgpr_read_b32 v7, a237
	v_accvgpr_read_b32 v8, a238
	v_accvgpr_read_b32 v9, a239
	v_mul_f32_e32 v2, v2, v2
	v_mul_f32_e32 v3, v3, v3
	v_mul_f32_e32 v4, v4, v4
	v_mul_f32_e32 v5, v5, v5
	v_mul_f32_e32 v6, v6, v6
	v_mul_f32_e32 v7, v7, v7
	v_mul_f32_e32 v8, v8, v8
	v_mul_f32_e32 v9, v9, v9
	v_add_f32_e32 v1, v2, v3
	v_add_f32_e32 v1, v1, v4
	v_add_f32_e32 v1, v1, v5
	v_add_f32_e32 v1, v1, v6
	v_add_f32_e32 v1, v1, v7
	v_add_f32_e32 v1, v1, v8
	v_add_f32_e32 v1, v1, v9
	v_add_f32_e32 v0, v0, v1
	s_waitcnt vmcnt(4)
	v_accvgpr_read_b32 v2, a240
	v_accvgpr_read_b32 v3, a241
	v_accvgpr_read_b32 v4, a242
	v_accvgpr_read_b32 v5, a243
	v_accvgpr_read_b32 v6, a244
	v_accvgpr_read_b32 v7, a245
	v_accvgpr_read_b32 v8, a246
	v_accvgpr_read_b32 v9, a247
	v_mul_f32_e32 v2, v2, v2
	v_mul_f32_e32 v3, v3, v3
	v_mul_f32_e32 v4, v4, v4
	v_mul_f32_e32 v5, v5, v5
	v_mul_f32_e32 v6, v6, v6
	v_mul_f32_e32 v7, v7, v7
	v_mul_f32_e32 v8, v8, v8
	v_mul_f32_e32 v9, v9, v9
	v_add_f32_e32 v1, v2, v3
	v_add_f32_e32 v1, v1, v4
	v_add_f32_e32 v1, v1, v5
	v_add_f32_e32 v1, v1, v6
	v_add_f32_e32 v1, v1, v7
	v_add_f32_e32 v1, v1, v8
	v_add_f32_e32 v1, v1, v9
	v_add_f32_e32 v0, v0, v1
	s_waitcnt vmcnt(2)
	v_accvgpr_read_b32 v2, a248
	v_accvgpr_read_b32 v3, a249
	v_accvgpr_read_b32 v4, a250
	v_accvgpr_read_b32 v5, a251
	v_accvgpr_read_b32 v6, a252
	v_accvgpr_read_b32 v7, a253
	v_accvgpr_read_b32 v8, a254
	v_accvgpr_read_b32 v9, a255
	v_mul_f32_e32 v2, v2, v2
	v_mul_f32_e32 v3, v3, v3
	v_mul_f32_e32 v4, v4, v4
	v_mul_f32_e32 v5, v5, v5
	v_mul_f32_e32 v6, v6, v6
	v_mul_f32_e32 v7, v7, v7
	v_mul_f32_e32 v8, v8, v8
	v_mul_f32_e32 v9, v9, v9
	v_add_f32_e32 v1, v2, v3
	v_add_f32_e32 v1, v1, v4
	v_add_f32_e32 v1, v1, v5
	v_add_f32_e32 v1, v1, v6
	v_add_f32_e32 v1, v1, v7
	v_add_f32_e32 v1, v1, v8
	v_add_f32_e32 v1, v1, v9
	v_add_f32_e32 v0, v0, v1
	s_waitcnt vmcnt(0)
	v_mov_b32_e32 v2, v84
	v_mov_b32_e32 v3, v85
	v_mov_b32_e32 v4, v86
	v_mov_b32_e32 v5, v87
	v_mov_b32_e32 v6, v88
	v_mov_b32_e32 v7, v89
	v_mov_b32_e32 v8, v90
	v_mov_b32_e32 v9, v91
	v_mul_f32_e32 v2, v2, v2
	v_mul_f32_e32 v3, v3, v3
	v_mul_f32_e32 v4, v4, v4
	v_mul_f32_e32 v5, v5, v5
	v_mul_f32_e32 v6, v6, v6
	v_mul_f32_e32 v7, v7, v7
	v_mul_f32_e32 v8, v8, v8
	v_mul_f32_e32 v9, v9, v9
	v_add_f32_e32 v1, v2, v3
	v_add_f32_e32 v1, v1, v4
	v_add_f32_e32 v1, v1, v5
	v_add_f32_e32 v1, v1, v6
	v_add_f32_e32 v1, v1, v7
	v_add_f32_e32 v1, v1, v8
	v_add_f32_e32 v1, v1, v9
	v_add_f32_e32 v0, v0, v1
	v_mov_b32_e32 v2, v172
	v_bfrev_b32_e32 v3, 0.5
	v_lshlrev_b32_e32 v2, 2, v2
	v_bitop3_b32 v2, v2, 64, v3 bitop3:0x6c
	ds_bpermute_b32 v2, v2, v0
	s_movk_i32 s0, 0x7ff
	v_cmp_lt_i32_e32 vcc, s0, v56
	s_movk_i32 s0, 0x80
	v_add_u32_e32 v1, 0xfffff800, v56
	s_waitcnt lgkmcnt(0)
	v_add_f32_e32 v0, v0, v2
	v_mov_b32_e32 v2, v172
	v_lshrrev_b32_e32 v1, 13, v1
	v_lshlrev_b32_e32 v2, 2, v2
	v_bitop3_b32 v2, v2, s0, v3 bitop3:0x6c
	ds_bpermute_b32 v2, v2, v0
	v_cndmask_b32_e32 v1, 8, v1, vcc
	v_ashrrev_i32_e32 v21, 31, v20
	v_add_u32_e32 v1, s89, v1
	v_lshlrev_b64 v[24:25], 11, v[20:21]
	s_waitcnt lgkmcnt(0)
	v_add_f32_e32 v0, v0, v2
	v_mov_b32_e32 v2, 0x358637bd
	v_fmamk_f32 v0, v0, 0x3a800000, v2
	v_cmp_gt_f32_e32 vcc, s46, v0
	v_mul_f32_e32 v2, 0x4b800000, v0
	v_mul_hi_u32_u24_e32 v27, 0x6000, v1
	v_cndmask_b32_e32 v0, v0, v2, vcc
	v_rsq_f32_e32 v0, v0
	v_mul_u32_u24_e32 v1, 0x6000, v1
	v_or_b32_e32 v24, v16, v24
	v_or_b32_e32 v26, v12, v1
	v_mul_f32_e32 v2, 0x45800000, v0
	v_cndmask_b32_e32 v28, v0, v2, vcc
	v_mov_b32_e32 v29, v28
	v_accvgpr_write_b32 a3, 0
	v_accvgpr_write_b32 a2, 0
	v_accvgpr_write_b32 a1, 0
	v_accvgpr_write_b32 a0, 0
	v_accvgpr_write_b32 a7, 0
	v_accvgpr_write_b32 a6, 0
	v_accvgpr_write_b32 a5, 0
	v_accvgpr_write_b32 a4, 0
	v_accvgpr_write_b32 a11, 0
	v_accvgpr_write_b32 a10, 0
	v_accvgpr_write_b32 a9, 0
	v_accvgpr_write_b32 a8, 0
	s_mov_b64 s[0:1], 0
	v_mov_b64_e32 v[30:31], v[18:19]
.LBB0_548:
	v_lshl_add_u64 v[84:85], s[90:91], 0, v[26:27]
	s_mov_b64 s[100:101], 0xce03000
	v_lshl_add_u64 v[86:87], v[84:85], 0, s[100:101]
	s_mov_b64 s[100:101], 0xce04000
	v_lshl_add_u64 v[84:85], v[84:85], 0, s[100:101]
	v_lshl_add_u64 v[88:89], s[90:91], 0, v[24:25]
	s_mov_b64 s[100:101], 0xf8bc700
	v_lshl_add_u64 v[88:89], v[88:89], 0, s[100:101]
	v_readlane_b32 s100, v255, 26
	v_and_b32_e32 v90, 15, v172
	v_bfe_u32 v91, v172, 4, 2
	v_lshlrev_b32_e32 v90, 11, v90
	v_lshl_or_b32 v90, v91, 4, v90
	v_mov_b32_e32 v91, 0
	s_mul_i32 s100, s100, 0x30000
	s_add_u32 s100, s100, 0xf85c700
	s_mov_b32 s101, 0
	v_lshl_add_u64 v[90:91], s[90:91], 0, v[90:91]
	v_lshl_add_u64 v[90:91], v[90:91], 0, s[100:101]
	s_mov_b64 s[100:101], 0x18000
	v_lshl_add_u64 v[92:93], v[90:91], 0, s[100:101]
	s_mov_b64 s[100:101], 0x8000
	v_lshl_add_u64 v[94:95], v[90:91], 0, s[100:101]
	s_mov_b64 s[100:101], 0x20000
	v_lshl_add_u64 v[96:97], v[90:91], 0, s[100:101]
	s_mov_b64 s[100:101], 0x10000
	v_lshl_add_u64 v[98:99], v[90:91], 0, s[100:101]
	s_mov_b64 s[100:101], 0x28000
	v_lshl_add_u64 v[100:101], v[90:91], 0, s[100:101]
	global_load_dwordx4 a[16:19], v[22:23], off offset:0
	global_load_dwordx4 a[20:23], v[22:23], off offset:16
	global_load_dwordx4 a[24:27], v[22:23], off offset:128
	global_load_dwordx4 a[28:31], v[22:23], off offset:144
	global_load_dwordx4 a[32:35], v[22:23], off offset:256
	global_load_dwordx4 a[36:39], v[22:23], off offset:272
	global_load_dwordx4 a[40:43], v[22:23], off offset:384
	global_load_dwordx4 a[44:47], v[22:23], off offset:400
	global_load_dwordx4 a[48:51], v[22:23], off offset:512
; DI f4 mfma16(h8 a, h8 b, f4 c) { return __builtin_amdgcn_mfma_f32_16x16x32_f16(a, b, c, 0, 0, 0); }
; DI void row2_phase(const Params& P, int l, int r_begin, char* smem) {
;     ...
;     for (int kk = 0; kk < 32; kk++) {
;       const int k0 = kk * 32;
;       float x[8], g[8], s1[8], s0[8];
;       *(float4*)&x[0] = *(const float4*)(xm + k0); *(float4*)&x[4] = *(const float4*)(xm + k0 + 4);
;       *(float4*)&g[0] = *(const float4*)(gam + fq * 8 + k0); *(float4*)&g[4] = *(const float4*)(gam + fq * 8 + k0 + 4);
;       *(float4*)&s1[0] = *(const float4*)(sc + k0); *(float4*)&s1[4] = *(const float4*)(sc + k0 + 4);
;       *(float4*)&s0[0] = *(const float4*)(sh + k0); *(float4*)&s0[4] = *(const float4*)(sh + k0 + 4);
;       h8 hi, lo;
; #pragma unroll
;       for (int i = 0; i < 8; i++) {
;         float v = x[i] * rstd * g[i] * (1.f + s1[i]) + s0[i];
;         hi[i] = (half_t)v; lo[i] = (half_t)(v - (float)hi[i]);
;       }
;       *(h8*)(hxo + k0) = hi;
; #pragma unroll
;       for (int n3 = 0; n3 < 3; n3++) {
;         h8 bh = *(const h8*)(Whi + (size_t)(n3 * 16 + fr) * 1024 + k0 + fq * 8);
;         h8 bl = *(const h8*)(Wlo + (size_t)(n3 * 16 + fr) * 1024 + k0 + fq * 8);
;         acc[n3] = mfma16(hi, bh, acc[n3]); acc[n3] = mfma16(lo, bh, acc[n3]); acc[n3] = mfma16(hi, bl, acc[n3]);
;       }
	global_load_dwordx4 a[52:55], v[22:23], off offset:528
	global_load_dwordx4 a[56:59], v[22:23], off offset:640
	global_load_dwordx4 a[60:63], v[22:23], off offset:656
	global_load_dwordx4 a[64:67], v[22:23], off offset:768
	global_load_dwordx4 a[68:71], v[22:23], off offset:784
	global_load_dwordx4 a[72:75], v[22:23], off offset:896
	global_load_dwordx4 a[76:79], v[22:23], off offset:912
	global_load_dwordx4 a[80:83], v[14:15], off offset:0
	global_load_dwordx4 a[84:87], v[14:15], off offset:16
	global_load_dwordx4 a[88:91], v[84:85], off offset:0
	global_load_dwordx4 a[92:95], v[84:85], off offset:16
	global_load_dwordx4 a[96:99], v[86:87], off offset:0
	global_load_dwordx4 a[100:103], v[86:87], off offset:16
	global_load_dwordx4 a[128:131], v[14:15], off offset:128
	global_load_dwordx4 a[132:135], v[14:15], off offset:144
	global_load_dwordx4 a[136:139], v[84:85], off offset:128
	global_load_dwordx4 a[140:143], v[84:85], off offset:144
	global_load_dwordx4 a[144:147], v[86:87], off offset:128
	global_load_dwordx4 a[148:151], v[86:87], off offset:144
	global_load_dwordx4 a[204:207], v[14:15], off offset:256
	global_load_dwordx4 a[208:211], v[14:15], off offset:272
	global_load_dwordx4 a[212:215], v[84:85], off offset:256
	global_load_dwordx4 a[216:219], v[84:85], off offset:272
	global_load_dwordx4 a[220:223], v[86:87], off offset:256
	global_load_dwordx4 a[224:227], v[86:87], off offset:272
	global_load_dwordx4 a[104:107], v[90:91], off offset:0
	global_load_dwordx4 a[108:111], v[92:93], off offset:0
	global_load_dwordx4 a[112:115], v[94:95], off offset:0
	global_load_dwordx4 a[116:119], v[96:97], off offset:0
	global_load_dwordx4 a[120:123], v[98:99], off offset:0
	global_load_dwordx4 a[124:127], v[100:101], off offset:0
	global_load_dwordx4 a[152:155], v[90:91], off offset:64
	global_load_dwordx4 a[156:159], v[92:93], off offset:64
	global_load_dwordx4 a[160:163], v[94:95], off offset:64
	global_load_dwordx4 a[164:167], v[96:97], off offset:64
	global_load_dwordx4 a[168:171], v[98:99], off offset:64
	global_load_dwordx4 a[172:175], v[100:101], off offset:64
	global_load_dwordx4 a[228:231], v[90:91], off offset:128
	global_load_dwordx4 a[232:235], v[92:93], off offset:128
	global_load_dwordx4 a[236:239], v[94:95], off offset:128
	global_load_dwordx4 a[240:243], v[96:97], off offset:128
	global_load_dwordx4 a[244:247], v[98:99], off offset:128
	global_load_dwordx4 a[248:251], v[100:101], off offset:128
	s_waitcnt vmcnt(30)
	v_accvgpr_read_b32 v0, a16
	v_accvgpr_read_b32 v1, a17
	v_accvgpr_read_b32 v2, a18
	v_accvgpr_read_b32 v3, a19
	v_accvgpr_read_b32 v4, a20
	v_accvgpr_read_b32 v5, a21
	v_accvgpr_read_b32 v6, a22
	v_accvgpr_read_b32 v7, a23
	v_accvgpr_read_b32 v32, a80
	v_accvgpr_read_b32 v33, a81
	v_accvgpr_read_b32 v34, a82
	v_accvgpr_read_b32 v35, a83
	v_accvgpr_read_b32 v36, a84
	v_accvgpr_read_b32 v37, a85
	v_accvgpr_read_b32 v38, a86
	v_accvgpr_read_b32 v39, a87
	v_accvgpr_read_b32 v40, a88
	v_accvgpr_read_b32 v41, a89
	v_accvgpr_read_b32 v42, a90
	v_accvgpr_read_b32 v43, a91
	v_accvgpr_read_b32 v44, a92
	v_accvgpr_read_b32 v45, a93
	v_accvgpr_read_b32 v46, a94
	v_accvgpr_read_b32 v47, a95
	v_accvgpr_read_b32 v58, a96
	v_accvgpr_read_b32 v59, a97
	v_accvgpr_read_b32 v60, a98
	v_accvgpr_read_b32 v61, a99
	v_accvgpr_read_b32 v62, a100
	v_accvgpr_read_b32 v63, a101
	v_accvgpr_read_b32 v64, a102
	v_accvgpr_read_b32 v65, a103
	global_load_dwordx4 a[16:19], v[22:23], off offset:1024
	global_load_dwordx4 a[20:23], v[22:23], off offset:1040
	global_load_dwordx4 a[80:83], v[14:15], off offset:384
	global_load_dwordx4 a[84:87], v[14:15], off offset:400
	global_load_dwordx4 a[88:91], v[84:85], off offset:384
	global_load_dwordx4 a[92:95], v[84:85], off offset:400
	global_load_dwordx4 a[96:99], v[86:87], off offset:384
	global_load_dwordx4 a[100:103], v[86:87], off offset:400
	v_pk_mul_f32 v[0:1], v[28:29], v[0:1]
	v_pk_mul_f32 v[2:3], v[28:29], v[2:3]
	v_pk_mul_f32 v[4:5], v[28:29], v[4:5]
	v_pk_mul_f32 v[6:7], v[28:29], v[6:7]
	v_pk_mul_f32 v[0:1], v[0:1], v[32:33]
	v_pk_mul_f32 v[2:3], v[2:3], v[34:35]
	v_pk_mul_f32 v[4:5], v[4:5], v[36:37]
	v_pk_mul_f32 v[6:7], v[6:7], v[38:39]
	v_pk_add_f32 v[40:41], v[40:41], 1.0 op_sel_hi:[1,0]
	v_pk_add_f32 v[42:43], v[42:43], 1.0 op_sel_hi:[1,0]
	v_pk_add_f32 v[44:45], v[44:45], 1.0 op_sel_hi:[1,0]
	v_pk_add_f32 v[46:47], v[46:47], 1.0 op_sel_hi:[1,0]
	v_pk_fma_f32 v[0:1], v[0:1], v[40:41], v[58:59]
	v_pk_fma_f32 v[2:3], v[2:3], v[42:43], v[60:61]
	v_pk_fma_f32 v[4:5], v[4:5], v[44:45], v[62:63]
	v_pk_fma_f32 v[6:7], v[6:7], v[46:47], v[64:65]
	v_cvt_pk_f16_f32 v74, v0, v1
	v_cvt_pk_f16_f32 v75, v2, v3
	v_cvt_pk_f16_f32 v76, v4, v5
	v_cvt_pk_f16_f32 v77, v6, v7
	v_cvt_f32_f16_e32 v66, v74
	v_cvt_f32_f16_sdwa v67, v74 dst_sel:DWORD dst_unused:UNUSED_PAD src0_sel:WORD_1
	v_cvt_f32_f16_e32 v68, v75
	v_cvt_f32_f16_sdwa v69, v75 dst_sel:DWORD dst_unused:UNUSED_PAD src0_sel:WORD_1
	v_cvt_f32_f16_e32 v70, v76
	v_cvt_f32_f16_sdwa v71, v76 dst_sel:DWORD dst_unused:UNUSED_PAD src0_sel:WORD_1
	v_cvt_f32_f16_e32 v72, v77
	v_cvt_f32_f16_sdwa v73, v77 dst_sel:DWORD dst_unused:UNUSED_PAD src0_sel:WORD_1
	v_pk_add_f32 v[0:1], v[0:1], v[66:67] neg_lo:[0,1] neg_hi:[0,1]
	v_pk_add_f32 v[2:3], v[2:3], v[68:69] neg_lo:[0,1] neg_hi:[0,1]
	v_pk_add_f32 v[4:5], v[4:5], v[70:71] neg_lo:[0,1] neg_hi:[0,1]
	v_pk_add_f32 v[6:7], v[6:7], v[72:73] neg_lo:[0,1] neg_hi:[0,1]
	s_nop 0
	v_cvt_pk_f16_f32 v78, v0, v1
	v_cvt_pk_f16_f32 v79, v2, v3
	v_cvt_pk_f16_f32 v80, v4, v5
	v_cvt_pk_f16_f32 v81, v6, v7
	global_store_dwordx4 v[88:89], v[74:77], off offset:0
	s_waitcnt vmcnt(21)
; DI f4 mfma16(h8 a, h8 b, f4 c) { return __builtin_amdgcn_mfma_f32_16x16x32_f16(a, b, c, 0, 0, 0); }
; DI void row2_phase(const Params& P, int l, int r_begin, char* smem) {
;     ...
;     for (int kk = 0; kk < 32; kk++) {
;       const int k0 = kk * 32;
;       float x[8], g[8], s1[8], s0[8];
;       *(float4*)&x[0] = *(const float4*)(xm + k0); *(float4*)&x[4] = *(const float4*)(xm + k0 + 4);
;       *(float4*)&g[0] = *(const float4*)(gam + fq * 8 + k0); *(float4*)&g[4] = *(const float4*)(gam + fq * 8 + k0 + 4);
;       *(float4*)&s1[0] = *(const float4*)(sc + k0); *(float4*)&s1[4] = *(const float4*)(sc + k0 + 4);
;       *(float4*)&s0[0] = *(const float4*)(sh + k0); *(float4*)&s0[4] = *(const float4*)(sh + k0 + 4);
;       h8 hi, lo;
; #pragma unroll
;       for (int i = 0; i < 8; i++) {
;         float v = x[i] * rstd * g[i] * (1.f + s1[i]) + s0[i];
;         hi[i] = (half_t)v; lo[i] = (half_t)(v - (float)hi[i]);
;       }
;       *(h8*)(hxo + k0) = hi;
; #pragma unroll
;       for (int n3 = 0; n3 < 3; n3++) {
;         h8 bh = *(const h8*)(Whi + (size_t)(n3 * 16 + fr) * 1024 + k0 + fq * 8);
;         h8 bl = *(const h8*)(Wlo + (size_t)(n3 * 16 + fr) * 1024 + k0 + fq * 8);
;         acc[n3] = mfma16(hi, bh, acc[n3]); acc[n3] = mfma16(lo, bh, acc[n3]); acc[n3] = mfma16(hi, bl, acc[n3]);
;       }
	v_mfma_f32_16x16x32_f16 a[8:11], v[74:77], a[104:107], a[8:11]
	v_mfma_f32_16x16x32_f16 a[8:11], v[78:81], a[104:107], a[8:11]
	v_mfma_f32_16x16x32_f16 a[8:11], v[74:77], a[108:111], a[8:11]
	v_mfma_f32_16x16x32_f16 a[4:7], v[74:77], a[112:115], a[4:7]
	v_mfma_f32_16x16x32_f16 a[4:7], v[78:81], a[112:115], a[4:7]
	v_mfma_f32_16x16x32_f16 a[4:7], v[74:77], a[116:119], a[4:7]
	v_mfma_f32_16x16x32_f16 a[0:3], v[74:77], a[120:123], a[0:3]
	v_mfma_f32_16x16x32_f16 a[0:3], v[78:81], a[120:123], a[0:3]
	v_mfma_f32_16x16x32_f16 a[0:3], v[74:77], a[124:127], a[0:3]
	global_load_dwordx4 a[104:107], v[90:91], off offset:192
	global_load_dwordx4 a[108:111], v[92:93], off offset:192
	global_load_dwordx4 a[112:115], v[94:95], off offset:192
	global_load_dwordx4 a[116:119], v[96:97], off offset:192
	global_load_dwordx4 a[120:123], v[98:99], off offset:192
	global_load_dwordx4 a[124:127], v[100:101], off offset:192
	s_waitcnt vmcnt(27)
	v_accvgpr_read_b32 v0, a24
	v_accvgpr_read_b32 v1, a25
	v_accvgpr_read_b32 v2, a26
	v_accvgpr_read_b32 v3, a27
	v_accvgpr_read_b32 v4, a28
	v_accvgpr_read_b32 v5, a29
	v_accvgpr_read_b32 v6, a30
	v_accvgpr_read_b32 v7, a31
	v_accvgpr_read_b32 v32, a128
	v_accvgpr_read_b32 v33, a129
	v_accvgpr_read_b32 v34, a130
	v_accvgpr_read_b32 v35, a131
	v_accvgpr_read_b32 v36, a132
	v_accvgpr_read_b32 v37, a133
	v_accvgpr_read_b32 v38, a134
	v_accvgpr_read_b32 v39, a135
	v_accvgpr_read_b32 v40, a136
	v_accvgpr_read_b32 v41, a137
	v_accvgpr_read_b32 v42, a138
	v_accvgpr_read_b32 v43, a139
	v_accvgpr_read_b32 v44, a140
	v_accvgpr_read_b32 v45, a141
	v_accvgpr_read_b32 v46, a142
	v_accvgpr_read_b32 v47, a143
	v_accvgpr_read_b32 v58, a144
	v_accvgpr_read_b32 v59, a145
	v_accvgpr_read_b32 v60, a146
	v_accvgpr_read_b32 v61, a147
	v_accvgpr_read_b32 v62, a148
	v_accvgpr_read_b32 v63, a149
	v_accvgpr_read_b32 v64, a150
	v_accvgpr_read_b32 v65, a151
	global_load_dwordx4 a[24:27], v[22:23], off offset:1152
	global_load_dwordx4 a[28:31], v[22:23], off offset:1168
	global_load_dwordx4 a[128:131], v[14:15], off offset:512
	global_load_dwordx4 a[132:135], v[14:15], off offset:528
	global_load_dwordx4 a[136:139], v[84:85], off offset:512
	global_load_dwordx4 a[140:143], v[84:85], off offset:528
	global_load_dwordx4 a[144:147], v[86:87], off offset:512
	global_load_dwordx4 a[148:151], v[86:87], off offset:528
	v_pk_mul_f32 v[0:1], v[28:29], v[0:1]
	v_pk_mul_f32 v[2:3], v[28:29], v[2:3]
	v_pk_mul_f32 v[4:5], v[28:29], v[4:5]
	v_pk_mul_f32 v[6:7], v[28:29], v[6:7]
	v_pk_mul_f32 v[0:1], v[0:1], v[32:33]
	v_pk_mul_f32 v[2:3], v[2:3], v[34:35]
	v_pk_mul_f32 v[4:5], v[4:5], v[36:37]
	v_pk_mul_f32 v[6:7], v[6:7], v[38:39]
	v_pk_add_f32 v[40:41], v[40:41], 1.0 op_sel_hi:[1,0]
	v_pk_add_f32 v[42:43], v[42:43], 1.0 op_sel_hi:[1,0]
	v_pk_add_f32 v[44:45], v[44:45], 1.0 op_sel_hi:[1,0]
	v_pk_add_f32 v[46:47], v[46:47], 1.0 op_sel_hi:[1,0]
	v_pk_fma_f32 v[0:1], v[0:1], v[40:41], v[58:59]
	v_pk_fma_f32 v[2:3], v[2:3], v[42:43], v[60:61]
	v_pk_fma_f32 v[4:5], v[4:5], v[44:45], v[62:63]
	v_pk_fma_f32 v[6:7], v[6:7], v[46:47], v[64:65]
	v_cvt_pk_f16_f32 v74, v0, v1
	v_cvt_pk_f16_f32 v75, v2, v3
	v_cvt_pk_f16_f32 v76, v4, v5
	v_cvt_pk_f16_f32 v77, v6, v7
	v_cvt_f32_f16_e32 v66, v74
	v_cvt_f32_f16_sdwa v67, v74 dst_sel:DWORD dst_unused:UNUSED_PAD src0_sel:WORD_1
	v_cvt_f32_f16_e32 v68, v75
	v_cvt_f32_f16_sdwa v69, v75 dst_sel:DWORD dst_unused:UNUSED_PAD src0_sel:WORD_1
	v_cvt_f32_f16_e32 v70, v76
	v_cvt_f32_f16_sdwa v71, v76 dst_sel:DWORD dst_unused:UNUSED_PAD src0_sel:WORD_1
	v_cvt_f32_f16_e32 v72, v77
	v_cvt_f32_f16_sdwa v73, v77 dst_sel:DWORD dst_unused:UNUSED_PAD src0_sel:WORD_1
	v_pk_add_f32 v[0:1], v[0:1], v[66:67] neg_lo:[0,1] neg_hi:[0,1]
	v_pk_add_f32 v[2:3], v[2:3], v[68:69] neg_lo:[0,1] neg_hi:[0,1]
	v_pk_add_f32 v[4:5], v[4:5], v[70:71] neg_lo:[0,1] neg_hi:[0,1]
	v_pk_add_f32 v[6:7], v[6:7], v[72:73] neg_lo:[0,1] neg_hi:[0,1]
	s_nop 0
	v_cvt_pk_f16_f32 v78, v0, v1
	v_cvt_pk_f16_f32 v79, v2, v3
	v_cvt_pk_f16_f32 v80, v4, v5
	v_cvt_pk_f16_f32 v81, v6, v7
	global_store_dwordx4 v[88:89], v[74:77], off offset:64
	s_waitcnt vmcnt(30)
	v_mfma_f32_16x16x32_f16 a[8:11], v[74:77], a[152:155], a[8:11]
	v_mfma_f32_16x16x32_f16 a[8:11], v[78:81], a[152:155], a[8:11]
	v_mfma_f32_16x16x32_f16 a[8:11], v[74:77], a[156:159], a[8:11]
	v_mfma_f32_16x16x32_f16 a[4:7], v[74:77], a[160:163], a[4:7]
	v_mfma_f32_16x16x32_f16 a[4:7], v[78:81], a[160:163], a[4:7]
	v_mfma_f32_16x16x32_f16 a[4:7], v[74:77], a[164:167], a[4:7]
	v_mfma_f32_16x16x32_f16 a[0:3], v[74:77], a[168:171], a[0:3]
	v_mfma_f32_16x16x32_f16 a[0:3], v[78:81], a[168:171], a[0:3]
	v_mfma_f32_16x16x32_f16 a[0:3], v[74:77], a[172:175], a[0:3]
	global_load_dwordx4 a[152:155], v[90:91], off offset:256
	global_load_dwordx4 a[156:159], v[92:93], off offset:256
	global_load_dwordx4 a[160:163], v[94:95], off offset:256
	global_load_dwordx4 a[164:167], v[96:97], off offset:256
	global_load_dwordx4 a[168:171], v[98:99], off offset:256
	global_load_dwordx4 a[172:175], v[100:101], off offset:256
	s_waitcnt vmcnt(36)
; DI f4 mfma16(h8 a, h8 b, f4 c) { return __builtin_amdgcn_mfma_f32_16x16x32_f16(a, b, c, 0, 0, 0); }
; DI void row2_phase(const Params& P, int l, int r_begin, char* smem) {
;     ...
;     for (int kk = 0; kk < 32; kk++) {
;       const int k0 = kk * 32;
;       float x[8], g[8], s1[8], s0[8];
;       *(float4*)&x[0] = *(const float4*)(xm + k0); *(float4*)&x[4] = *(const float4*)(xm + k0 + 4);
;       *(float4*)&g[0] = *(const float4*)(gam + fq * 8 + k0); *(float4*)&g[4] = *(const float4*)(gam + fq * 8 + k0 + 4);
;       *(float4*)&s1[0] = *(const float4*)(sc + k0); *(float4*)&s1[4] = *(const float4*)(sc + k0 + 4);
;       *(float4*)&s0[0] = *(const float4*)(sh + k0); *(float4*)&s0[4] = *(const float4*)(sh + k0 + 4);
;       h8 hi, lo;
; #pragma unroll
;       for (int i = 0; i < 8; i++) {
;         float v = x[i] * rstd * g[i] * (1.f + s1[i]) + s0[i];
;         hi[i] = (half_t)v; lo[i] = (half_t)(v - (float)hi[i]);
;       }
;       *(h8*)(hxo + k0) = hi;
; #pragma unroll
;       for (int n3 = 0; n3 < 3; n3++) {
;         h8 bh = *(const h8*)(Whi + (size_t)(n3 * 16 + fr) * 1024 + k0 + fq * 8);
;         h8 bl = *(const h8*)(Wlo + (size_t)(n3 * 16 + fr) * 1024 + k0 + fq * 8);
;         acc[n3] = mfma16(hi, bh, acc[n3]); acc[n3] = mfma16(lo, bh, acc[n3]); acc[n3] = mfma16(hi, bl, acc[n3]);
;       }
	v_accvgpr_read_b32 v0, a32
	v_accvgpr_read_b32 v1, a33
	v_accvgpr_read_b32 v2, a34
	v_accvgpr_read_b32 v3, a35
	v_accvgpr_read_b32 v4, a36
	v_accvgpr_read_b32 v5, a37
	v_accvgpr_read_b32 v6, a38
	v_accvgpr_read_b32 v7, a39
	v_accvgpr_read_b32 v32, a204
	v_accvgpr_read_b32 v33, a205
	v_accvgpr_read_b32 v34, a206
	v_accvgpr_read_b32 v35, a207
	v_accvgpr_read_b32 v36, a208
	v_accvgpr_read_b32 v37, a209
	v_accvgpr_read_b32 v38, a210
	v_accvgpr_read_b32 v39, a211
	v_accvgpr_read_b32 v40, a212
	v_accvgpr_read_b32 v41, a213
	v_accvgpr_read_b32 v42, a214
	v_accvgpr_read_b32 v43, a215
	v_accvgpr_read_b32 v44, a216
	v_accvgpr_read_b32 v45, a217
	v_accvgpr_read_b32 v46, a218
	v_accvgpr_read_b32 v47, a219
	v_accvgpr_read_b32 v58, a220
	v_accvgpr_read_b32 v59, a221
	v_accvgpr_read_b32 v60, a222
	v_accvgpr_read_b32 v61, a223
	v_accvgpr_read_b32 v62, a224
	v_accvgpr_read_b32 v63, a225
	v_accvgpr_read_b32 v64, a226
	v_accvgpr_read_b32 v65, a227
	global_load_dwordx4 a[32:35], v[22:23], off offset:1280
	global_load_dwordx4 a[36:39], v[22:23], off offset:1296
	global_load_dwordx4 a[204:207], v[14:15], off offset:640
	global_load_dwordx4 a[208:211], v[14:15], off offset:656
	global_load_dwordx4 a[212:215], v[84:85], off offset:640
	global_load_dwordx4 a[216:219], v[84:85], off offset:656
	global_load_dwordx4 a[220:223], v[86:87], off offset:640
	global_load_dwordx4 a[224:227], v[86:87], off offset:656
	v_pk_mul_f32 v[0:1], v[28:29], v[0:1]
	v_pk_mul_f32 v[2:3], v[28:29], v[2:3]
	v_pk_mul_f32 v[4:5], v[28:29], v[4:5]
	v_pk_mul_f32 v[6:7], v[28:29], v[6:7]
	v_pk_mul_f32 v[0:1], v[0:1], v[32:33]
	v_pk_mul_f32 v[2:3], v[2:3], v[34:35]
	v_pk_mul_f32 v[4:5], v[4:5], v[36:37]
	v_pk_mul_f32 v[6:7], v[6:7], v[38:39]
	v_pk_add_f32 v[40:41], v[40:41], 1.0 op_sel_hi:[1,0]
	v_pk_add_f32 v[42:43], v[42:43], 1.0 op_sel_hi:[1,0]
	v_pk_add_f32 v[44:45], v[44:45], 1.0 op_sel_hi:[1,0]
	v_pk_add_f32 v[46:47], v[46:47], 1.0 op_sel_hi:[1,0]
	v_pk_fma_f32 v[0:1], v[0:1], v[40:41], v[58:59]
	v_pk_fma_f32 v[2:3], v[2:3], v[42:43], v[60:61]
	v_pk_fma_f32 v[4:5], v[4:5], v[44:45], v[62:63]
	v_pk_fma_f32 v[6:7], v[6:7], v[46:47], v[64:65]
	v_cvt_pk_f16_f32 v74, v0, v1
	v_cvt_pk_f16_f32 v75, v2, v3
	v_cvt_pk_f16_f32 v76, v4, v5
	v_cvt_pk_f16_f32 v77, v6, v7
	v_cvt_f32_f16_e32 v66, v74
	v_cvt_f32_f16_sdwa v67, v74 dst_sel:DWORD dst_unused:UNUSED_PAD src0_sel:WORD_1
	v_cvt_f32_f16_e32 v68, v75
	v_cvt_f32_f16_sdwa v69, v75 dst_sel:DWORD dst_unused:UNUSED_PAD src0_sel:WORD_1
	v_cvt_f32_f16_e32 v70, v76
	v_cvt_f32_f16_sdwa v71, v76 dst_sel:DWORD dst_unused:UNUSED_PAD src0_sel:WORD_1
	v_cvt_f32_f16_e32 v72, v77
	v_cvt_f32_f16_sdwa v73, v77 dst_sel:DWORD dst_unused:UNUSED_PAD src0_sel:WORD_1
	v_pk_add_f32 v[0:1], v[0:1], v[66:67] neg_lo:[0,1] neg_hi:[0,1]
	v_pk_add_f32 v[2:3], v[2:3], v[68:69] neg_lo:[0,1] neg_hi:[0,1]
	v_pk_add_f32 v[4:5], v[4:5], v[70:71] neg_lo:[0,1] neg_hi:[0,1]
	v_pk_add_f32 v[6:7], v[6:7], v[72:73] neg_lo:[0,1] neg_hi:[0,1]
	s_nop 0
	v_cvt_pk_f16_f32 v78, v0, v1
	v_cvt_pk_f16_f32 v79, v2, v3
	v_cvt_pk_f16_f32 v80, v4, v5
	v_cvt_pk_f16_f32 v81, v6, v7
	global_store_dwordx4 v[88:89], v[74:77], off offset:128
	s_waitcnt vmcnt(39)
	v_mfma_f32_16x16x32_f16 a[8:11], v[74:77], a[228:231], a[8:11]
	v_mfma_f32_16x16x32_f16 a[8:11], v[78:81], a[228:231], a[8:11]
	v_mfma_f32_16x16x32_f16 a[8:11], v[74:77], a[232:235], a[8:11]
	v_mfma_f32_16x16x32_f16 a[4:7], v[74:77], a[236:239], a[4:7]
	v_mfma_f32_16x16x32_f16 a[4:7], v[78:81], a[236:239], a[4:7]
	v_mfma_f32_16x16x32_f16 a[4:7], v[74:77], a[240:243], a[4:7]
	v_mfma_f32_16x16x32_f16 a[0:3], v[74:77], a[244:247], a[0:3]
	v_mfma_f32_16x16x32_f16 a[0:3], v[78:81], a[244:247], a[0:3]
	v_mfma_f32_16x16x32_f16 a[0:3], v[74:77], a[248:251], a[0:3]
	global_load_dwordx4 a[228:231], v[90:91], off offset:320
	global_load_dwordx4 a[232:235], v[92:93], off offset:320
	global_load_dwordx4 a[236:239], v[94:95], off offset:320
	global_load_dwordx4 a[240:243], v[96:97], off offset:320
	global_load_dwordx4 a[244:247], v[98:99], off offset:320
	global_load_dwordx4 a[248:251], v[100:101], off offset:320
	s_waitcnt vmcnt(37)
	v_accvgpr_read_b32 v0, a40
	v_accvgpr_read_b32 v1, a41
	v_accvgpr_read_b32 v2, a42
	v_accvgpr_read_b32 v3, a43
	v_accvgpr_read_b32 v4, a44
	v_accvgpr_read_b32 v5, a45
	v_accvgpr_read_b32 v6, a46
	v_accvgpr_read_b32 v7, a47
	v_accvgpr_read_b32 v32, a80
	v_accvgpr_read_b32 v33, a81
	v_accvgpr_read_b32 v34, a82
	v_accvgpr_read_b32 v35, a83
	v_accvgpr_read_b32 v36, a84
	v_accvgpr_read_b32 v37, a85
	v_accvgpr_read_b32 v38, a86
	v_accvgpr_read_b32 v39, a87
	v_accvgpr_read_b32 v40, a88
	v_accvgpr_read_b32 v41, a89
	v_accvgpr_read_b32 v42, a90
	v_accvgpr_read_b32 v43, a91
	v_accvgpr_read_b32 v44, a92
	v_accvgpr_read_b32 v45, a93
	v_accvgpr_read_b32 v46, a94
	v_accvgpr_read_b32 v47, a95
	v_accvgpr_read_b32 v58, a96
	v_accvgpr_read_b32 v59, a97
	v_accvgpr_read_b32 v60, a98
	v_accvgpr_read_b32 v61, a99
	v_accvgpr_read_b32 v62, a100
	v_accvgpr_read_b32 v63, a101
	v_accvgpr_read_b32 v64, a102
	v_accvgpr_read_b32 v65, a103
	global_load_dwordx4 a[40:43], v[22:23], off offset:1408
	global_load_dwordx4 a[44:47], v[22:23], off offset:1424
	global_load_dwordx4 a[80:83], v[14:15], off offset:768
	global_load_dwordx4 a[84:87], v[14:15], off offset:784
	global_load_dwordx4 a[88:91], v[84:85], off offset:768
	global_load_dwordx4 a[92:95], v[84:85], off offset:784
	global_load_dwordx4 a[96:99], v[86:87], off offset:768
	global_load_dwordx4 a[100:103], v[86:87], off offset:784
	v_pk_mul_f32 v[0:1], v[28:29], v[0:1]
	v_pk_mul_f32 v[2:3], v[28:29], v[2:3]
	v_pk_mul_f32 v[4:5], v[28:29], v[4:5]
	v_pk_mul_f32 v[6:7], v[28:29], v[6:7]
	v_pk_mul_f32 v[0:1], v[0:1], v[32:33]
; DI f4 mfma16(h8 a, h8 b, f4 c) { return __builtin_amdgcn_mfma_f32_16x16x32_f16(a, b, c, 0, 0, 0); }
; DI void row2_phase(const Params& P, int l, int r_begin, char* smem) {
;     ...
;     for (int kk = 0; kk < 32; kk++) {
;       const int k0 = kk * 32;
;       float x[8], g[8], s1[8], s0[8];
;       *(float4*)&x[0] = *(const float4*)(xm + k0); *(float4*)&x[4] = *(const float4*)(xm + k0 + 4);
;       *(float4*)&g[0] = *(const float4*)(gam + fq * 8 + k0); *(float4*)&g[4] = *(const float4*)(gam + fq * 8 + k0 + 4);
;       *(float4*)&s1[0] = *(const float4*)(sc + k0); *(float4*)&s1[4] = *(const float4*)(sc + k0 + 4);
;       *(float4*)&s0[0] = *(const float4*)(sh + k0); *(float4*)&s0[4] = *(const float4*)(sh + k0 + 4);
;       h8 hi, lo;
; #pragma unroll
;       for (int i = 0; i < 8; i++) {
;         float v = x[i] * rstd * g[i] * (1.f + s1[i]) + s0[i];
;         hi[i] = (half_t)v; lo[i] = (half_t)(v - (float)hi[i]);
;       }
;       *(h8*)(hxo + k0) = hi;
; #pragma unroll
;       for (int n3 = 0; n3 < 3; n3++) {
;         h8 bh = *(const h8*)(Whi + (size_t)(n3 * 16 + fr) * 1024 + k0 + fq * 8);
;         h8 bl = *(const h8*)(Wlo + (size_t)(n3 * 16 + fr) * 1024 + k0 + fq * 8);
;         acc[n3] = mfma16(hi, bh, acc[n3]); acc[n3] = mfma16(lo, bh, acc[n3]); acc[n3] = mfma16(hi, bl, acc[n3]);
;       }
	v_pk_mul_f32 v[2:3], v[2:3], v[34:35]
	v_pk_mul_f32 v[4:5], v[4:5], v[36:37]
	v_pk_mul_f32 v[6:7], v[6:7], v[38:39]
	v_pk_add_f32 v[40:41], v[40:41], 1.0 op_sel_hi:[1,0]
	v_pk_add_f32 v[42:43], v[42:43], 1.0 op_sel_hi:[1,0]
	v_pk_add_f32 v[44:45], v[44:45], 1.0 op_sel_hi:[1,0]
	v_pk_add_f32 v[46:47], v[46:47], 1.0 op_sel_hi:[1,0]
	v_pk_fma_f32 v[0:1], v[0:1], v[40:41], v[58:59]
	v_pk_fma_f32 v[2:3], v[2:3], v[42:43], v[60:61]
	v_pk_fma_f32 v[4:5], v[4:5], v[44:45], v[62:63]
	v_pk_fma_f32 v[6:7], v[6:7], v[46:47], v[64:65]
	v_cvt_pk_f16_f32 v74, v0, v1
	v_cvt_pk_f16_f32 v75, v2, v3
	v_cvt_pk_f16_f32 v76, v4, v5
	v_cvt_pk_f16_f32 v77, v6, v7
	v_cvt_f32_f16_e32 v66, v74
	v_cvt_f32_f16_sdwa v67, v74 dst_sel:DWORD dst_unused:UNUSED_PAD src0_sel:WORD_1
	v_cvt_f32_f16_e32 v68, v75
	v_cvt_f32_f16_sdwa v69, v75 dst_sel:DWORD dst_unused:UNUSED_PAD src0_sel:WORD_1
	v_cvt_f32_f16_e32 v70, v76
	v_cvt_f32_f16_sdwa v71, v76 dst_sel:DWORD dst_unused:UNUSED_PAD src0_sel:WORD_1
	v_cvt_f32_f16_e32 v72, v77
	v_cvt_f32_f16_sdwa v73, v77 dst_sel:DWORD dst_unused:UNUSED_PAD src0_sel:WORD_1
	v_pk_add_f32 v[0:1], v[0:1], v[66:67] neg_lo:[0,1] neg_hi:[0,1]
	v_pk_add_f32 v[2:3], v[2:3], v[68:69] neg_lo:[0,1] neg_hi:[0,1]
	v_pk_add_f32 v[4:5], v[4:5], v[70:71] neg_lo:[0,1] neg_hi:[0,1]
	v_pk_add_f32 v[6:7], v[6:7], v[72:73] neg_lo:[0,1] neg_hi:[0,1]
	s_nop 0
	v_cvt_pk_f16_f32 v78, v0, v1
	v_cvt_pk_f16_f32 v79, v2, v3
	v_cvt_pk_f16_f32 v80, v4, v5
	v_cvt_pk_f16_f32 v81, v6, v7
	global_store_dwordx4 v[88:89], v[74:77], off offset:192
	s_waitcnt vmcnt(39)
	v_mfma_f32_16x16x32_f16 a[8:11], v[74:77], a[104:107], a[8:11]
	v_mfma_f32_16x16x32_f16 a[8:11], v[78:81], a[104:107], a[8:11]
	v_mfma_f32_16x16x32_f16 a[8:11], v[74:77], a[108:111], a[8:11]
	v_mfma_f32_16x16x32_f16 a[4:7], v[74:77], a[112:115], a[4:7]
	v_mfma_f32_16x16x32_f16 a[4:7], v[78:81], a[112:115], a[4:7]
	v_mfma_f32_16x16x32_f16 a[4:7], v[74:77], a[116:119], a[4:7]
	v_mfma_f32_16x16x32_f16 a[0:3], v[74:77], a[120:123], a[0:3]
	v_mfma_f32_16x16x32_f16 a[0:3], v[78:81], a[120:123], a[0:3]
	v_mfma_f32_16x16x32_f16 a[0:3], v[74:77], a[124:127], a[0:3]
	global_load_dwordx4 a[104:107], v[90:91], off offset:384
	global_load_dwordx4 a[108:111], v[92:93], off offset:384
	global_load_dwordx4 a[112:115], v[94:95], off offset:384
	global_load_dwordx4 a[116:119], v[96:97], off offset:384
	global_load_dwordx4 a[120:123], v[98:99], off offset:384
	global_load_dwordx4 a[124:127], v[100:101], off offset:384
	s_waitcnt vmcnt(37)
	v_accvgpr_read_b32 v0, a48
	v_accvgpr_read_b32 v1, a49
	v_accvgpr_read_b32 v2, a50
	v_accvgpr_read_b32 v3, a51
	v_accvgpr_read_b32 v4, a52
	v_accvgpr_read_b32 v5, a53
	v_accvgpr_read_b32 v6, a54
	v_accvgpr_read_b32 v7, a55
	v_accvgpr_read_b32 v32, a128
	v_accvgpr_read_b32 v33, a129
	v_accvgpr_read_b32 v34, a130
	v_accvgpr_read_b32 v35, a131
	v_accvgpr_read_b32 v36, a132
	v_accvgpr_read_b32 v37, a133
	v_accvgpr_read_b32 v38, a134
	v_accvgpr_read_b32 v39, a135
	v_accvgpr_read_b32 v40, a136
	v_accvgpr_read_b32 v41, a137
	v_accvgpr_read_b32 v42, a138
	v_accvgpr_read_b32 v43, a139
	v_accvgpr_read_b32 v44, a140
	v_accvgpr_read_b32 v45, a141
	v_accvgpr_read_b32 v46, a142
	v_accvgpr_read_b32 v47, a143
	v_accvgpr_read_b32 v58, a144
	v_accvgpr_read_b32 v59, a145
	v_accvgpr_read_b32 v60, a146
	v_accvgpr_read_b32 v61, a147
	v_accvgpr_read_b32 v62, a148
	v_accvgpr_read_b32 v63, a149
	v_accvgpr_read_b32 v64, a150
	v_accvgpr_read_b32 v65, a151
	global_load_dwordx4 a[48:51], v[22:23], off offset:1536
	global_load_dwordx4 a[52:55], v[22:23], off offset:1552
	global_load_dwordx4 a[128:131], v[14:15], off offset:896
	global_load_dwordx4 a[132:135], v[14:15], off offset:912
	global_load_dwordx4 a[136:139], v[84:85], off offset:896
	global_load_dwordx4 a[140:143], v[84:85], off offset:912
	global_load_dwordx4 a[144:147], v[86:87], off offset:896
	global_load_dwordx4 a[148:151], v[86:87], off offset:912
	v_pk_mul_f32 v[0:1], v[28:29], v[0:1]
	v_pk_mul_f32 v[2:3], v[28:29], v[2:3]
	v_pk_mul_f32 v[4:5], v[28:29], v[4:5]
	v_pk_mul_f32 v[6:7], v[28:29], v[6:7]
	v_pk_mul_f32 v[0:1], v[0:1], v[32:33]
	v_pk_mul_f32 v[2:3], v[2:3], v[34:35]
	v_pk_mul_f32 v[4:5], v[4:5], v[36:37]
	v_pk_mul_f32 v[6:7], v[6:7], v[38:39]
	v_pk_add_f32 v[40:41], v[40:41], 1.0 op_sel_hi:[1,0]
	v_pk_add_f32 v[42:43], v[42:43], 1.0 op_sel_hi:[1,0]
	v_pk_add_f32 v[44:45], v[44:45], 1.0 op_sel_hi:[1,0]
	v_pk_add_f32 v[46:47], v[46:47], 1.0 op_sel_hi:[1,0]
	v_pk_fma_f32 v[0:1], v[0:1], v[40:41], v[58:59]
	v_pk_fma_f32 v[2:3], v[2:3], v[42:43], v[60:61]
	v_pk_fma_f32 v[4:5], v[4:5], v[44:45], v[62:63]
	v_pk_fma_f32 v[6:7], v[6:7], v[46:47], v[64:65]
	v_cvt_pk_f16_f32 v74, v0, v1
	v_cvt_pk_f16_f32 v75, v2, v3
	v_cvt_pk_f16_f32 v76, v4, v5
	v_cvt_pk_f16_f32 v77, v6, v7
	v_cvt_f32_f16_e32 v66, v74
	v_cvt_f32_f16_sdwa v67, v74 dst_sel:DWORD dst_unused:UNUSED_PAD src0_sel:WORD_1
	v_cvt_f32_f16_e32 v68, v75
	v_cvt_f32_f16_sdwa v69, v75 dst_sel:DWORD dst_unused:UNUSED_PAD src0_sel:WORD_1
	v_cvt_f32_f16_e32 v70, v76
	v_cvt_f32_f16_sdwa v71, v76 dst_sel:DWORD dst_unused:UNUSED_PAD src0_sel:WORD_1
	v_cvt_f32_f16_e32 v72, v77
	v_cvt_f32_f16_sdwa v73, v77 dst_sel:DWORD dst_unused:UNUSED_PAD src0_sel:WORD_1
	v_pk_add_f32 v[0:1], v[0:1], v[66:67] neg_lo:[0,1] neg_hi:[0,1]
	v_pk_add_f32 v[2:3], v[2:3], v[68:69] neg_lo:[0,1] neg_hi:[0,1]
	v_pk_add_f32 v[4:5], v[4:5], v[70:71] neg_lo:[0,1] neg_hi:[0,1]
	v_pk_add_f32 v[6:7], v[6:7], v[72:73] neg_lo:[0,1] neg_hi:[0,1]
	s_nop 0
	v_cvt_pk_f16_f32 v78, v0, v1
	v_cvt_pk_f16_f32 v79, v2, v3
	v_cvt_pk_f16_f32 v80, v4, v5
	v_cvt_pk_f16_f32 v81, v6, v7
	global_store_dwordx4 v[88:89], v[74:77], off offset:256
	s_waitcnt vmcnt(39)
; DI f4 mfma16(h8 a, h8 b, f4 c) { return __builtin_amdgcn_mfma_f32_16x16x32_f16(a, b, c, 0, 0, 0); }
; DI void row2_phase(const Params& P, int l, int r_begin, char* smem) {
;     ...
;     for (int kk = 0; kk < 32; kk++) {
;       const int k0 = kk * 32;
;       float x[8], g[8], s1[8], s0[8];
;       *(float4*)&x[0] = *(const float4*)(xm + k0); *(float4*)&x[4] = *(const float4*)(xm + k0 + 4);
;       *(float4*)&g[0] = *(const float4*)(gam + fq * 8 + k0); *(float4*)&g[4] = *(const float4*)(gam + fq * 8 + k0 + 4);
;       *(float4*)&s1[0] = *(const float4*)(sc + k0); *(float4*)&s1[4] = *(const float4*)(sc + k0 + 4);
;       *(float4*)&s0[0] = *(const float4*)(sh + k0); *(float4*)&s0[4] = *(const float4*)(sh + k0 + 4);
;       h8 hi, lo;
; #pragma unroll
;       for (int i = 0; i < 8; i++) {
;         float v = x[i] * rstd * g[i] * (1.f + s1[i]) + s0[i];
;         hi[i] = (half_t)v; lo[i] = (half_t)(v - (float)hi[i]);
;       }
;       *(h8*)(hxo + k0) = hi;
; #pragma unroll
;       for (int n3 = 0; n3 < 3; n3++) {
;         h8 bh = *(const h8*)(Whi + (size_t)(n3 * 16 + fr) * 1024 + k0 + fq * 8);
;         h8 bl = *(const h8*)(Wlo + (size_t)(n3 * 16 + fr) * 1024 + k0 + fq * 8);
;         acc[n3] = mfma16(hi, bh, acc[n3]); acc[n3] = mfma16(lo, bh, acc[n3]); acc[n3] = mfma16(hi, bl, acc[n3]);
;       }
	v_mfma_f32_16x16x32_f16 a[8:11], v[74:77], a[152:155], a[8:11]
	v_mfma_f32_16x16x32_f16 a[8:11], v[78:81], a[152:155], a[8:11]
	v_mfma_f32_16x16x32_f16 a[8:11], v[74:77], a[156:159], a[8:11]
	v_mfma_f32_16x16x32_f16 a[4:7], v[74:77], a[160:163], a[4:7]
	v_mfma_f32_16x16x32_f16 a[4:7], v[78:81], a[160:163], a[4:7]
	v_mfma_f32_16x16x32_f16 a[4:7], v[74:77], a[164:167], a[4:7]
	v_mfma_f32_16x16x32_f16 a[0:3], v[74:77], a[168:171], a[0:3]
	v_mfma_f32_16x16x32_f16 a[0:3], v[78:81], a[168:171], a[0:3]
	v_mfma_f32_16x16x32_f16 a[0:3], v[74:77], a[172:175], a[0:3]
	global_load_dwordx4 a[152:155], v[90:91], off offset:448
	global_load_dwordx4 a[156:159], v[92:93], off offset:448
	global_load_dwordx4 a[160:163], v[94:95], off offset:448
	global_load_dwordx4 a[164:167], v[96:97], off offset:448
	global_load_dwordx4 a[168:171], v[98:99], off offset:448
	global_load_dwordx4 a[172:175], v[100:101], off offset:448
	s_waitcnt vmcnt(37)
	v_accvgpr_read_b32 v0, a56
	v_accvgpr_read_b32 v1, a57
	v_accvgpr_read_b32 v2, a58
	v_accvgpr_read_b32 v3, a59
	v_accvgpr_read_b32 v4, a60
	v_accvgpr_read_b32 v5, a61
	v_accvgpr_read_b32 v6, a62
	v_accvgpr_read_b32 v7, a63
	v_accvgpr_read_b32 v32, a204
	v_accvgpr_read_b32 v33, a205
	v_accvgpr_read_b32 v34, a206
	v_accvgpr_read_b32 v35, a207
	v_accvgpr_read_b32 v36, a208
	v_accvgpr_read_b32 v37, a209
	v_accvgpr_read_b32 v38, a210
	v_accvgpr_read_b32 v39, a211
	v_accvgpr_read_b32 v40, a212
	v_accvgpr_read_b32 v41, a213
	v_accvgpr_read_b32 v42, a214
	v_accvgpr_read_b32 v43, a215
	v_accvgpr_read_b32 v44, a216
	v_accvgpr_read_b32 v45, a217
	v_accvgpr_read_b32 v46, a218
	v_accvgpr_read_b32 v47, a219
	v_accvgpr_read_b32 v58, a220
	v_accvgpr_read_b32 v59, a221
	v_accvgpr_read_b32 v60, a222
	v_accvgpr_read_b32 v61, a223
	v_accvgpr_read_b32 v62, a224
	v_accvgpr_read_b32 v63, a225
	v_accvgpr_read_b32 v64, a226
	v_accvgpr_read_b32 v65, a227
	global_load_dwordx4 a[56:59], v[22:23], off offset:1664
	global_load_dwordx4 a[60:63], v[22:23], off offset:1680
	global_load_dwordx4 a[204:207], v[14:15], off offset:1024
	global_load_dwordx4 a[208:211], v[14:15], off offset:1040
	global_load_dwordx4 a[212:215], v[84:85], off offset:1024
	global_load_dwordx4 a[216:219], v[84:85], off offset:1040
	global_load_dwordx4 a[220:223], v[86:87], off offset:1024
	global_load_dwordx4 a[224:227], v[86:87], off offset:1040
	v_pk_mul_f32 v[0:1], v[28:29], v[0:1]
	v_pk_mul_f32 v[2:3], v[28:29], v[2:3]
	v_pk_mul_f32 v[4:5], v[28:29], v[4:5]
	v_pk_mul_f32 v[6:7], v[28:29], v[6:7]
	v_pk_mul_f32 v[0:1], v[0:1], v[32:33]
	v_pk_mul_f32 v[2:3], v[2:3], v[34:35]
	v_pk_mul_f32 v[4:5], v[4:5], v[36:37]
	v_pk_mul_f32 v[6:7], v[6:7], v[38:39]
	v_pk_add_f32 v[40:41], v[40:41], 1.0 op_sel_hi:[1,0]
	v_pk_add_f32 v[42:43], v[42:43], 1.0 op_sel_hi:[1,0]
	v_pk_add_f32 v[44:45], v[44:45], 1.0 op_sel_hi:[1,0]
	v_pk_add_f32 v[46:47], v[46:47], 1.0 op_sel_hi:[1,0]
	v_pk_fma_f32 v[0:1], v[0:1], v[40:41], v[58:59]
	v_pk_fma_f32 v[2:3], v[2:3], v[42:43], v[60:61]
	v_pk_fma_f32 v[4:5], v[4:5], v[44:45], v[62:63]
	v_pk_fma_f32 v[6:7], v[6:7], v[46:47], v[64:65]
	v_cvt_pk_f16_f32 v74, v0, v1
	v_cvt_pk_f16_f32 v75, v2, v3
	v_cvt_pk_f16_f32 v76, v4, v5
	v_cvt_pk_f16_f32 v77, v6, v7
	v_cvt_f32_f16_e32 v66, v74
	v_cvt_f32_f16_sdwa v67, v74 dst_sel:DWORD dst_unused:UNUSED_PAD src0_sel:WORD_1
	v_cvt_f32_f16_e32 v68, v75
	v_cvt_f32_f16_sdwa v69, v75 dst_sel:DWORD dst_unused:UNUSED_PAD src0_sel:WORD_1
	v_cvt_f32_f16_e32 v70, v76
	v_cvt_f32_f16_sdwa v71, v76 dst_sel:DWORD dst_unused:UNUSED_PAD src0_sel:WORD_1
	v_cvt_f32_f16_e32 v72, v77
	v_cvt_f32_f16_sdwa v73, v77 dst_sel:DWORD dst_unused:UNUSED_PAD src0_sel:WORD_1
	v_pk_add_f32 v[0:1], v[0:1], v[66:67] neg_lo:[0,1] neg_hi:[0,1]
	v_pk_add_f32 v[2:3], v[2:3], v[68:69] neg_lo:[0,1] neg_hi:[0,1]
	v_pk_add_f32 v[4:5], v[4:5], v[70:71] neg_lo:[0,1] neg_hi:[0,1]
	v_pk_add_f32 v[6:7], v[6:7], v[72:73] neg_lo:[0,1] neg_hi:[0,1]
	s_nop 0
	v_cvt_pk_f16_f32 v78, v0, v1
	v_cvt_pk_f16_f32 v79, v2, v3
	v_cvt_pk_f16_f32 v80, v4, v5
	v_cvt_pk_f16_f32 v81, v6, v7
	global_store_dwordx4 v[88:89], v[74:77], off offset:320
	s_waitcnt vmcnt(39)
	v_mfma_f32_16x16x32_f16 a[8:11], v[74:77], a[228:231], a[8:11]
	v_mfma_f32_16x16x32_f16 a[8:11], v[78:81], a[228:231], a[8:11]
	v_mfma_f32_16x16x32_f16 a[8:11], v[74:77], a[232:235], a[8:11]
	v_mfma_f32_16x16x32_f16 a[4:7], v[74:77], a[236:239], a[4:7]
	v_mfma_f32_16x16x32_f16 a[4:7], v[78:81], a[236:239], a[4:7]
	v_mfma_f32_16x16x32_f16 a[4:7], v[74:77], a[240:243], a[4:7]
	v_mfma_f32_16x16x32_f16 a[0:3], v[74:77], a[244:247], a[0:3]
	v_mfma_f32_16x16x32_f16 a[0:3], v[78:81], a[244:247], a[0:3]
	v_mfma_f32_16x16x32_f16 a[0:3], v[74:77], a[248:251], a[0:3]
	global_load_dwordx4 a[228:231], v[90:91], off offset:512
	global_load_dwordx4 a[232:235], v[92:93], off offset:512
	global_load_dwordx4 a[236:239], v[94:95], off offset:512
	global_load_dwordx4 a[240:243], v[96:97], off offset:512
	global_load_dwordx4 a[244:247], v[98:99], off offset:512
	global_load_dwordx4 a[248:251], v[100:101], off offset:512
	s_waitcnt vmcnt(37)
; DI f4 mfma16(h8 a, h8 b, f4 c) { return __builtin_amdgcn_mfma_f32_16x16x32_f16(a, b, c, 0, 0, 0); }
; DI void row2_phase(const Params& P, int l, int r_begin, char* smem) {
;     ...
;     for (int kk = 0; kk < 32; kk++) {
;       const int k0 = kk * 32;
;       float x[8], g[8], s1[8], s0[8];
;       *(float4*)&x[0] = *(const float4*)(xm + k0); *(float4*)&x[4] = *(const float4*)(xm + k0 + 4);
;       *(float4*)&g[0] = *(const float4*)(gam + fq * 8 + k0); *(float4*)&g[4] = *(const float4*)(gam + fq * 8 + k0 + 4);
;       *(float4*)&s1[0] = *(const float4*)(sc + k0); *(float4*)&s1[4] = *(const float4*)(sc + k0 + 4);
;       *(float4*)&s0[0] = *(const float4*)(sh + k0); *(float4*)&s0[4] = *(const float4*)(sh + k0 + 4);
;       h8 hi, lo;
; #pragma unroll
;       for (int i = 0; i < 8; i++) {
;         float v = x[i] * rstd * g[i] * (1.f + s1[i]) + s0[i];
;         hi[i] = (half_t)v; lo[i] = (half_t)(v - (float)hi[i]);
;       }
;       *(h8*)(hxo + k0) = hi;
; #pragma unroll
;       for (int n3 = 0; n3 < 3; n3++) {
;         h8 bh = *(const h8*)(Whi + (size_t)(n3 * 16 + fr) * 1024 + k0 + fq * 8);
;         h8 bl = *(const h8*)(Wlo + (size_t)(n3 * 16 + fr) * 1024 + k0 + fq * 8);
;         acc[n3] = mfma16(hi, bh, acc[n3]); acc[n3] = mfma16(lo, bh, acc[n3]); acc[n3] = mfma16(hi, bl, acc[n3]);
;       }
	v_accvgpr_read_b32 v0, a64
	v_accvgpr_read_b32 v1, a65
	v_accvgpr_read_b32 v2, a66
	v_accvgpr_read_b32 v3, a67
	v_accvgpr_read_b32 v4, a68
	v_accvgpr_read_b32 v5, a69
	v_accvgpr_read_b32 v6, a70
	v_accvgpr_read_b32 v7, a71
	v_accvgpr_read_b32 v32, a80
	v_accvgpr_read_b32 v33, a81
	v_accvgpr_read_b32 v34, a82
	v_accvgpr_read_b32 v35, a83
	v_accvgpr_read_b32 v36, a84
	v_accvgpr_read_b32 v37, a85
	v_accvgpr_read_b32 v38, a86
	v_accvgpr_read_b32 v39, a87
	v_accvgpr_read_b32 v40, a88
	v_accvgpr_read_b32 v41, a89
	v_accvgpr_read_b32 v42, a90
	v_accvgpr_read_b32 v43, a91
	v_accvgpr_read_b32 v44, a92
	v_accvgpr_read_b32 v45, a93
	v_accvgpr_read_b32 v46, a94
	v_accvgpr_read_b32 v47, a95
	v_accvgpr_read_b32 v58, a96
	v_accvgpr_read_b32 v59, a97
	v_accvgpr_read_b32 v60, a98
	v_accvgpr_read_b32 v61, a99
	v_accvgpr_read_b32 v62, a100
	v_accvgpr_read_b32 v63, a101
	v_accvgpr_read_b32 v64, a102
	v_accvgpr_read_b32 v65, a103
	global_load_dwordx4 a[64:67], v[22:23], off offset:1792
	global_load_dwordx4 a[68:71], v[22:23], off offset:1808
	global_load_dwordx4 a[80:83], v[14:15], off offset:1152
	global_load_dwordx4 a[84:87], v[14:15], off offset:1168
	global_load_dwordx4 a[88:91], v[84:85], off offset:1152
	global_load_dwordx4 a[92:95], v[84:85], off offset:1168
	global_load_dwordx4 a[96:99], v[86:87], off offset:1152
	global_load_dwordx4 a[100:103], v[86:87], off offset:1168
	v_pk_mul_f32 v[0:1], v[28:29], v[0:1]
	v_pk_mul_f32 v[2:3], v[28:29], v[2:3]
	v_pk_mul_f32 v[4:5], v[28:29], v[4:5]
	v_pk_mul_f32 v[6:7], v[28:29], v[6:7]
	v_pk_mul_f32 v[0:1], v[0:1], v[32:33]
	v_pk_mul_f32 v[2:3], v[2:3], v[34:35]
	v_pk_mul_f32 v[4:5], v[4:5], v[36:37]
	v_pk_mul_f32 v[6:7], v[6:7], v[38:39]
	v_pk_add_f32 v[40:41], v[40:41], 1.0 op_sel_hi:[1,0]
	v_pk_add_f32 v[42:43], v[42:43], 1.0 op_sel_hi:[1,0]
	v_pk_add_f32 v[44:45], v[44:45], 1.0 op_sel_hi:[1,0]
	v_pk_add_f32 v[46:47], v[46:47], 1.0 op_sel_hi:[1,0]
	v_pk_fma_f32 v[0:1], v[0:1], v[40:41], v[58:59]
	v_pk_fma_f32 v[2:3], v[2:3], v[42:43], v[60:61]
	v_pk_fma_f32 v[4:5], v[4:5], v[44:45], v[62:63]
	v_pk_fma_f32 v[6:7], v[6:7], v[46:47], v[64:65]
	v_cvt_pk_f16_f32 v74, v0, v1
	v_cvt_pk_f16_f32 v75, v2, v3
	v_cvt_pk_f16_f32 v76, v4, v5
	v_cvt_pk_f16_f32 v77, v6, v7
	v_cvt_f32_f16_e32 v66, v74
	v_cvt_f32_f16_sdwa v67, v74 dst_sel:DWORD dst_unused:UNUSED_PAD src0_sel:WORD_1
	v_cvt_f32_f16_e32 v68, v75
	v_cvt_f32_f16_sdwa v69, v75 dst_sel:DWORD dst_unused:UNUSED_PAD src0_sel:WORD_1
	v_cvt_f32_f16_e32 v70, v76
	v_cvt_f32_f16_sdwa v71, v76 dst_sel:DWORD dst_unused:UNUSED_PAD src0_sel:WORD_1
	v_cvt_f32_f16_e32 v72, v77
	v_cvt_f32_f16_sdwa v73, v77 dst_sel:DWORD dst_unused:UNUSED_PAD src0_sel:WORD_1
	v_pk_add_f32 v[0:1], v[0:1], v[66:67] neg_lo:[0,1] neg_hi:[0,1]
	v_pk_add_f32 v[2:3], v[2:3], v[68:69] neg_lo:[0,1] neg_hi:[0,1]
	v_pk_add_f32 v[4:5], v[4:5], v[70:71] neg_lo:[0,1] neg_hi:[0,1]
	v_pk_add_f32 v[6:7], v[6:7], v[72:73] neg_lo:[0,1] neg_hi:[0,1]
	s_nop 0
	v_cvt_pk_f16_f32 v78, v0, v1
	v_cvt_pk_f16_f32 v79, v2, v3
	v_cvt_pk_f16_f32 v80, v4, v5
	v_cvt_pk_f16_f32 v81, v6, v7
	global_store_dwordx4 v[88:89], v[74:77], off offset:384
	s_waitcnt vmcnt(39)
	v_mfma_f32_16x16x32_f16 a[8:11], v[74:77], a[104:107], a[8:11]
	v_mfma_f32_16x16x32_f16 a[8:11], v[78:81], a[104:107], a[8:11]
	v_mfma_f32_16x16x32_f16 a[8:11], v[74:77], a[108:111], a[8:11]
	v_mfma_f32_16x16x32_f16 a[4:7], v[74:77], a[112:115], a[4:7]
	v_mfma_f32_16x16x32_f16 a[4:7], v[78:81], a[112:115], a[4:7]
	v_mfma_f32_16x16x32_f16 a[4:7], v[74:77], a[116:119], a[4:7]
	v_mfma_f32_16x16x32_f16 a[0:3], v[74:77], a[120:123], a[0:3]
	v_mfma_f32_16x16x32_f16 a[0:3], v[78:81], a[120:123], a[0:3]
	v_mfma_f32_16x16x32_f16 a[0:3], v[74:77], a[124:127], a[0:3]
	global_load_dwordx4 a[104:107], v[90:91], off offset:576
	global_load_dwordx4 a[108:111], v[92:93], off offset:576
	global_load_dwordx4 a[112:115], v[94:95], off offset:576
	global_load_dwordx4 a[116:119], v[96:97], off offset:576
	global_load_dwordx4 a[120:123], v[98:99], off offset:576
	global_load_dwordx4 a[124:127], v[100:101], off offset:576
	s_waitcnt vmcnt(37)
	v_accvgpr_read_b32 v0, a72
	v_accvgpr_read_b32 v1, a73
	v_accvgpr_read_b32 v2, a74
	v_accvgpr_read_b32 v3, a75
	v_accvgpr_read_b32 v4, a76
	v_accvgpr_read_b32 v5, a77
	v_accvgpr_read_b32 v6, a78
	v_accvgpr_read_b32 v7, a79
	v_accvgpr_read_b32 v32, a128
	v_accvgpr_read_b32 v33, a129
	v_accvgpr_read_b32 v34, a130
	v_accvgpr_read_b32 v35, a131
	v_accvgpr_read_b32 v36, a132
	v_accvgpr_read_b32 v37, a133
	v_accvgpr_read_b32 v38, a134
	v_accvgpr_read_b32 v39, a135
	v_accvgpr_read_b32 v40, a136
	v_accvgpr_read_b32 v41, a137
	v_accvgpr_read_b32 v42, a138
	v_accvgpr_read_b32 v43, a139
	v_accvgpr_read_b32 v44, a140
	v_accvgpr_read_b32 v45, a141
	v_accvgpr_read_b32 v46, a142
	v_accvgpr_read_b32 v47, a143
	v_accvgpr_read_b32 v58, a144
	v_accvgpr_read_b32 v59, a145
	v_accvgpr_read_b32 v60, a146
	v_accvgpr_read_b32 v61, a147
	v_accvgpr_read_b32 v62, a148
	v_accvgpr_read_b32 v63, a149
	v_accvgpr_read_b32 v64, a150
	v_accvgpr_read_b32 v65, a151
	global_load_dwordx4 a[72:75], v[22:23], off offset:1920
	global_load_dwordx4 a[76:79], v[22:23], off offset:1936
	global_load_dwordx4 a[128:131], v[14:15], off offset:1280
	global_load_dwordx4 a[132:135], v[14:15], off offset:1296
	global_load_dwordx4 a[136:139], v[84:85], off offset:1280
	global_load_dwordx4 a[140:143], v[84:85], off offset:1296
	global_load_dwordx4 a[144:147], v[86:87], off offset:1280
	global_load_dwordx4 a[148:151], v[86:87], off offset:1296
	v_pk_mul_f32 v[0:1], v[28:29], v[0:1]
	v_pk_mul_f32 v[2:3], v[28:29], v[2:3]
	v_pk_mul_f32 v[4:5], v[28:29], v[4:5]
	v_pk_mul_f32 v[6:7], v[28:29], v[6:7]
; DI f4 mfma16(h8 a, h8 b, f4 c) { return __builtin_amdgcn_mfma_f32_16x16x32_f16(a, b, c, 0, 0, 0); }
; DI void row2_phase(const Params& P, int l, int r_begin, char* smem) {
;     ...
;     for (int kk = 0; kk < 32; kk++) {
;       const int k0 = kk * 32;
;       float x[8], g[8], s1[8], s0[8];
;       *(float4*)&x[0] = *(const float4*)(xm + k0); *(float4*)&x[4] = *(const float4*)(xm + k0 + 4);
;       *(float4*)&g[0] = *(const float4*)(gam + fq * 8 + k0); *(float4*)&g[4] = *(const float4*)(gam + fq * 8 + k0 + 4);
;       *(float4*)&s1[0] = *(const float4*)(sc + k0); *(float4*)&s1[4] = *(const float4*)(sc + k0 + 4);
;       *(float4*)&s0[0] = *(const float4*)(sh + k0); *(float4*)&s0[4] = *(const float4*)(sh + k0 + 4);
;       h8 hi, lo;
; #pragma unroll
;       for (int i = 0; i < 8; i++) {
;         float v = x[i] * rstd * g[i] * (1.f + s1[i]) + s0[i];
;         hi[i] = (half_t)v; lo[i] = (half_t)(v - (float)hi[i]);
;       }
;       *(h8*)(hxo + k0) = hi;
; #pragma unroll
;       for (int n3 = 0; n3 < 3; n3++) {
;         h8 bh = *(const h8*)(Whi + (size_t)(n3 * 16 + fr) * 1024 + k0 + fq * 8);
;         h8 bl = *(const h8*)(Wlo + (size_t)(n3 * 16 + fr) * 1024 + k0 + fq * 8);
;         acc[n3] = mfma16(hi, bh, acc[n3]); acc[n3] = mfma16(lo, bh, acc[n3]); acc[n3] = mfma16(hi, bl, acc[n3]);
;       }
	v_pk_mul_f32 v[0:1], v[0:1], v[32:33]
	v_pk_mul_f32 v[2:3], v[2:3], v[34:35]
	v_pk_mul_f32 v[4:5], v[4:5], v[36:37]
	v_pk_mul_f32 v[6:7], v[6:7], v[38:39]
	v_pk_add_f32 v[40:41], v[40:41], 1.0 op_sel_hi:[1,0]
	v_pk_add_f32 v[42:43], v[42:43], 1.0 op_sel_hi:[1,0]
	v_pk_add_f32 v[44:45], v[44:45], 1.0 op_sel_hi:[1,0]
	v_pk_add_f32 v[46:47], v[46:47], 1.0 op_sel_hi:[1,0]
	v_pk_fma_f32 v[0:1], v[0:1], v[40:41], v[58:59]
	v_pk_fma_f32 v[2:3], v[2:3], v[42:43], v[60:61]
	v_pk_fma_f32 v[4:5], v[4:5], v[44:45], v[62:63]
	v_pk_fma_f32 v[6:7], v[6:7], v[46:47], v[64:65]
	v_cvt_pk_f16_f32 v74, v0, v1
	v_cvt_pk_f16_f32 v75, v2, v3
	v_cvt_pk_f16_f32 v76, v4, v5
	v_cvt_pk_f16_f32 v77, v6, v7
	v_cvt_f32_f16_e32 v66, v74
	v_cvt_f32_f16_sdwa v67, v74 dst_sel:DWORD dst_unused:UNUSED_PAD src0_sel:WORD_1
	v_cvt_f32_f16_e32 v68, v75
	v_cvt_f32_f16_sdwa v69, v75 dst_sel:DWORD dst_unused:UNUSED_PAD src0_sel:WORD_1
	v_cvt_f32_f16_e32 v70, v76
	v_cvt_f32_f16_sdwa v71, v76 dst_sel:DWORD dst_unused:UNUSED_PAD src0_sel:WORD_1
	v_cvt_f32_f16_e32 v72, v77
	v_cvt_f32_f16_sdwa v73, v77 dst_sel:DWORD dst_unused:UNUSED_PAD src0_sel:WORD_1
	v_pk_add_f32 v[0:1], v[0:1], v[66:67] neg_lo:[0,1] neg_hi:[0,1]
	v_pk_add_f32 v[2:3], v[2:3], v[68:69] neg_lo:[0,1] neg_hi:[0,1]
	v_pk_add_f32 v[4:5], v[4:5], v[70:71] neg_lo:[0,1] neg_hi:[0,1]
	v_pk_add_f32 v[6:7], v[6:7], v[72:73] neg_lo:[0,1] neg_hi:[0,1]
	s_nop 0
	v_cvt_pk_f16_f32 v78, v0, v1
	v_cvt_pk_f16_f32 v79, v2, v3
	v_cvt_pk_f16_f32 v80, v4, v5
	v_cvt_pk_f16_f32 v81, v6, v7
	global_store_dwordx4 v[88:89], v[74:77], off offset:448
	s_waitcnt vmcnt(39)
	v_mfma_f32_16x16x32_f16 a[8:11], v[74:77], a[152:155], a[8:11]
	v_mfma_f32_16x16x32_f16 a[8:11], v[78:81], a[152:155], a[8:11]
	v_mfma_f32_16x16x32_f16 a[8:11], v[74:77], a[156:159], a[8:11]
	v_mfma_f32_16x16x32_f16 a[4:7], v[74:77], a[160:163], a[4:7]
	v_mfma_f32_16x16x32_f16 a[4:7], v[78:81], a[160:163], a[4:7]
	v_mfma_f32_16x16x32_f16 a[4:7], v[74:77], a[164:167], a[4:7]
	v_mfma_f32_16x16x32_f16 a[0:3], v[74:77], a[168:171], a[0:3]
	v_mfma_f32_16x16x32_f16 a[0:3], v[78:81], a[168:171], a[0:3]
	v_mfma_f32_16x16x32_f16 a[0:3], v[74:77], a[172:175], a[0:3]
	global_load_dwordx4 a[152:155], v[90:91], off offset:640
	global_load_dwordx4 a[156:159], v[92:93], off offset:640
	global_load_dwordx4 a[160:163], v[94:95], off offset:640
	global_load_dwordx4 a[164:167], v[96:97], off offset:640
	global_load_dwordx4 a[168:171], v[98:99], off offset:640
	global_load_dwordx4 a[172:175], v[100:101], off offset:640
	s_waitcnt vmcnt(37)
	v_accvgpr_read_b32 v0, a16
	v_accvgpr_read_b32 v1, a17
	v_accvgpr_read_b32 v2, a18
	v_accvgpr_read_b32 v3, a19
	v_accvgpr_read_b32 v4, a20
	v_accvgpr_read_b32 v5, a21
	v_accvgpr_read_b32 v6, a22
	v_accvgpr_read_b32 v7, a23
	v_accvgpr_read_b32 v32, a204
	v_accvgpr_read_b32 v33, a205
	v_accvgpr_read_b32 v34, a206
	v_accvgpr_read_b32 v35, a207
	v_accvgpr_read_b32 v36, a208
	v_accvgpr_read_b32 v37, a209
	v_accvgpr_read_b32 v38, a210
	v_accvgpr_read_b32 v39, a211
	v_accvgpr_read_b32 v40, a212
	v_accvgpr_read_b32 v41, a213
	v_accvgpr_read_b32 v42, a214
	v_accvgpr_read_b32 v43, a215
	v_accvgpr_read_b32 v44, a216
	v_accvgpr_read_b32 v45, a217
	v_accvgpr_read_b32 v46, a218
	v_accvgpr_read_b32 v47, a219
	v_accvgpr_read_b32 v58, a220
	v_accvgpr_read_b32 v59, a221
	v_accvgpr_read_b32 v60, a222
	v_accvgpr_read_b32 v61, a223
	v_accvgpr_read_b32 v62, a224
	v_accvgpr_read_b32 v63, a225
	v_accvgpr_read_b32 v64, a226
	v_accvgpr_read_b32 v65, a227
	global_load_dwordx4 a[16:19], v[22:23], off offset:2048
	global_load_dwordx4 a[20:23], v[22:23], off offset:2064
	global_load_dwordx4 a[204:207], v[14:15], off offset:1408
	global_load_dwordx4 a[208:211], v[14:15], off offset:1424
	global_load_dwordx4 a[212:215], v[84:85], off offset:1408
	global_load_dwordx4 a[216:219], v[84:85], off offset:1424
	global_load_dwordx4 a[220:223], v[86:87], off offset:1408
	global_load_dwordx4 a[224:227], v[86:87], off offset:1424
	v_pk_mul_f32 v[0:1], v[28:29], v[0:1]
	v_pk_mul_f32 v[2:3], v[28:29], v[2:3]
	v_pk_mul_f32 v[4:5], v[28:29], v[4:5]
	v_pk_mul_f32 v[6:7], v[28:29], v[6:7]
	v_pk_mul_f32 v[0:1], v[0:1], v[32:33]
	v_pk_mul_f32 v[2:3], v[2:3], v[34:35]
	v_pk_mul_f32 v[4:5], v[4:5], v[36:37]
	v_pk_mul_f32 v[6:7], v[6:7], v[38:39]
	v_pk_add_f32 v[40:41], v[40:41], 1.0 op_sel_hi:[1,0]
	v_pk_add_f32 v[42:43], v[42:43], 1.0 op_sel_hi:[1,0]
	v_pk_add_f32 v[44:45], v[44:45], 1.0 op_sel_hi:[1,0]
	v_pk_add_f32 v[46:47], v[46:47], 1.0 op_sel_hi:[1,0]
	v_pk_fma_f32 v[0:1], v[0:1], v[40:41], v[58:59]
	v_pk_fma_f32 v[2:3], v[2:3], v[42:43], v[60:61]
	v_pk_fma_f32 v[4:5], v[4:5], v[44:45], v[62:63]
	v_pk_fma_f32 v[6:7], v[6:7], v[46:47], v[64:65]
	v_cvt_pk_f16_f32 v74, v0, v1
	v_cvt_pk_f16_f32 v75, v2, v3
	v_cvt_pk_f16_f32 v76, v4, v5
	v_cvt_pk_f16_f32 v77, v6, v7
	v_cvt_f32_f16_e32 v66, v74
	v_cvt_f32_f16_sdwa v67, v74 dst_sel:DWORD dst_unused:UNUSED_PAD src0_sel:WORD_1
	v_cvt_f32_f16_e32 v68, v75
	v_cvt_f32_f16_sdwa v69, v75 dst_sel:DWORD dst_unused:UNUSED_PAD src0_sel:WORD_1
	v_cvt_f32_f16_e32 v70, v76
	v_cvt_f32_f16_sdwa v71, v76 dst_sel:DWORD dst_unused:UNUSED_PAD src0_sel:WORD_1
	v_cvt_f32_f16_e32 v72, v77
	v_cvt_f32_f16_sdwa v73, v77 dst_sel:DWORD dst_unused:UNUSED_PAD src0_sel:WORD_1
	v_pk_add_f32 v[0:1], v[0:1], v[66:67] neg_lo:[0,1] neg_hi:[0,1]
	v_pk_add_f32 v[2:3], v[2:3], v[68:69] neg_lo:[0,1] neg_hi:[0,1]
	v_pk_add_f32 v[4:5], v[4:5], v[70:71] neg_lo:[0,1] neg_hi:[0,1]
	v_pk_add_f32 v[6:7], v[6:7], v[72:73] neg_lo:[0,1] neg_hi:[0,1]
	s_nop 0
	v_cvt_pk_f16_f32 v78, v0, v1
	v_cvt_pk_f16_f32 v79, v2, v3
	v_cvt_pk_f16_f32 v80, v4, v5
	v_cvt_pk_f16_f32 v81, v6, v7
	global_store_dwordx4 v[88:89], v[74:77], off offset:512
	s_waitcnt vmcnt(39)
; DI f4 mfma16(h8 a, h8 b, f4 c) { return __builtin_amdgcn_mfma_f32_16x16x32_f16(a, b, c, 0, 0, 0); }
; DI void row2_phase(const Params& P, int l, int r_begin, char* smem) {
;     ...
;     for (int kk = 0; kk < 32; kk++) {
;       const int k0 = kk * 32;
;       float x[8], g[8], s1[8], s0[8];
;       *(float4*)&x[0] = *(const float4*)(xm + k0); *(float4*)&x[4] = *(const float4*)(xm + k0 + 4);
;       *(float4*)&g[0] = *(const float4*)(gam + fq * 8 + k0); *(float4*)&g[4] = *(const float4*)(gam + fq * 8 + k0 + 4);
;       *(float4*)&s1[0] = *(const float4*)(sc + k0); *(float4*)&s1[4] = *(const float4*)(sc + k0 + 4);
;       *(float4*)&s0[0] = *(const float4*)(sh + k0); *(float4*)&s0[4] = *(const float4*)(sh + k0 + 4);
;       h8 hi, lo;
; #pragma unroll
;       for (int i = 0; i < 8; i++) {
;         float v = x[i] * rstd * g[i] * (1.f + s1[i]) + s0[i];
;         hi[i] = (half_t)v; lo[i] = (half_t)(v - (float)hi[i]);
;       }
;       *(h8*)(hxo + k0) = hi;
; #pragma unroll
;       for (int n3 = 0; n3 < 3; n3++) {
;         h8 bh = *(const h8*)(Whi + (size_t)(n3 * 16 + fr) * 1024 + k0 + fq * 8);
;         h8 bl = *(const h8*)(Wlo + (size_t)(n3 * 16 + fr) * 1024 + k0 + fq * 8);
;         acc[n3] = mfma16(hi, bh, acc[n3]); acc[n3] = mfma16(lo, bh, acc[n3]); acc[n3] = mfma16(hi, bl, acc[n3]);
;       }
	v_mfma_f32_16x16x32_f16 a[8:11], v[74:77], a[228:231], a[8:11]
	v_mfma_f32_16x16x32_f16 a[8:11], v[78:81], a[228:231], a[8:11]
	v_mfma_f32_16x16x32_f16 a[8:11], v[74:77], a[232:235], a[8:11]
	v_mfma_f32_16x16x32_f16 a[4:7], v[74:77], a[236:239], a[4:7]
	v_mfma_f32_16x16x32_f16 a[4:7], v[78:81], a[236:239], a[4:7]
	v_mfma_f32_16x16x32_f16 a[4:7], v[74:77], a[240:243], a[4:7]
	v_mfma_f32_16x16x32_f16 a[0:3], v[74:77], a[244:247], a[0:3]
	v_mfma_f32_16x16x32_f16 a[0:3], v[78:81], a[244:247], a[0:3]
	v_mfma_f32_16x16x32_f16 a[0:3], v[74:77], a[248:251], a[0:3]
	global_load_dwordx4 a[228:231], v[90:91], off offset:704
	global_load_dwordx4 a[232:235], v[92:93], off offset:704
	global_load_dwordx4 a[236:239], v[94:95], off offset:704
	global_load_dwordx4 a[240:243], v[96:97], off offset:704
	global_load_dwordx4 a[244:247], v[98:99], off offset:704
	global_load_dwordx4 a[248:251], v[100:101], off offset:704
	s_waitcnt vmcnt(37)
	v_accvgpr_read_b32 v0, a24
	v_accvgpr_read_b32 v1, a25
	v_accvgpr_read_b32 v2, a26
	v_accvgpr_read_b32 v3, a27
	v_accvgpr_read_b32 v4, a28
	v_accvgpr_read_b32 v5, a29
	v_accvgpr_read_b32 v6, a30
	v_accvgpr_read_b32 v7, a31
	v_accvgpr_read_b32 v32, a80
	v_accvgpr_read_b32 v33, a81
	v_accvgpr_read_b32 v34, a82
	v_accvgpr_read_b32 v35, a83
	v_accvgpr_read_b32 v36, a84
	v_accvgpr_read_b32 v37, a85
	v_accvgpr_read_b32 v38, a86
	v_accvgpr_read_b32 v39, a87
	v_accvgpr_read_b32 v40, a88
	v_accvgpr_read_b32 v41, a89
	v_accvgpr_read_b32 v42, a90
	v_accvgpr_read_b32 v43, a91
	v_accvgpr_read_b32 v44, a92
	v_accvgpr_read_b32 v45, a93
	v_accvgpr_read_b32 v46, a94
	v_accvgpr_read_b32 v47, a95
	v_accvgpr_read_b32 v58, a96
	v_accvgpr_read_b32 v59, a97
	v_accvgpr_read_b32 v60, a98
	v_accvgpr_read_b32 v61, a99
	v_accvgpr_read_b32 v62, a100
	v_accvgpr_read_b32 v63, a101
	v_accvgpr_read_b32 v64, a102
	v_accvgpr_read_b32 v65, a103
	global_load_dwordx4 a[24:27], v[22:23], off offset:2176
	global_load_dwordx4 a[28:31], v[22:23], off offset:2192
	global_load_dwordx4 a[80:83], v[14:15], off offset:1536
	global_load_dwordx4 a[84:87], v[14:15], off offset:1552
	global_load_dwordx4 a[88:91], v[84:85], off offset:1536
	global_load_dwordx4 a[92:95], v[84:85], off offset:1552
	global_load_dwordx4 a[96:99], v[86:87], off offset:1536
	global_load_dwordx4 a[100:103], v[86:87], off offset:1552
	v_pk_mul_f32 v[0:1], v[28:29], v[0:1]
	v_pk_mul_f32 v[2:3], v[28:29], v[2:3]
	v_pk_mul_f32 v[4:5], v[28:29], v[4:5]
	v_pk_mul_f32 v[6:7], v[28:29], v[6:7]
	v_pk_mul_f32 v[0:1], v[0:1], v[32:33]
	v_pk_mul_f32 v[2:3], v[2:3], v[34:35]
	v_pk_mul_f32 v[4:5], v[4:5], v[36:37]
	v_pk_mul_f32 v[6:7], v[6:7], v[38:39]
	v_pk_add_f32 v[40:41], v[40:41], 1.0 op_sel_hi:[1,0]
	v_pk_add_f32 v[42:43], v[42:43], 1.0 op_sel_hi:[1,0]
	v_pk_add_f32 v[44:45], v[44:45], 1.0 op_sel_hi:[1,0]
	v_pk_add_f32 v[46:47], v[46:47], 1.0 op_sel_hi:[1,0]
	v_pk_fma_f32 v[0:1], v[0:1], v[40:41], v[58:59]
	v_pk_fma_f32 v[2:3], v[2:3], v[42:43], v[60:61]
	v_pk_fma_f32 v[4:5], v[4:5], v[44:45], v[62:63]
	v_pk_fma_f32 v[6:7], v[6:7], v[46:47], v[64:65]
	v_cvt_pk_f16_f32 v74, v0, v1
	v_cvt_pk_f16_f32 v75, v2, v3
	v_cvt_pk_f16_f32 v76, v4, v5
	v_cvt_pk_f16_f32 v77, v6, v7
	v_cvt_f32_f16_e32 v66, v74
	v_cvt_f32_f16_sdwa v67, v74 dst_sel:DWORD dst_unused:UNUSED_PAD src0_sel:WORD_1
	v_cvt_f32_f16_e32 v68, v75
	v_cvt_f32_f16_sdwa v69, v75 dst_sel:DWORD dst_unused:UNUSED_PAD src0_sel:WORD_1
	v_cvt_f32_f16_e32 v70, v76
	v_cvt_f32_f16_sdwa v71, v76 dst_sel:DWORD dst_unused:UNUSED_PAD src0_sel:WORD_1
	v_cvt_f32_f16_e32 v72, v77
	v_cvt_f32_f16_sdwa v73, v77 dst_sel:DWORD dst_unused:UNUSED_PAD src0_sel:WORD_1
	v_pk_add_f32 v[0:1], v[0:1], v[66:67] neg_lo:[0,1] neg_hi:[0,1]
	v_pk_add_f32 v[2:3], v[2:3], v[68:69] neg_lo:[0,1] neg_hi:[0,1]
	v_pk_add_f32 v[4:5], v[4:5], v[70:71] neg_lo:[0,1] neg_hi:[0,1]
	v_pk_add_f32 v[6:7], v[6:7], v[72:73] neg_lo:[0,1] neg_hi:[0,1]
	s_nop 0
	v_cvt_pk_f16_f32 v78, v0, v1
	v_cvt_pk_f16_f32 v79, v2, v3
	v_cvt_pk_f16_f32 v80, v4, v5
	v_cvt_pk_f16_f32 v81, v6, v7
	global_store_dwordx4 v[88:89], v[74:77], off offset:576
	s_waitcnt vmcnt(39)
	v_mfma_f32_16x16x32_f16 a[8:11], v[74:77], a[104:107], a[8:11]
	v_mfma_f32_16x16x32_f16 a[8:11], v[78:81], a[104:107], a[8:11]
	v_mfma_f32_16x16x32_f16 a[8:11], v[74:77], a[108:111], a[8:11]
	v_mfma_f32_16x16x32_f16 a[4:7], v[74:77], a[112:115], a[4:7]
	v_mfma_f32_16x16x32_f16 a[4:7], v[78:81], a[112:115], a[4:7]
	v_mfma_f32_16x16x32_f16 a[4:7], v[74:77], a[116:119], a[4:7]
	v_mfma_f32_16x16x32_f16 a[0:3], v[74:77], a[120:123], a[0:3]
	v_mfma_f32_16x16x32_f16 a[0:3], v[78:81], a[120:123], a[0:3]
	v_mfma_f32_16x16x32_f16 a[0:3], v[74:77], a[124:127], a[0:3]
	global_load_dwordx4 a[104:107], v[90:91], off offset:768
	global_load_dwordx4 a[108:111], v[92:93], off offset:768
	global_load_dwordx4 a[112:115], v[94:95], off offset:768
	global_load_dwordx4 a[116:119], v[96:97], off offset:768
	global_load_dwordx4 a[120:123], v[98:99], off offset:768
	global_load_dwordx4 a[124:127], v[100:101], off offset:768
	s_waitcnt vmcnt(37)
; DI f4 mfma16(h8 a, h8 b, f4 c) { return __builtin_amdgcn_mfma_f32_16x16x32_f16(a, b, c, 0, 0, 0); }
; DI void row2_phase(const Params& P, int l, int r_begin, char* smem) {
;     ...
;     for (int kk = 0; kk < 32; kk++) {
;       const int k0 = kk * 32;
;       float x[8], g[8], s1[8], s0[8];
;       *(float4*)&x[0] = *(const float4*)(xm + k0); *(float4*)&x[4] = *(const float4*)(xm + k0 + 4);
;       *(float4*)&g[0] = *(const float4*)(gam + fq * 8 + k0); *(float4*)&g[4] = *(const float4*)(gam + fq * 8 + k0 + 4);
;       *(float4*)&s1[0] = *(const float4*)(sc + k0); *(float4*)&s1[4] = *(const float4*)(sc + k0 + 4);
;       *(float4*)&s0[0] = *(const float4*)(sh + k0); *(float4*)&s0[4] = *(const float4*)(sh + k0 + 4);
;       h8 hi, lo;
; #pragma unroll
;       for (int i = 0; i < 8; i++) {
;         float v = x[i] * rstd * g[i] * (1.f + s1[i]) + s0[i];
;         hi[i] = (half_t)v; lo[i] = (half_t)(v - (float)hi[i]);
;       }
;       *(h8*)(hxo + k0) = hi;
; #pragma unroll
;       for (int n3 = 0; n3 < 3; n3++) {
;         h8 bh = *(const h8*)(Whi + (size_t)(n3 * 16 + fr) * 1024 + k0 + fq * 8);
;         h8 bl = *(const h8*)(Wlo + (size_t)(n3 * 16 + fr) * 1024 + k0 + fq * 8);
;         acc[n3] = mfma16(hi, bh, acc[n3]); acc[n3] = mfma16(lo, bh, acc[n3]); acc[n3] = mfma16(hi, bl, acc[n3]);
;       }
	v_accvgpr_read_b32 v0, a32
	v_accvgpr_read_b32 v1, a33
	v_accvgpr_read_b32 v2, a34
	v_accvgpr_read_b32 v3, a35
	v_accvgpr_read_b32 v4, a36
	v_accvgpr_read_b32 v5, a37
	v_accvgpr_read_b32 v6, a38
	v_accvgpr_read_b32 v7, a39
	v_accvgpr_read_b32 v32, a128
	v_accvgpr_read_b32 v33, a129
	v_accvgpr_read_b32 v34, a130
	v_accvgpr_read_b32 v35, a131
	v_accvgpr_read_b32 v36, a132
	v_accvgpr_read_b32 v37, a133
	v_accvgpr_read_b32 v38, a134
	v_accvgpr_read_b32 v39, a135
	v_accvgpr_read_b32 v40, a136
	v_accvgpr_read_b32 v41, a137
	v_accvgpr_read_b32 v42, a138
	v_accvgpr_read_b32 v43, a139
	v_accvgpr_read_b32 v44, a140
	v_accvgpr_read_b32 v45, a141
	v_accvgpr_read_b32 v46, a142
	v_accvgpr_read_b32 v47, a143
	v_accvgpr_read_b32 v58, a144
	v_accvgpr_read_b32 v59, a145
	v_accvgpr_read_b32 v60, a146
	v_accvgpr_read_b32 v61, a147
	v_accvgpr_read_b32 v62, a148
	v_accvgpr_read_b32 v63, a149
	v_accvgpr_read_b32 v64, a150
	v_accvgpr_read_b32 v65, a151
	global_load_dwordx4 a[32:35], v[22:23], off offset:2304
	global_load_dwordx4 a[36:39], v[22:23], off offset:2320
	global_load_dwordx4 a[128:131], v[14:15], off offset:1664
	global_load_dwordx4 a[132:135], v[14:15], off offset:1680
	global_load_dwordx4 a[136:139], v[84:85], off offset:1664
	global_load_dwordx4 a[140:143], v[84:85], off offset:1680
	global_load_dwordx4 a[144:147], v[86:87], off offset:1664
	global_load_dwordx4 a[148:151], v[86:87], off offset:1680
	v_pk_mul_f32 v[0:1], v[28:29], v[0:1]
	v_pk_mul_f32 v[2:3], v[28:29], v[2:3]
	v_pk_mul_f32 v[4:5], v[28:29], v[4:5]
	v_pk_mul_f32 v[6:7], v[28:29], v[6:7]
	v_pk_mul_f32 v[0:1], v[0:1], v[32:33]
	v_pk_mul_f32 v[2:3], v[2:3], v[34:35]
	v_pk_mul_f32 v[4:5], v[4:5], v[36:37]
	v_pk_mul_f32 v[6:7], v[6:7], v[38:39]
	v_pk_add_f32 v[40:41], v[40:41], 1.0 op_sel_hi:[1,0]
	v_pk_add_f32 v[42:43], v[42:43], 1.0 op_sel_hi:[1,0]
	v_pk_add_f32 v[44:45], v[44:45], 1.0 op_sel_hi:[1,0]
	v_pk_add_f32 v[46:47], v[46:47], 1.0 op_sel_hi:[1,0]
	v_pk_fma_f32 v[0:1], v[0:1], v[40:41], v[58:59]
	v_pk_fma_f32 v[2:3], v[2:3], v[42:43], v[60:61]
	v_pk_fma_f32 v[4:5], v[4:5], v[44:45], v[62:63]
	v_pk_fma_f32 v[6:7], v[6:7], v[46:47], v[64:65]
	v_cvt_pk_f16_f32 v74, v0, v1
	v_cvt_pk_f16_f32 v75, v2, v3
	v_cvt_pk_f16_f32 v76, v4, v5
	v_cvt_pk_f16_f32 v77, v6, v7
	v_cvt_f32_f16_e32 v66, v74
	v_cvt_f32_f16_sdwa v67, v74 dst_sel:DWORD dst_unused:UNUSED_PAD src0_sel:WORD_1
	v_cvt_f32_f16_e32 v68, v75
	v_cvt_f32_f16_sdwa v69, v75 dst_sel:DWORD dst_unused:UNUSED_PAD src0_sel:WORD_1
	v_cvt_f32_f16_e32 v70, v76
	v_cvt_f32_f16_sdwa v71, v76 dst_sel:DWORD dst_unused:UNUSED_PAD src0_sel:WORD_1
	v_cvt_f32_f16_e32 v72, v77
	v_cvt_f32_f16_sdwa v73, v77 dst_sel:DWORD dst_unused:UNUSED_PAD src0_sel:WORD_1
	v_pk_add_f32 v[0:1], v[0:1], v[66:67] neg_lo:[0,1] neg_hi:[0,1]
	v_pk_add_f32 v[2:3], v[2:3], v[68:69] neg_lo:[0,1] neg_hi:[0,1]
	v_pk_add_f32 v[4:5], v[4:5], v[70:71] neg_lo:[0,1] neg_hi:[0,1]
	v_pk_add_f32 v[6:7], v[6:7], v[72:73] neg_lo:[0,1] neg_hi:[0,1]
	s_nop 0
	v_cvt_pk_f16_f32 v78, v0, v1
	v_cvt_pk_f16_f32 v79, v2, v3
	v_cvt_pk_f16_f32 v80, v4, v5
	v_cvt_pk_f16_f32 v81, v6, v7
	global_store_dwordx4 v[88:89], v[74:77], off offset:640
	s_waitcnt vmcnt(39)
	v_mfma_f32_16x16x32_f16 a[8:11], v[74:77], a[152:155], a[8:11]
	v_mfma_f32_16x16x32_f16 a[8:11], v[78:81], a[152:155], a[8:11]
	v_mfma_f32_16x16x32_f16 a[8:11], v[74:77], a[156:159], a[8:11]
	v_mfma_f32_16x16x32_f16 a[4:7], v[74:77], a[160:163], a[4:7]
	v_mfma_f32_16x16x32_f16 a[4:7], v[78:81], a[160:163], a[4:7]
	v_mfma_f32_16x16x32_f16 a[4:7], v[74:77], a[164:167], a[4:7]
	v_mfma_f32_16x16x32_f16 a[0:3], v[74:77], a[168:171], a[0:3]
	v_mfma_f32_16x16x32_f16 a[0:3], v[78:81], a[168:171], a[0:3]
	v_mfma_f32_16x16x32_f16 a[0:3], v[74:77], a[172:175], a[0:3]
	global_load_dwordx4 a[152:155], v[90:91], off offset:832
	global_load_dwordx4 a[156:159], v[92:93], off offset:832
	global_load_dwordx4 a[160:163], v[94:95], off offset:832
	global_load_dwordx4 a[164:167], v[96:97], off offset:832
	global_load_dwordx4 a[168:171], v[98:99], off offset:832
	global_load_dwordx4 a[172:175], v[100:101], off offset:832
	s_waitcnt vmcnt(37)
	v_accvgpr_read_b32 v0, a40
	v_accvgpr_read_b32 v1, a41
	v_accvgpr_read_b32 v2, a42
	v_accvgpr_read_b32 v3, a43
	v_accvgpr_read_b32 v4, a44
	v_accvgpr_read_b32 v5, a45
	v_accvgpr_read_b32 v6, a46
	v_accvgpr_read_b32 v7, a47
	v_accvgpr_read_b32 v32, a204
	v_accvgpr_read_b32 v33, a205
	v_accvgpr_read_b32 v34, a206
	v_accvgpr_read_b32 v35, a207
	v_accvgpr_read_b32 v36, a208
	v_accvgpr_read_b32 v37, a209
	v_accvgpr_read_b32 v38, a210
	v_accvgpr_read_b32 v39, a211
	v_accvgpr_read_b32 v40, a212
	v_accvgpr_read_b32 v41, a213
	v_accvgpr_read_b32 v42, a214
	v_accvgpr_read_b32 v43, a215
	v_accvgpr_read_b32 v44, a216
	v_accvgpr_read_b32 v45, a217
	v_accvgpr_read_b32 v46, a218
	v_accvgpr_read_b32 v47, a219
	v_accvgpr_read_b32 v58, a220
	v_accvgpr_read_b32 v59, a221
	v_accvgpr_read_b32 v60, a222
	v_accvgpr_read_b32 v61, a223
	v_accvgpr_read_b32 v62, a224
	v_accvgpr_read_b32 v63, a225
	v_accvgpr_read_b32 v64, a226
	v_accvgpr_read_b32 v65, a227
	global_load_dwordx4 a[40:43], v[22:23], off offset:2432
	global_load_dwordx4 a[44:47], v[22:23], off offset:2448
	global_load_dwordx4 a[204:207], v[14:15], off offset:1792
	global_load_dwordx4 a[208:211], v[14:15], off offset:1808
	global_load_dwordx4 a[212:215], v[84:85], off offset:1792
	global_load_dwordx4 a[216:219], v[84:85], off offset:1808
	global_load_dwordx4 a[220:223], v[86:87], off offset:1792
	global_load_dwordx4 a[224:227], v[86:87], off offset:1808
	v_pk_mul_f32 v[0:1], v[28:29], v[0:1]
	v_pk_mul_f32 v[2:3], v[28:29], v[2:3]
	v_pk_mul_f32 v[4:5], v[28:29], v[4:5]
; DI f4 mfma16(h8 a, h8 b, f4 c) { return __builtin_amdgcn_mfma_f32_16x16x32_f16(a, b, c, 0, 0, 0); }
; DI void row2_phase(const Params& P, int l, int r_begin, char* smem) {
;     ...
;     for (int kk = 0; kk < 32; kk++) {
;       const int k0 = kk * 32;
;       float x[8], g[8], s1[8], s0[8];
;       *(float4*)&x[0] = *(const float4*)(xm + k0); *(float4*)&x[4] = *(const float4*)(xm + k0 + 4);
;       *(float4*)&g[0] = *(const float4*)(gam + fq * 8 + k0); *(float4*)&g[4] = *(const float4*)(gam + fq * 8 + k0 + 4);
;       *(float4*)&s1[0] = *(const float4*)(sc + k0); *(float4*)&s1[4] = *(const float4*)(sc + k0 + 4);
;       *(float4*)&s0[0] = *(const float4*)(sh + k0); *(float4*)&s0[4] = *(const float4*)(sh + k0 + 4);
;       h8 hi, lo;
; #pragma unroll
;       for (int i = 0; i < 8; i++) {
;         float v = x[i] * rstd * g[i] * (1.f + s1[i]) + s0[i];
;         hi[i] = (half_t)v; lo[i] = (half_t)(v - (float)hi[i]);
;       }
;       *(h8*)(hxo + k0) = hi;
; #pragma unroll
;       for (int n3 = 0; n3 < 3; n3++) {
;         h8 bh = *(const h8*)(Whi + (size_t)(n3 * 16 + fr) * 1024 + k0 + fq * 8);
;         h8 bl = *(const h8*)(Wlo + (size_t)(n3 * 16 + fr) * 1024 + k0 + fq * 8);
;         acc[n3] = mfma16(hi, bh, acc[n3]); acc[n3] = mfma16(lo, bh, acc[n3]); acc[n3] = mfma16(hi, bl, acc[n3]);
;       }
	v_pk_mul_f32 v[6:7], v[28:29], v[6:7]
	v_pk_mul_f32 v[0:1], v[0:1], v[32:33]
	v_pk_mul_f32 v[2:3], v[2:3], v[34:35]
	v_pk_mul_f32 v[4:5], v[4:5], v[36:37]
	v_pk_mul_f32 v[6:7], v[6:7], v[38:39]
	v_pk_add_f32 v[40:41], v[40:41], 1.0 op_sel_hi:[1,0]
	v_pk_add_f32 v[42:43], v[42:43], 1.0 op_sel_hi:[1,0]
	v_pk_add_f32 v[44:45], v[44:45], 1.0 op_sel_hi:[1,0]
	v_pk_add_f32 v[46:47], v[46:47], 1.0 op_sel_hi:[1,0]
	v_pk_fma_f32 v[0:1], v[0:1], v[40:41], v[58:59]
	v_pk_fma_f32 v[2:3], v[2:3], v[42:43], v[60:61]
	v_pk_fma_f32 v[4:5], v[4:5], v[44:45], v[62:63]
	v_pk_fma_f32 v[6:7], v[6:7], v[46:47], v[64:65]
	v_cvt_pk_f16_f32 v74, v0, v1
	v_cvt_pk_f16_f32 v75, v2, v3
	v_cvt_pk_f16_f32 v76, v4, v5
	v_cvt_pk_f16_f32 v77, v6, v7
	v_cvt_f32_f16_e32 v66, v74
	v_cvt_f32_f16_sdwa v67, v74 dst_sel:DWORD dst_unused:UNUSED_PAD src0_sel:WORD_1
	v_cvt_f32_f16_e32 v68, v75
	v_cvt_f32_f16_sdwa v69, v75 dst_sel:DWORD dst_unused:UNUSED_PAD src0_sel:WORD_1
	v_cvt_f32_f16_e32 v70, v76
	v_cvt_f32_f16_sdwa v71, v76 dst_sel:DWORD dst_unused:UNUSED_PAD src0_sel:WORD_1
	v_cvt_f32_f16_e32 v72, v77
	v_cvt_f32_f16_sdwa v73, v77 dst_sel:DWORD dst_unused:UNUSED_PAD src0_sel:WORD_1
	v_pk_add_f32 v[0:1], v[0:1], v[66:67] neg_lo:[0,1] neg_hi:[0,1]
	v_pk_add_f32 v[2:3], v[2:3], v[68:69] neg_lo:[0,1] neg_hi:[0,1]
	v_pk_add_f32 v[4:5], v[4:5], v[70:71] neg_lo:[0,1] neg_hi:[0,1]
	v_pk_add_f32 v[6:7], v[6:7], v[72:73] neg_lo:[0,1] neg_hi:[0,1]
	s_nop 0
	v_cvt_pk_f16_f32 v78, v0, v1
	v_cvt_pk_f16_f32 v79, v2, v3
	v_cvt_pk_f16_f32 v80, v4, v5
	v_cvt_pk_f16_f32 v81, v6, v7
	global_store_dwordx4 v[88:89], v[74:77], off offset:704
	s_waitcnt vmcnt(39)
	v_mfma_f32_16x16x32_f16 a[8:11], v[74:77], a[228:231], a[8:11]
	v_mfma_f32_16x16x32_f16 a[8:11], v[78:81], a[228:231], a[8:11]
	v_mfma_f32_16x16x32_f16 a[8:11], v[74:77], a[232:235], a[8:11]
	v_mfma_f32_16x16x32_f16 a[4:7], v[74:77], a[236:239], a[4:7]
	v_mfma_f32_16x16x32_f16 a[4:7], v[78:81], a[236:239], a[4:7]
	v_mfma_f32_16x16x32_f16 a[4:7], v[74:77], a[240:243], a[4:7]
	v_mfma_f32_16x16x32_f16 a[0:3], v[74:77], a[244:247], a[0:3]
	v_mfma_f32_16x16x32_f16 a[0:3], v[78:81], a[244:247], a[0:3]
	v_mfma_f32_16x16x32_f16 a[0:3], v[74:77], a[248:251], a[0:3]
	global_load_dwordx4 a[228:231], v[90:91], off offset:896
	global_load_dwordx4 a[232:235], v[92:93], off offset:896
	global_load_dwordx4 a[236:239], v[94:95], off offset:896
	global_load_dwordx4 a[240:243], v[96:97], off offset:896
	global_load_dwordx4 a[244:247], v[98:99], off offset:896
	global_load_dwordx4 a[248:251], v[100:101], off offset:896
	s_waitcnt vmcnt(37)
	v_accvgpr_read_b32 v0, a48
	v_accvgpr_read_b32 v1, a49
	v_accvgpr_read_b32 v2, a50
	v_accvgpr_read_b32 v3, a51
	v_accvgpr_read_b32 v4, a52
	v_accvgpr_read_b32 v5, a53
	v_accvgpr_read_b32 v6, a54
	v_accvgpr_read_b32 v7, a55
	v_accvgpr_read_b32 v32, a80
	v_accvgpr_read_b32 v33, a81
	v_accvgpr_read_b32 v34, a82
	v_accvgpr_read_b32 v35, a83
	v_accvgpr_read_b32 v36, a84
	v_accvgpr_read_b32 v37, a85
	v_accvgpr_read_b32 v38, a86
	v_accvgpr_read_b32 v39, a87
	v_accvgpr_read_b32 v40, a88
	v_accvgpr_read_b32 v41, a89
	v_accvgpr_read_b32 v42, a90
	v_accvgpr_read_b32 v43, a91
	v_accvgpr_read_b32 v44, a92
	v_accvgpr_read_b32 v45, a93
	v_accvgpr_read_b32 v46, a94
	v_accvgpr_read_b32 v47, a95
	v_accvgpr_read_b32 v58, a96
	v_accvgpr_read_b32 v59, a97
	v_accvgpr_read_b32 v60, a98
	v_accvgpr_read_b32 v61, a99
	v_accvgpr_read_b32 v62, a100
	v_accvgpr_read_b32 v63, a101
	v_accvgpr_read_b32 v64, a102
	v_accvgpr_read_b32 v65, a103
	global_load_dwordx4 a[48:51], v[22:23], off offset:2560
	global_load_dwordx4 a[52:55], v[22:23], off offset:2576
	global_load_dwordx4 a[80:83], v[14:15], off offset:1920
	global_load_dwordx4 a[84:87], v[14:15], off offset:1936
	global_load_dwordx4 a[88:91], v[84:85], off offset:1920
	global_load_dwordx4 a[92:95], v[84:85], off offset:1936
	global_load_dwordx4 a[96:99], v[86:87], off offset:1920
	global_load_dwordx4 a[100:103], v[86:87], off offset:1936
	v_pk_mul_f32 v[0:1], v[28:29], v[0:1]
	v_pk_mul_f32 v[2:3], v[28:29], v[2:3]
	v_pk_mul_f32 v[4:5], v[28:29], v[4:5]
	v_pk_mul_f32 v[6:7], v[28:29], v[6:7]
	v_pk_mul_f32 v[0:1], v[0:1], v[32:33]
	v_pk_mul_f32 v[2:3], v[2:3], v[34:35]
	v_pk_mul_f32 v[4:5], v[4:5], v[36:37]
	v_pk_mul_f32 v[6:7], v[6:7], v[38:39]
	v_pk_add_f32 v[40:41], v[40:41], 1.0 op_sel_hi:[1,0]
	v_pk_add_f32 v[42:43], v[42:43], 1.0 op_sel_hi:[1,0]
	v_pk_add_f32 v[44:45], v[44:45], 1.0 op_sel_hi:[1,0]
	v_pk_add_f32 v[46:47], v[46:47], 1.0 op_sel_hi:[1,0]
	v_pk_fma_f32 v[0:1], v[0:1], v[40:41], v[58:59]
	v_pk_fma_f32 v[2:3], v[2:3], v[42:43], v[60:61]
	v_pk_fma_f32 v[4:5], v[4:5], v[44:45], v[62:63]
	v_pk_fma_f32 v[6:7], v[6:7], v[46:47], v[64:65]
	v_cvt_pk_f16_f32 v74, v0, v1
	v_cvt_pk_f16_f32 v75, v2, v3
	v_cvt_pk_f16_f32 v76, v4, v5
	v_cvt_pk_f16_f32 v77, v6, v7
	v_cvt_f32_f16_e32 v66, v74
	v_cvt_f32_f16_sdwa v67, v74 dst_sel:DWORD dst_unused:UNUSED_PAD src0_sel:WORD_1
	v_cvt_f32_f16_e32 v68, v75
	v_cvt_f32_f16_sdwa v69, v75 dst_sel:DWORD dst_unused:UNUSED_PAD src0_sel:WORD_1
	v_cvt_f32_f16_e32 v70, v76
	v_cvt_f32_f16_sdwa v71, v76 dst_sel:DWORD dst_unused:UNUSED_PAD src0_sel:WORD_1
	v_cvt_f32_f16_e32 v72, v77
	v_cvt_f32_f16_sdwa v73, v77 dst_sel:DWORD dst_unused:UNUSED_PAD src0_sel:WORD_1
	v_pk_add_f32 v[0:1], v[0:1], v[66:67] neg_lo:[0,1] neg_hi:[0,1]
	v_pk_add_f32 v[2:3], v[2:3], v[68:69] neg_lo:[0,1] neg_hi:[0,1]
	v_pk_add_f32 v[4:5], v[4:5], v[70:71] neg_lo:[0,1] neg_hi:[0,1]
	v_pk_add_f32 v[6:7], v[6:7], v[72:73] neg_lo:[0,1] neg_hi:[0,1]
	s_nop 0
	v_cvt_pk_f16_f32 v78, v0, v1
	v_cvt_pk_f16_f32 v79, v2, v3
	v_cvt_pk_f16_f32 v80, v4, v5
	v_cvt_pk_f16_f32 v81, v6, v7
	global_store_dwordx4 v[88:89], v[74:77], off offset:768
	s_waitcnt vmcnt(39)
; DI f4 mfma16(h8 a, h8 b, f4 c) { return __builtin_amdgcn_mfma_f32_16x16x32_f16(a, b, c, 0, 0, 0); }
; DI void row2_phase(const Params& P, int l, int r_begin, char* smem) {
;     ...
;     for (int kk = 0; kk < 32; kk++) {
;       const int k0 = kk * 32;
;       float x[8], g[8], s1[8], s0[8];
;       *(float4*)&x[0] = *(const float4*)(xm + k0); *(float4*)&x[4] = *(const float4*)(xm + k0 + 4);
;       *(float4*)&g[0] = *(const float4*)(gam + fq * 8 + k0); *(float4*)&g[4] = *(const float4*)(gam + fq * 8 + k0 + 4);
;       *(float4*)&s1[0] = *(const float4*)(sc + k0); *(float4*)&s1[4] = *(const float4*)(sc + k0 + 4);
;       *(float4*)&s0[0] = *(const float4*)(sh + k0); *(float4*)&s0[4] = *(const float4*)(sh + k0 + 4);
;       h8 hi, lo;
; #pragma unroll
;       for (int i = 0; i < 8; i++) {
;         float v = x[i] * rstd * g[i] * (1.f + s1[i]) + s0[i];
;         hi[i] = (half_t)v; lo[i] = (half_t)(v - (float)hi[i]);
;       }
;       *(h8*)(hxo + k0) = hi;
; #pragma unroll
;       for (int n3 = 0; n3 < 3; n3++) {
;         h8 bh = *(const h8*)(Whi + (size_t)(n3 * 16 + fr) * 1024 + k0 + fq * 8);
;         h8 bl = *(const h8*)(Wlo + (size_t)(n3 * 16 + fr) * 1024 + k0 + fq * 8);
;         acc[n3] = mfma16(hi, bh, acc[n3]); acc[n3] = mfma16(lo, bh, acc[n3]); acc[n3] = mfma16(hi, bl, acc[n3]);
;       }
	v_mfma_f32_16x16x32_f16 a[8:11], v[74:77], a[104:107], a[8:11]
	v_mfma_f32_16x16x32_f16 a[8:11], v[78:81], a[104:107], a[8:11]
	v_mfma_f32_16x16x32_f16 a[8:11], v[74:77], a[108:111], a[8:11]
	v_mfma_f32_16x16x32_f16 a[4:7], v[74:77], a[112:115], a[4:7]
	v_mfma_f32_16x16x32_f16 a[4:7], v[78:81], a[112:115], a[4:7]
	v_mfma_f32_16x16x32_f16 a[4:7], v[74:77], a[116:119], a[4:7]
	v_mfma_f32_16x16x32_f16 a[0:3], v[74:77], a[120:123], a[0:3]
	v_mfma_f32_16x16x32_f16 a[0:3], v[78:81], a[120:123], a[0:3]
	v_mfma_f32_16x16x32_f16 a[0:3], v[74:77], a[124:127], a[0:3]
	global_load_dwordx4 a[104:107], v[90:91], off offset:960
	global_load_dwordx4 a[108:111], v[92:93], off offset:960
	global_load_dwordx4 a[112:115], v[94:95], off offset:960
	global_load_dwordx4 a[116:119], v[96:97], off offset:960
	global_load_dwordx4 a[120:123], v[98:99], off offset:960
	global_load_dwordx4 a[124:127], v[100:101], off offset:960
	s_waitcnt vmcnt(37)
	v_accvgpr_read_b32 v0, a56
	v_accvgpr_read_b32 v1, a57
	v_accvgpr_read_b32 v2, a58
	v_accvgpr_read_b32 v3, a59
	v_accvgpr_read_b32 v4, a60
	v_accvgpr_read_b32 v5, a61
	v_accvgpr_read_b32 v6, a62
	v_accvgpr_read_b32 v7, a63
	v_accvgpr_read_b32 v32, a128
	v_accvgpr_read_b32 v33, a129
	v_accvgpr_read_b32 v34, a130
	v_accvgpr_read_b32 v35, a131
	v_accvgpr_read_b32 v36, a132
	v_accvgpr_read_b32 v37, a133
	v_accvgpr_read_b32 v38, a134
	v_accvgpr_read_b32 v39, a135
	v_accvgpr_read_b32 v40, a136
	v_accvgpr_read_b32 v41, a137
	v_accvgpr_read_b32 v42, a138
	v_accvgpr_read_b32 v43, a139
	v_accvgpr_read_b32 v44, a140
	v_accvgpr_read_b32 v45, a141
	v_accvgpr_read_b32 v46, a142
	v_accvgpr_read_b32 v47, a143
	v_accvgpr_read_b32 v58, a144
	v_accvgpr_read_b32 v59, a145
	v_accvgpr_read_b32 v60, a146
	v_accvgpr_read_b32 v61, a147
	v_accvgpr_read_b32 v62, a148
	v_accvgpr_read_b32 v63, a149
	v_accvgpr_read_b32 v64, a150
	v_accvgpr_read_b32 v65, a151
	global_load_dwordx4 a[56:59], v[22:23], off offset:2688
	global_load_dwordx4 a[60:63], v[22:23], off offset:2704
	global_load_dwordx4 a[128:131], v[14:15], off offset:2048
	global_load_dwordx4 a[132:135], v[14:15], off offset:2064
	global_load_dwordx4 a[136:139], v[84:85], off offset:2048
	global_load_dwordx4 a[140:143], v[84:85], off offset:2064
	global_load_dwordx4 a[144:147], v[86:87], off offset:2048
	global_load_dwordx4 a[148:151], v[86:87], off offset:2064
	v_pk_mul_f32 v[0:1], v[28:29], v[0:1]
	v_pk_mul_f32 v[2:3], v[28:29], v[2:3]
	v_pk_mul_f32 v[4:5], v[28:29], v[4:5]
	v_pk_mul_f32 v[6:7], v[28:29], v[6:7]
	v_pk_mul_f32 v[0:1], v[0:1], v[32:33]
	v_pk_mul_f32 v[2:3], v[2:3], v[34:35]
	v_pk_mul_f32 v[4:5], v[4:5], v[36:37]
	v_pk_mul_f32 v[6:7], v[6:7], v[38:39]
	v_pk_add_f32 v[40:41], v[40:41], 1.0 op_sel_hi:[1,0]
	v_pk_add_f32 v[42:43], v[42:43], 1.0 op_sel_hi:[1,0]
	v_pk_add_f32 v[44:45], v[44:45], 1.0 op_sel_hi:[1,0]
	v_pk_add_f32 v[46:47], v[46:47], 1.0 op_sel_hi:[1,0]
	v_pk_fma_f32 v[0:1], v[0:1], v[40:41], v[58:59]
	v_pk_fma_f32 v[2:3], v[2:3], v[42:43], v[60:61]
	v_pk_fma_f32 v[4:5], v[4:5], v[44:45], v[62:63]
	v_pk_fma_f32 v[6:7], v[6:7], v[46:47], v[64:65]
	v_cvt_pk_f16_f32 v74, v0, v1
	v_cvt_pk_f16_f32 v75, v2, v3
	v_cvt_pk_f16_f32 v76, v4, v5
	v_cvt_pk_f16_f32 v77, v6, v7
	v_cvt_f32_f16_e32 v66, v74
	v_cvt_f32_f16_sdwa v67, v74 dst_sel:DWORD dst_unused:UNUSED_PAD src0_sel:WORD_1
	v_cvt_f32_f16_e32 v68, v75
	v_cvt_f32_f16_sdwa v69, v75 dst_sel:DWORD dst_unused:UNUSED_PAD src0_sel:WORD_1
	v_cvt_f32_f16_e32 v70, v76
	v_cvt_f32_f16_sdwa v71, v76 dst_sel:DWORD dst_unused:UNUSED_PAD src0_sel:WORD_1
	v_cvt_f32_f16_e32 v72, v77
	v_cvt_f32_f16_sdwa v73, v77 dst_sel:DWORD dst_unused:UNUSED_PAD src0_sel:WORD_1
	v_pk_add_f32 v[0:1], v[0:1], v[66:67] neg_lo:[0,1] neg_hi:[0,1]
	v_pk_add_f32 v[2:3], v[2:3], v[68:69] neg_lo:[0,1] neg_hi:[0,1]
	v_pk_add_f32 v[4:5], v[4:5], v[70:71] neg_lo:[0,1] neg_hi:[0,1]
	v_pk_add_f32 v[6:7], v[6:7], v[72:73] neg_lo:[0,1] neg_hi:[0,1]
	s_nop 0
	v_cvt_pk_f16_f32 v78, v0, v1
	v_cvt_pk_f16_f32 v79, v2, v3
	v_cvt_pk_f16_f32 v80, v4, v5
	v_cvt_pk_f16_f32 v81, v6, v7
	global_store_dwordx4 v[88:89], v[74:77], off offset:832
	s_waitcnt vmcnt(39)
	v_mfma_f32_16x16x32_f16 a[8:11], v[74:77], a[152:155], a[8:11]
	v_mfma_f32_16x16x32_f16 a[8:11], v[78:81], a[152:155], a[8:11]
	v_mfma_f32_16x16x32_f16 a[8:11], v[74:77], a[156:159], a[8:11]
	v_mfma_f32_16x16x32_f16 a[4:7], v[74:77], a[160:163], a[4:7]
	v_mfma_f32_16x16x32_f16 a[4:7], v[78:81], a[160:163], a[4:7]
	v_mfma_f32_16x16x32_f16 a[4:7], v[74:77], a[164:167], a[4:7]
	v_mfma_f32_16x16x32_f16 a[0:3], v[74:77], a[168:171], a[0:3]
	v_mfma_f32_16x16x32_f16 a[0:3], v[78:81], a[168:171], a[0:3]
	v_mfma_f32_16x16x32_f16 a[0:3], v[74:77], a[172:175], a[0:3]
	global_load_dwordx4 a[152:155], v[90:91], off offset:1024
	global_load_dwordx4 a[156:159], v[92:93], off offset:1024
	global_load_dwordx4 a[160:163], v[94:95], off offset:1024
	global_load_dwordx4 a[164:167], v[96:97], off offset:1024
	global_load_dwordx4 a[168:171], v[98:99], off offset:1024
	global_load_dwordx4 a[172:175], v[100:101], off offset:1024
	s_waitcnt vmcnt(37)
; DI f4 mfma16(h8 a, h8 b, f4 c) { return __builtin_amdgcn_mfma_f32_16x16x32_f16(a, b, c, 0, 0, 0); }
; DI void row2_phase(const Params& P, int l, int r_begin, char* smem) {
;     ...
;     for (int kk = 0; kk < 32; kk++) {
;       const int k0 = kk * 32;
;       float x[8], g[8], s1[8], s0[8];
;       *(float4*)&x[0] = *(const float4*)(xm + k0); *(float4*)&x[4] = *(const float4*)(xm + k0 + 4);
;       *(float4*)&g[0] = *(const float4*)(gam + fq * 8 + k0); *(float4*)&g[4] = *(const float4*)(gam + fq * 8 + k0 + 4);
;       *(float4*)&s1[0] = *(const float4*)(sc + k0); *(float4*)&s1[4] = *(const float4*)(sc + k0 + 4);
;       *(float4*)&s0[0] = *(const float4*)(sh + k0); *(float4*)&s0[4] = *(const float4*)(sh + k0 + 4);
;       h8 hi, lo;
; #pragma unroll
;       for (int i = 0; i < 8; i++) {
;         float v = x[i] * rstd * g[i] * (1.f + s1[i]) + s0[i];
;         hi[i] = (half_t)v; lo[i] = (half_t)(v - (float)hi[i]);
;       }
;       *(h8*)(hxo + k0) = hi;
; #pragma unroll
;       for (int n3 = 0; n3 < 3; n3++) {
;         h8 bh = *(const h8*)(Whi + (size_t)(n3 * 16 + fr) * 1024 + k0 + fq * 8);
;         h8 bl = *(const h8*)(Wlo + (size_t)(n3 * 16 + fr) * 1024 + k0 + fq * 8);
;         acc[n3] = mfma16(hi, bh, acc[n3]); acc[n3] = mfma16(lo, bh, acc[n3]); acc[n3] = mfma16(hi, bl, acc[n3]);
;       }
	v_accvgpr_read_b32 v0, a64
	v_accvgpr_read_b32 v1, a65
	v_accvgpr_read_b32 v2, a66
	v_accvgpr_read_b32 v3, a67
	v_accvgpr_read_b32 v4, a68
	v_accvgpr_read_b32 v5, a69
	v_accvgpr_read_b32 v6, a70
	v_accvgpr_read_b32 v7, a71
	v_accvgpr_read_b32 v32, a204
	v_accvgpr_read_b32 v33, a205
	v_accvgpr_read_b32 v34, a206
	v_accvgpr_read_b32 v35, a207
	v_accvgpr_read_b32 v36, a208
	v_accvgpr_read_b32 v37, a209
	v_accvgpr_read_b32 v38, a210
	v_accvgpr_read_b32 v39, a211
	v_accvgpr_read_b32 v40, a212
	v_accvgpr_read_b32 v41, a213
	v_accvgpr_read_b32 v42, a214
	v_accvgpr_read_b32 v43, a215
	v_accvgpr_read_b32 v44, a216
	v_accvgpr_read_b32 v45, a217
	v_accvgpr_read_b32 v46, a218
	v_accvgpr_read_b32 v47, a219
	v_accvgpr_read_b32 v58, a220
	v_accvgpr_read_b32 v59, a221
	v_accvgpr_read_b32 v60, a222
	v_accvgpr_read_b32 v61, a223
	v_accvgpr_read_b32 v62, a224
	v_accvgpr_read_b32 v63, a225
	v_accvgpr_read_b32 v64, a226
	v_accvgpr_read_b32 v65, a227
	global_load_dwordx4 a[64:67], v[22:23], off offset:2816
	global_load_dwordx4 a[68:71], v[22:23], off offset:2832
	global_load_dwordx4 a[204:207], v[14:15], off offset:2176
	global_load_dwordx4 a[208:211], v[14:15], off offset:2192
	global_load_dwordx4 a[212:215], v[84:85], off offset:2176
	global_load_dwordx4 a[216:219], v[84:85], off offset:2192
	global_load_dwordx4 a[220:223], v[86:87], off offset:2176
	global_load_dwordx4 a[224:227], v[86:87], off offset:2192
	v_pk_mul_f32 v[0:1], v[28:29], v[0:1]
	v_pk_mul_f32 v[2:3], v[28:29], v[2:3]
	v_pk_mul_f32 v[4:5], v[28:29], v[4:5]
	v_pk_mul_f32 v[6:7], v[28:29], v[6:7]
	v_pk_mul_f32 v[0:1], v[0:1], v[32:33]
	v_pk_mul_f32 v[2:3], v[2:3], v[34:35]
	v_pk_mul_f32 v[4:5], v[4:5], v[36:37]
	v_pk_mul_f32 v[6:7], v[6:7], v[38:39]
	v_pk_add_f32 v[40:41], v[40:41], 1.0 op_sel_hi:[1,0]
	v_pk_add_f32 v[42:43], v[42:43], 1.0 op_sel_hi:[1,0]
	v_pk_add_f32 v[44:45], v[44:45], 1.0 op_sel_hi:[1,0]
	v_pk_add_f32 v[46:47], v[46:47], 1.0 op_sel_hi:[1,0]
	v_pk_fma_f32 v[0:1], v[0:1], v[40:41], v[58:59]
	v_pk_fma_f32 v[2:3], v[2:3], v[42:43], v[60:61]
	v_pk_fma_f32 v[4:5], v[4:5], v[44:45], v[62:63]
	v_pk_fma_f32 v[6:7], v[6:7], v[46:47], v[64:65]
	v_cvt_pk_f16_f32 v74, v0, v1
	v_cvt_pk_f16_f32 v75, v2, v3
	v_cvt_pk_f16_f32 v76, v4, v5
	v_cvt_pk_f16_f32 v77, v6, v7
	v_cvt_f32_f16_e32 v66, v74
	v_cvt_f32_f16_sdwa v67, v74 dst_sel:DWORD dst_unused:UNUSED_PAD src0_sel:WORD_1
	v_cvt_f32_f16_e32 v68, v75
	v_cvt_f32_f16_sdwa v69, v75 dst_sel:DWORD dst_unused:UNUSED_PAD src0_sel:WORD_1
	v_cvt_f32_f16_e32 v70, v76
	v_cvt_f32_f16_sdwa v71, v76 dst_sel:DWORD dst_unused:UNUSED_PAD src0_sel:WORD_1
	v_cvt_f32_f16_e32 v72, v77
	v_cvt_f32_f16_sdwa v73, v77 dst_sel:DWORD dst_unused:UNUSED_PAD src0_sel:WORD_1
	v_pk_add_f32 v[0:1], v[0:1], v[66:67] neg_lo:[0,1] neg_hi:[0,1]
	v_pk_add_f32 v[2:3], v[2:3], v[68:69] neg_lo:[0,1] neg_hi:[0,1]
	v_pk_add_f32 v[4:5], v[4:5], v[70:71] neg_lo:[0,1] neg_hi:[0,1]
	v_pk_add_f32 v[6:7], v[6:7], v[72:73] neg_lo:[0,1] neg_hi:[0,1]
	s_nop 0
	v_cvt_pk_f16_f32 v78, v0, v1
	v_cvt_pk_f16_f32 v79, v2, v3
	v_cvt_pk_f16_f32 v80, v4, v5
	v_cvt_pk_f16_f32 v81, v6, v7
	global_store_dwordx4 v[88:89], v[74:77], off offset:896
	s_waitcnt vmcnt(39)
	v_mfma_f32_16x16x32_f16 a[8:11], v[74:77], a[228:231], a[8:11]
	v_mfma_f32_16x16x32_f16 a[8:11], v[78:81], a[228:231], a[8:11]
	v_mfma_f32_16x16x32_f16 a[8:11], v[74:77], a[232:235], a[8:11]
	v_mfma_f32_16x16x32_f16 a[4:7], v[74:77], a[236:239], a[4:7]
	v_mfma_f32_16x16x32_f16 a[4:7], v[78:81], a[236:239], a[4:7]
	v_mfma_f32_16x16x32_f16 a[4:7], v[74:77], a[240:243], a[4:7]
	v_mfma_f32_16x16x32_f16 a[0:3], v[74:77], a[244:247], a[0:3]
	v_mfma_f32_16x16x32_f16 a[0:3], v[78:81], a[244:247], a[0:3]
	v_mfma_f32_16x16x32_f16 a[0:3], v[74:77], a[248:251], a[0:3]
	global_load_dwordx4 a[228:231], v[90:91], off offset:1088
	global_load_dwordx4 a[232:235], v[92:93], off offset:1088
	global_load_dwordx4 a[236:239], v[94:95], off offset:1088
	global_load_dwordx4 a[240:243], v[96:97], off offset:1088
	global_load_dwordx4 a[244:247], v[98:99], off offset:1088
	global_load_dwordx4 a[248:251], v[100:101], off offset:1088
	s_waitcnt vmcnt(37)
	v_accvgpr_read_b32 v0, a72
	v_accvgpr_read_b32 v1, a73
	v_accvgpr_read_b32 v2, a74
	v_accvgpr_read_b32 v3, a75
	v_accvgpr_read_b32 v4, a76
	v_accvgpr_read_b32 v5, a77
	v_accvgpr_read_b32 v6, a78
	v_accvgpr_read_b32 v7, a79
	v_accvgpr_read_b32 v32, a80
	v_accvgpr_read_b32 v33, a81
	v_accvgpr_read_b32 v34, a82
	v_accvgpr_read_b32 v35, a83
	v_accvgpr_read_b32 v36, a84
	v_accvgpr_read_b32 v37, a85
	v_accvgpr_read_b32 v38, a86
	v_accvgpr_read_b32 v39, a87
	v_accvgpr_read_b32 v40, a88
	v_accvgpr_read_b32 v41, a89
	v_accvgpr_read_b32 v42, a90
	v_accvgpr_read_b32 v43, a91
	v_accvgpr_read_b32 v44, a92
	v_accvgpr_read_b32 v45, a93
	v_accvgpr_read_b32 v46, a94
	v_accvgpr_read_b32 v47, a95
	v_accvgpr_read_b32 v58, a96
	v_accvgpr_read_b32 v59, a97
	v_accvgpr_read_b32 v60, a98
	v_accvgpr_read_b32 v61, a99
	v_accvgpr_read_b32 v62, a100
	v_accvgpr_read_b32 v63, a101
	v_accvgpr_read_b32 v64, a102
	v_accvgpr_read_b32 v65, a103
	global_load_dwordx4 a[72:75], v[22:23], off offset:2944
	global_load_dwordx4 a[76:79], v[22:23], off offset:2960
	global_load_dwordx4 a[80:83], v[14:15], off offset:2304
	global_load_dwordx4 a[84:87], v[14:15], off offset:2320
	global_load_dwordx4 a[88:91], v[84:85], off offset:2304
	global_load_dwordx4 a[92:95], v[84:85], off offset:2320
	global_load_dwordx4 a[96:99], v[86:87], off offset:2304
	global_load_dwordx4 a[100:103], v[86:87], off offset:2320
	v_pk_mul_f32 v[0:1], v[28:29], v[0:1]
	v_pk_mul_f32 v[2:3], v[28:29], v[2:3]
	v_pk_mul_f32 v[4:5], v[28:29], v[4:5]
	v_pk_mul_f32 v[6:7], v[28:29], v[6:7]
; DI f4 mfma16(h8 a, h8 b, f4 c) { return __builtin_amdgcn_mfma_f32_16x16x32_f16(a, b, c, 0, 0, 0); }
; DI void row2_phase(const Params& P, int l, int r_begin, char* smem) {
;     ...
;     for (int kk = 0; kk < 32; kk++) {
;       const int k0 = kk * 32;
;       float x[8], g[8], s1[8], s0[8];
;       *(float4*)&x[0] = *(const float4*)(xm + k0); *(float4*)&x[4] = *(const float4*)(xm + k0 + 4);
;       *(float4*)&g[0] = *(const float4*)(gam + fq * 8 + k0); *(float4*)&g[4] = *(const float4*)(gam + fq * 8 + k0 + 4);
;       *(float4*)&s1[0] = *(const float4*)(sc + k0); *(float4*)&s1[4] = *(const float4*)(sc + k0 + 4);
;       *(float4*)&s0[0] = *(const float4*)(sh + k0); *(float4*)&s0[4] = *(const float4*)(sh + k0 + 4);
;       h8 hi, lo;
; #pragma unroll
;       for (int i = 0; i < 8; i++) {
;         float v = x[i] * rstd * g[i] * (1.f + s1[i]) + s0[i];
;         hi[i] = (half_t)v; lo[i] = (half_t)(v - (float)hi[i]);
;       }
;       *(h8*)(hxo + k0) = hi;
; #pragma unroll
;       for (int n3 = 0; n3 < 3; n3++) {
;         h8 bh = *(const h8*)(Whi + (size_t)(n3 * 16 + fr) * 1024 + k0 + fq * 8);
;         h8 bl = *(const h8*)(Wlo + (size_t)(n3 * 16 + fr) * 1024 + k0 + fq * 8);
;         acc[n3] = mfma16(hi, bh, acc[n3]); acc[n3] = mfma16(lo, bh, acc[n3]); acc[n3] = mfma16(hi, bl, acc[n3]);
;       }
	v_pk_mul_f32 v[0:1], v[0:1], v[32:33]
	v_pk_mul_f32 v[2:3], v[2:3], v[34:35]
	v_pk_mul_f32 v[4:5], v[4:5], v[36:37]
	v_pk_mul_f32 v[6:7], v[6:7], v[38:39]
	v_pk_add_f32 v[40:41], v[40:41], 1.0 op_sel_hi:[1,0]
	v_pk_add_f32 v[42:43], v[42:43], 1.0 op_sel_hi:[1,0]
	v_pk_add_f32 v[44:45], v[44:45], 1.0 op_sel_hi:[1,0]
	v_pk_add_f32 v[46:47], v[46:47], 1.0 op_sel_hi:[1,0]
	v_pk_fma_f32 v[0:1], v[0:1], v[40:41], v[58:59]
	v_pk_fma_f32 v[2:3], v[2:3], v[42:43], v[60:61]
	v_pk_fma_f32 v[4:5], v[4:5], v[44:45], v[62:63]
	v_pk_fma_f32 v[6:7], v[6:7], v[46:47], v[64:65]
	v_cvt_pk_f16_f32 v74, v0, v1
	v_cvt_pk_f16_f32 v75, v2, v3
	v_cvt_pk_f16_f32 v76, v4, v5
	v_cvt_pk_f16_f32 v77, v6, v7
	v_cvt_f32_f16_e32 v66, v74
	v_cvt_f32_f16_sdwa v67, v74 dst_sel:DWORD dst_unused:UNUSED_PAD src0_sel:WORD_1
	v_cvt_f32_f16_e32 v68, v75
	v_cvt_f32_f16_sdwa v69, v75 dst_sel:DWORD dst_unused:UNUSED_PAD src0_sel:WORD_1
	v_cvt_f32_f16_e32 v70, v76
	v_cvt_f32_f16_sdwa v71, v76 dst_sel:DWORD dst_unused:UNUSED_PAD src0_sel:WORD_1
	v_cvt_f32_f16_e32 v72, v77
	v_cvt_f32_f16_sdwa v73, v77 dst_sel:DWORD dst_unused:UNUSED_PAD src0_sel:WORD_1
	v_pk_add_f32 v[0:1], v[0:1], v[66:67] neg_lo:[0,1] neg_hi:[0,1]
	v_pk_add_f32 v[2:3], v[2:3], v[68:69] neg_lo:[0,1] neg_hi:[0,1]
	v_pk_add_f32 v[4:5], v[4:5], v[70:71] neg_lo:[0,1] neg_hi:[0,1]
	v_pk_add_f32 v[6:7], v[6:7], v[72:73] neg_lo:[0,1] neg_hi:[0,1]
	s_nop 0
	v_cvt_pk_f16_f32 v78, v0, v1
	v_cvt_pk_f16_f32 v79, v2, v3
	v_cvt_pk_f16_f32 v80, v4, v5
	v_cvt_pk_f16_f32 v81, v6, v7
	global_store_dwordx4 v[88:89], v[74:77], off offset:960
	s_waitcnt vmcnt(39)
	v_mfma_f32_16x16x32_f16 a[8:11], v[74:77], a[104:107], a[8:11]
	v_mfma_f32_16x16x32_f16 a[8:11], v[78:81], a[104:107], a[8:11]
	v_mfma_f32_16x16x32_f16 a[8:11], v[74:77], a[108:111], a[8:11]
	v_mfma_f32_16x16x32_f16 a[4:7], v[74:77], a[112:115], a[4:7]
	v_mfma_f32_16x16x32_f16 a[4:7], v[78:81], a[112:115], a[4:7]
	v_mfma_f32_16x16x32_f16 a[4:7], v[74:77], a[116:119], a[4:7]
	v_mfma_f32_16x16x32_f16 a[0:3], v[74:77], a[120:123], a[0:3]
	v_mfma_f32_16x16x32_f16 a[0:3], v[78:81], a[120:123], a[0:3]
	v_mfma_f32_16x16x32_f16 a[0:3], v[74:77], a[124:127], a[0:3]
	global_load_dwordx4 a[104:107], v[90:91], off offset:1152
	global_load_dwordx4 a[108:111], v[92:93], off offset:1152
	global_load_dwordx4 a[112:115], v[94:95], off offset:1152
	global_load_dwordx4 a[116:119], v[96:97], off offset:1152
	global_load_dwordx4 a[120:123], v[98:99], off offset:1152
	global_load_dwordx4 a[124:127], v[100:101], off offset:1152
	s_waitcnt vmcnt(37)
	v_accvgpr_read_b32 v0, a16
	v_accvgpr_read_b32 v1, a17
	v_accvgpr_read_b32 v2, a18
	v_accvgpr_read_b32 v3, a19
	v_accvgpr_read_b32 v4, a20
	v_accvgpr_read_b32 v5, a21
	v_accvgpr_read_b32 v6, a22
	v_accvgpr_read_b32 v7, a23
	v_accvgpr_read_b32 v32, a128
	v_accvgpr_read_b32 v33, a129
	v_accvgpr_read_b32 v34, a130
	v_accvgpr_read_b32 v35, a131
	v_accvgpr_read_b32 v36, a132
	v_accvgpr_read_b32 v37, a133
	v_accvgpr_read_b32 v38, a134
	v_accvgpr_read_b32 v39, a135
	v_accvgpr_read_b32 v40, a136
	v_accvgpr_read_b32 v41, a137
	v_accvgpr_read_b32 v42, a138
	v_accvgpr_read_b32 v43, a139
	v_accvgpr_read_b32 v44, a140
	v_accvgpr_read_b32 v45, a141
	v_accvgpr_read_b32 v46, a142
	v_accvgpr_read_b32 v47, a143
	v_accvgpr_read_b32 v58, a144
	v_accvgpr_read_b32 v59, a145
	v_accvgpr_read_b32 v60, a146
	v_accvgpr_read_b32 v61, a147
	v_accvgpr_read_b32 v62, a148
	v_accvgpr_read_b32 v63, a149
	v_accvgpr_read_b32 v64, a150
	v_accvgpr_read_b32 v65, a151
	global_load_dwordx4 a[16:19], v[22:23], off offset:3072
	global_load_dwordx4 a[20:23], v[22:23], off offset:3088
	global_load_dwordx4 a[128:131], v[14:15], off offset:2432
	global_load_dwordx4 a[132:135], v[14:15], off offset:2448
	global_load_dwordx4 a[136:139], v[84:85], off offset:2432
	global_load_dwordx4 a[140:143], v[84:85], off offset:2448
	global_load_dwordx4 a[144:147], v[86:87], off offset:2432
	global_load_dwordx4 a[148:151], v[86:87], off offset:2448
	v_pk_mul_f32 v[0:1], v[28:29], v[0:1]
	v_pk_mul_f32 v[2:3], v[28:29], v[2:3]
	v_pk_mul_f32 v[4:5], v[28:29], v[4:5]
	v_pk_mul_f32 v[6:7], v[28:29], v[6:7]
	v_pk_mul_f32 v[0:1], v[0:1], v[32:33]
	v_pk_mul_f32 v[2:3], v[2:3], v[34:35]
	v_pk_mul_f32 v[4:5], v[4:5], v[36:37]
	v_pk_mul_f32 v[6:7], v[6:7], v[38:39]
	v_pk_add_f32 v[40:41], v[40:41], 1.0 op_sel_hi:[1,0]
	v_pk_add_f32 v[42:43], v[42:43], 1.0 op_sel_hi:[1,0]
	v_pk_add_f32 v[44:45], v[44:45], 1.0 op_sel_hi:[1,0]
	v_pk_add_f32 v[46:47], v[46:47], 1.0 op_sel_hi:[1,0]
	v_pk_fma_f32 v[0:1], v[0:1], v[40:41], v[58:59]
	v_pk_fma_f32 v[2:3], v[2:3], v[42:43], v[60:61]
	v_pk_fma_f32 v[4:5], v[4:5], v[44:45], v[62:63]
	v_pk_fma_f32 v[6:7], v[6:7], v[46:47], v[64:65]
	v_cvt_pk_f16_f32 v74, v0, v1
	v_cvt_pk_f16_f32 v75, v2, v3
	v_cvt_pk_f16_f32 v76, v4, v5
	v_cvt_pk_f16_f32 v77, v6, v7
	v_cvt_f32_f16_e32 v66, v74
	v_cvt_f32_f16_sdwa v67, v74 dst_sel:DWORD dst_unused:UNUSED_PAD src0_sel:WORD_1
	v_cvt_f32_f16_e32 v68, v75
	v_cvt_f32_f16_sdwa v69, v75 dst_sel:DWORD dst_unused:UNUSED_PAD src0_sel:WORD_1
	v_cvt_f32_f16_e32 v70, v76
	v_cvt_f32_f16_sdwa v71, v76 dst_sel:DWORD dst_unused:UNUSED_PAD src0_sel:WORD_1
	v_cvt_f32_f16_e32 v72, v77
	v_cvt_f32_f16_sdwa v73, v77 dst_sel:DWORD dst_unused:UNUSED_PAD src0_sel:WORD_1
	v_pk_add_f32 v[0:1], v[0:1], v[66:67] neg_lo:[0,1] neg_hi:[0,1]
	v_pk_add_f32 v[2:3], v[2:3], v[68:69] neg_lo:[0,1] neg_hi:[0,1]
	v_pk_add_f32 v[4:5], v[4:5], v[70:71] neg_lo:[0,1] neg_hi:[0,1]
	v_pk_add_f32 v[6:7], v[6:7], v[72:73] neg_lo:[0,1] neg_hi:[0,1]
	s_nop 0
	v_cvt_pk_f16_f32 v78, v0, v1
	v_cvt_pk_f16_f32 v79, v2, v3
	v_cvt_pk_f16_f32 v80, v4, v5
	v_cvt_pk_f16_f32 v81, v6, v7
	global_store_dwordx4 v[88:89], v[74:77], off offset:1024
	s_waitcnt vmcnt(39)
; DI f4 mfma16(h8 a, h8 b, f4 c) { return __builtin_amdgcn_mfma_f32_16x16x32_f16(a, b, c, 0, 0, 0); }
; DI void row2_phase(const Params& P, int l, int r_begin, char* smem) {
;     ...
; #pragma unroll 4
;     for (int kk = 0; kk < 32; kk++) {
;       const int k0 = kk * 32;
;       float x[8], g[8], s1[8], s0[8];
;       *(float4*)&x[0] = *(const float4*)(xm + k0); *(float4*)&x[4] = *(const float4*)(xm + k0 + 4);
;       *(float4*)&g[0] = *(const float4*)(gam + fq * 8 + k0); *(float4*)&g[4] = *(const float4*)(gam + fq * 8 + k0 + 4);
;       *(float4*)&s1[0] = *(const float4*)(sc + k0); *(float4*)&s1[4] = *(const float4*)(sc + k0 + 4);
;       *(float4*)&s0[0] = *(const float4*)(sh + k0); *(float4*)&s0[4] = *(const float4*)(sh + k0 + 4);
;       h8 hi, lo;
; #pragma unroll
;       for (int i = 0; i < 8; i++) {
;         float v = x[i] * rstd * g[i] * (1.f + s1[i]) + s0[i];
;         hi[i] = (half_t)v; lo[i] = (half_t)(v - (float)hi[i]);
;       }
;       *(h8*)(hxo + k0) = hi;
; #pragma unroll
;       for (int n3 = 0; n3 < 3; n3++) {
;         h8 bh = *(const h8*)(Whi + (size_t)(n3 * 16 + fr) * 1024 + k0 + fq * 8);
;         h8 bl = *(const h8*)(Wlo + (size_t)(n3 * 16 + fr) * 1024 + k0 + fq * 8);
;         acc[n3] = mfma16(hi, bh, acc[n3]); acc[n3] = mfma16(lo, bh, acc[n3]); acc[n3] = mfma16(hi, bl, acc[n3]);
;       }
;     }
	v_mfma_f32_16x16x32_f16 a[8:11], v[74:77], a[152:155], a[8:11]
	v_mfma_f32_16x16x32_f16 a[8:11], v[78:81], a[152:155], a[8:11]
	v_mfma_f32_16x16x32_f16 a[8:11], v[74:77], a[156:159], a[8:11]
	v_mfma_f32_16x16x32_f16 a[4:7], v[74:77], a[160:163], a[4:7]
	v_mfma_f32_16x16x32_f16 a[4:7], v[78:81], a[160:163], a[4:7]
	v_mfma_f32_16x16x32_f16 a[4:7], v[74:77], a[164:167], a[4:7]
	v_mfma_f32_16x16x32_f16 a[0:3], v[74:77], a[168:171], a[0:3]
	v_mfma_f32_16x16x32_f16 a[0:3], v[78:81], a[168:171], a[0:3]
	v_mfma_f32_16x16x32_f16 a[0:3], v[74:77], a[172:175], a[0:3]
	global_load_dwordx4 a[152:155], v[90:91], off offset:1216
	global_load_dwordx4 a[156:159], v[92:93], off offset:1216
	global_load_dwordx4 a[160:163], v[94:95], off offset:1216
	global_load_dwordx4 a[164:167], v[96:97], off offset:1216
	global_load_dwordx4 a[168:171], v[98:99], off offset:1216
	global_load_dwordx4 a[172:175], v[100:101], off offset:1216
	s_waitcnt vmcnt(37)
	v_accvgpr_read_b32 v0, a24
	v_accvgpr_read_b32 v1, a25
	v_accvgpr_read_b32 v2, a26
	v_accvgpr_read_b32 v3, a27
	v_accvgpr_read_b32 v4, a28
	v_accvgpr_read_b32 v5, a29
	v_accvgpr_read_b32 v6, a30
	v_accvgpr_read_b32 v7, a31
	v_accvgpr_read_b32 v32, a204
	v_accvgpr_read_b32 v33, a205
	v_accvgpr_read_b32 v34, a206
	v_accvgpr_read_b32 v35, a207
	v_accvgpr_read_b32 v36, a208
	v_accvgpr_read_b32 v37, a209
	v_accvgpr_read_b32 v38, a210
	v_accvgpr_read_b32 v39, a211
	v_accvgpr_read_b32 v40, a212
	v_accvgpr_read_b32 v41, a213
	v_accvgpr_read_b32 v42, a214
	v_accvgpr_read_b32 v43, a215
	v_accvgpr_read_b32 v44, a216
	v_accvgpr_read_b32 v45, a217
	v_accvgpr_read_b32 v46, a218
	v_accvgpr_read_b32 v47, a219
	v_accvgpr_read_b32 v58, a220
	v_accvgpr_read_b32 v59, a221
	v_accvgpr_read_b32 v60, a222
	v_accvgpr_read_b32 v61, a223
	v_accvgpr_read_b32 v62, a224
	v_accvgpr_read_b32 v63, a225
	v_accvgpr_read_b32 v64, a226
	v_accvgpr_read_b32 v65, a227
	global_load_dwordx4 a[24:27], v[22:23], off offset:3200
	global_load_dwordx4 a[28:31], v[22:23], off offset:3216
	global_load_dwordx4 a[204:207], v[14:15], off offset:2560
	global_load_dwordx4 a[208:211], v[14:15], off offset:2576
	global_load_dwordx4 a[212:215], v[84:85], off offset:2560
	global_load_dwordx4 a[216:219], v[84:85], off offset:2576
	global_load_dwordx4 a[220:223], v[86:87], off offset:2560
	global_load_dwordx4 a[224:227], v[86:87], off offset:2576
	v_pk_mul_f32 v[0:1], v[28:29], v[0:1]
	v_pk_mul_f32 v[2:3], v[28:29], v[2:3]
	v_pk_mul_f32 v[4:5], v[28:29], v[4:5]
	v_pk_mul_f32 v[6:7], v[28:29], v[6:7]
	v_pk_mul_f32 v[0:1], v[0:1], v[32:33]
	v_pk_mul_f32 v[2:3], v[2:3], v[34:35]
	v_pk_mul_f32 v[4:5], v[4:5], v[36:37]
	v_pk_mul_f32 v[6:7], v[6:7], v[38:39]
	v_pk_add_f32 v[40:41], v[40:41], 1.0 op_sel_hi:[1,0]
	v_pk_add_f32 v[42:43], v[42:43], 1.0 op_sel_hi:[1,0]
	v_pk_add_f32 v[44:45], v[44:45], 1.0 op_sel_hi:[1,0]
	v_pk_add_f32 v[46:47], v[46:47], 1.0 op_sel_hi:[1,0]
	v_pk_fma_f32 v[0:1], v[0:1], v[40:41], v[58:59]
	v_pk_fma_f32 v[2:3], v[2:3], v[42:43], v[60:61]
	v_pk_fma_f32 v[4:5], v[4:5], v[44:45], v[62:63]
	v_pk_fma_f32 v[6:7], v[6:7], v[46:47], v[64:65]
	v_cvt_pk_f16_f32 v74, v0, v1
	v_cvt_pk_f16_f32 v75, v2, v3
	v_cvt_pk_f16_f32 v76, v4, v5
	v_cvt_pk_f16_f32 v77, v6, v7
	v_cvt_f32_f16_e32 v66, v74
	v_cvt_f32_f16_sdwa v67, v74 dst_sel:DWORD dst_unused:UNUSED_PAD src0_sel:WORD_1
	v_cvt_f32_f16_e32 v68, v75
	v_cvt_f32_f16_sdwa v69, v75 dst_sel:DWORD dst_unused:UNUSED_PAD src0_sel:WORD_1
	v_cvt_f32_f16_e32 v70, v76
	v_cvt_f32_f16_sdwa v71, v76 dst_sel:DWORD dst_unused:UNUSED_PAD src0_sel:WORD_1
	v_cvt_f32_f16_e32 v72, v77
	v_cvt_f32_f16_sdwa v73, v77 dst_sel:DWORD dst_unused:UNUSED_PAD src0_sel:WORD_1
	v_pk_add_f32 v[0:1], v[0:1], v[66:67] neg_lo:[0,1] neg_hi:[0,1]
	v_pk_add_f32 v[2:3], v[2:3], v[68:69] neg_lo:[0,1] neg_hi:[0,1]
	v_pk_add_f32 v[4:5], v[4:5], v[70:71] neg_lo:[0,1] neg_hi:[0,1]
	v_pk_add_f32 v[6:7], v[6:7], v[72:73] neg_lo:[0,1] neg_hi:[0,1]
	s_nop 0
	v_cvt_pk_f16_f32 v78, v0, v1
	v_cvt_pk_f16_f32 v79, v2, v3
	v_cvt_pk_f16_f32 v80, v4, v5
	v_cvt_pk_f16_f32 v81, v6, v7
	global_store_dwordx4 v[88:89], v[74:77], off offset:1088
	s_waitcnt vmcnt(39)
	v_mfma_f32_16x16x32_f16 a[8:11], v[74:77], a[228:231], a[8:11]
	v_mfma_f32_16x16x32_f16 a[8:11], v[78:81], a[228:231], a[8:11]
	v_mfma_f32_16x16x32_f16 a[8:11], v[74:77], a[232:235], a[8:11]
	v_mfma_f32_16x16x32_f16 a[4:7], v[74:77], a[236:239], a[4:7]
	v_mfma_f32_16x16x32_f16 a[4:7], v[78:81], a[236:239], a[4:7]
	v_mfma_f32_16x16x32_f16 a[4:7], v[74:77], a[240:243], a[4:7]
	v_mfma_f32_16x16x32_f16 a[0:3], v[74:77], a[244:247], a[0:3]
	v_mfma_f32_16x16x32_f16 a[0:3], v[78:81], a[244:247], a[0:3]
	v_mfma_f32_16x16x32_f16 a[0:3], v[74:77], a[248:251], a[0:3]
	global_load_dwordx4 a[228:231], v[90:91], off offset:1280
	global_load_dwordx4 a[232:235], v[92:93], off offset:1280
	global_load_dwordx4 a[236:239], v[94:95], off offset:1280
	global_load_dwordx4 a[240:243], v[96:97], off offset:1280
	global_load_dwordx4 a[244:247], v[98:99], off offset:1280
	global_load_dwordx4 a[248:251], v[100:101], off offset:1280
	s_waitcnt vmcnt(37)
; DI f4 mfma16(h8 a, h8 b, f4 c) { return __builtin_amdgcn_mfma_f32_16x16x32_f16(a, b, c, 0, 0, 0); }
; DI void row2_phase(const Params& P, int l, int r_begin, char* smem) {
;     ...
; #pragma unroll 4
;     for (int kk = 0; kk < 32; kk++) {
;       const int k0 = kk * 32;
;       float x[8], g[8], s1[8], s0[8];
;       *(float4*)&x[0] = *(const float4*)(xm + k0); *(float4*)&x[4] = *(const float4*)(xm + k0 + 4);
;       *(float4*)&g[0] = *(const float4*)(gam + fq * 8 + k0); *(float4*)&g[4] = *(const float4*)(gam + fq * 8 + k0 + 4);
;       *(float4*)&s1[0] = *(const float4*)(sc + k0); *(float4*)&s1[4] = *(const float4*)(sc + k0 + 4);
;       *(float4*)&s0[0] = *(const float4*)(sh + k0); *(float4*)&s0[4] = *(const float4*)(sh + k0 + 4);
;       h8 hi, lo;
; #pragma unroll
;       for (int i = 0; i < 8; i++) {
;         float v = x[i] * rstd * g[i] * (1.f + s1[i]) + s0[i];
;         hi[i] = (half_t)v; lo[i] = (half_t)(v - (float)hi[i]);
;       }
;       *(h8*)(hxo + k0) = hi;
; #pragma unroll
;       for (int n3 = 0; n3 < 3; n3++) {
;         h8 bh = *(const h8*)(Whi + (size_t)(n3 * 16 + fr) * 1024 + k0 + fq * 8);
;         h8 bl = *(const h8*)(Wlo + (size_t)(n3 * 16 + fr) * 1024 + k0 + fq * 8);
;         acc[n3] = mfma16(hi, bh, acc[n3]); acc[n3] = mfma16(lo, bh, acc[n3]); acc[n3] = mfma16(hi, bl, acc[n3]);
;       }
;     }
	v_accvgpr_read_b32 v0, a32
	v_accvgpr_read_b32 v1, a33
	v_accvgpr_read_b32 v2, a34
	v_accvgpr_read_b32 v3, a35
	v_accvgpr_read_b32 v4, a36
	v_accvgpr_read_b32 v5, a37
	v_accvgpr_read_b32 v6, a38
	v_accvgpr_read_b32 v7, a39
	v_accvgpr_read_b32 v32, a80
	v_accvgpr_read_b32 v33, a81
	v_accvgpr_read_b32 v34, a82
	v_accvgpr_read_b32 v35, a83
	v_accvgpr_read_b32 v36, a84
	v_accvgpr_read_b32 v37, a85
	v_accvgpr_read_b32 v38, a86
	v_accvgpr_read_b32 v39, a87
	v_accvgpr_read_b32 v40, a88
	v_accvgpr_read_b32 v41, a89
	v_accvgpr_read_b32 v42, a90
	v_accvgpr_read_b32 v43, a91
	v_accvgpr_read_b32 v44, a92
	v_accvgpr_read_b32 v45, a93
	v_accvgpr_read_b32 v46, a94
	v_accvgpr_read_b32 v47, a95
	v_accvgpr_read_b32 v58, a96
	v_accvgpr_read_b32 v59, a97
	v_accvgpr_read_b32 v60, a98
	v_accvgpr_read_b32 v61, a99
	v_accvgpr_read_b32 v62, a100
	v_accvgpr_read_b32 v63, a101
	v_accvgpr_read_b32 v64, a102
	v_accvgpr_read_b32 v65, a103
	global_load_dwordx4 a[32:35], v[22:23], off offset:3328
	global_load_dwordx4 a[36:39], v[22:23], off offset:3344
	global_load_dwordx4 a[80:83], v[14:15], off offset:2688
	global_load_dwordx4 a[84:87], v[14:15], off offset:2704
	global_load_dwordx4 a[88:91], v[84:85], off offset:2688
	global_load_dwordx4 a[92:95], v[84:85], off offset:2704
	global_load_dwordx4 a[96:99], v[86:87], off offset:2688
	global_load_dwordx4 a[100:103], v[86:87], off offset:2704
	v_pk_mul_f32 v[0:1], v[28:29], v[0:1]
	v_pk_mul_f32 v[2:3], v[28:29], v[2:3]
	v_pk_mul_f32 v[4:5], v[28:29], v[4:5]
	v_pk_mul_f32 v[6:7], v[28:29], v[6:7]
	v_pk_mul_f32 v[0:1], v[0:1], v[32:33]
	v_pk_mul_f32 v[2:3], v[2:3], v[34:35]
	v_pk_mul_f32 v[4:5], v[4:5], v[36:37]
	v_pk_mul_f32 v[6:7], v[6:7], v[38:39]
	v_pk_add_f32 v[40:41], v[40:41], 1.0 op_sel_hi:[1,0]
	v_pk_add_f32 v[42:43], v[42:43], 1.0 op_sel_hi:[1,0]
	v_pk_add_f32 v[44:45], v[44:45], 1.0 op_sel_hi:[1,0]
	v_pk_add_f32 v[46:47], v[46:47], 1.0 op_sel_hi:[1,0]
	v_pk_fma_f32 v[0:1], v[0:1], v[40:41], v[58:59]
	v_pk_fma_f32 v[2:3], v[2:3], v[42:43], v[60:61]
	v_pk_fma_f32 v[4:5], v[4:5], v[44:45], v[62:63]
	v_pk_fma_f32 v[6:7], v[6:7], v[46:47], v[64:65]
	v_cvt_pk_f16_f32 v74, v0, v1
	v_cvt_pk_f16_f32 v75, v2, v3
	v_cvt_pk_f16_f32 v76, v4, v5
	v_cvt_pk_f16_f32 v77, v6, v7
	v_cvt_f32_f16_e32 v66, v74
	v_cvt_f32_f16_sdwa v67, v74 dst_sel:DWORD dst_unused:UNUSED_PAD src0_sel:WORD_1
	v_cvt_f32_f16_e32 v68, v75
	v_cvt_f32_f16_sdwa v69, v75 dst_sel:DWORD dst_unused:UNUSED_PAD src0_sel:WORD_1
	v_cvt_f32_f16_e32 v70, v76
	v_cvt_f32_f16_sdwa v71, v76 dst_sel:DWORD dst_unused:UNUSED_PAD src0_sel:WORD_1
	v_cvt_f32_f16_e32 v72, v77
	v_cvt_f32_f16_sdwa v73, v77 dst_sel:DWORD dst_unused:UNUSED_PAD src0_sel:WORD_1
	v_pk_add_f32 v[0:1], v[0:1], v[66:67] neg_lo:[0,1] neg_hi:[0,1]
	v_pk_add_f32 v[2:3], v[2:3], v[68:69] neg_lo:[0,1] neg_hi:[0,1]
	v_pk_add_f32 v[4:5], v[4:5], v[70:71] neg_lo:[0,1] neg_hi:[0,1]
	v_pk_add_f32 v[6:7], v[6:7], v[72:73] neg_lo:[0,1] neg_hi:[0,1]
	s_nop 0
	v_cvt_pk_f16_f32 v78, v0, v1
	v_cvt_pk_f16_f32 v79, v2, v3
	v_cvt_pk_f16_f32 v80, v4, v5
	v_cvt_pk_f16_f32 v81, v6, v7
	global_store_dwordx4 v[88:89], v[74:77], off offset:1152
	s_waitcnt vmcnt(39)
	v_mfma_f32_16x16x32_f16 a[8:11], v[74:77], a[104:107], a[8:11]
	v_mfma_f32_16x16x32_f16 a[8:11], v[78:81], a[104:107], a[8:11]
	v_mfma_f32_16x16x32_f16 a[8:11], v[74:77], a[108:111], a[8:11]
	v_mfma_f32_16x16x32_f16 a[4:7], v[74:77], a[112:115], a[4:7]
	v_mfma_f32_16x16x32_f16 a[4:7], v[78:81], a[112:115], a[4:7]
	v_mfma_f32_16x16x32_f16 a[4:7], v[74:77], a[116:119], a[4:7]
	v_mfma_f32_16x16x32_f16 a[0:3], v[74:77], a[120:123], a[0:3]
	v_mfma_f32_16x16x32_f16 a[0:3], v[78:81], a[120:123], a[0:3]
	v_mfma_f32_16x16x32_f16 a[0:3], v[74:77], a[124:127], a[0:3]
	global_load_dwordx4 a[104:107], v[90:91], off offset:1344
	global_load_dwordx4 a[108:111], v[92:93], off offset:1344
	global_load_dwordx4 a[112:115], v[94:95], off offset:1344
	global_load_dwordx4 a[116:119], v[96:97], off offset:1344
	global_load_dwordx4 a[120:123], v[98:99], off offset:1344
	global_load_dwordx4 a[124:127], v[100:101], off offset:1344
	s_waitcnt vmcnt(37)
	v_accvgpr_read_b32 v0, a40
	v_accvgpr_read_b32 v1, a41
	v_accvgpr_read_b32 v2, a42
	v_accvgpr_read_b32 v3, a43
	v_accvgpr_read_b32 v4, a44
	v_accvgpr_read_b32 v5, a45
	v_accvgpr_read_b32 v6, a46
	v_accvgpr_read_b32 v7, a47
	v_accvgpr_read_b32 v32, a128
	v_accvgpr_read_b32 v33, a129
	v_accvgpr_read_b32 v34, a130
	v_accvgpr_read_b32 v35, a131
	v_accvgpr_read_b32 v36, a132
	v_accvgpr_read_b32 v37, a133
	v_accvgpr_read_b32 v38, a134
	v_accvgpr_read_b32 v39, a135
	v_accvgpr_read_b32 v40, a136
	v_accvgpr_read_b32 v41, a137
	v_accvgpr_read_b32 v42, a138
	v_accvgpr_read_b32 v43, a139
	v_accvgpr_read_b32 v44, a140
	v_accvgpr_read_b32 v45, a141
	v_accvgpr_read_b32 v46, a142
	v_accvgpr_read_b32 v47, a143
	v_accvgpr_read_b32 v58, a144
	v_accvgpr_read_b32 v59, a145
	v_accvgpr_read_b32 v60, a146
	v_accvgpr_read_b32 v61, a147
	v_accvgpr_read_b32 v62, a148
	v_accvgpr_read_b32 v63, a149
	v_accvgpr_read_b32 v64, a150
	v_accvgpr_read_b32 v65, a151
	global_load_dwordx4 a[40:43], v[22:23], off offset:3456
	global_load_dwordx4 a[44:47], v[22:23], off offset:3472
	global_load_dwordx4 a[128:131], v[14:15], off offset:2816
	global_load_dwordx4 a[132:135], v[14:15], off offset:2832
	global_load_dwordx4 a[136:139], v[84:85], off offset:2816
	global_load_dwordx4 a[140:143], v[84:85], off offset:2832
	global_load_dwordx4 a[144:147], v[86:87], off offset:2816
	global_load_dwordx4 a[148:151], v[86:87], off offset:2832
	v_pk_mul_f32 v[0:1], v[28:29], v[0:1]
	v_pk_mul_f32 v[2:3], v[28:29], v[2:3]
	v_pk_mul_f32 v[4:5], v[28:29], v[4:5]
	v_pk_mul_f32 v[6:7], v[28:29], v[6:7]
; DI f4 mfma16(h8 a, h8 b, f4 c) { return __builtin_amdgcn_mfma_f32_16x16x32_f16(a, b, c, 0, 0, 0); }
; DI void row2_phase(const Params& P, int l, int r_begin, char* smem) {
;     ...
; #pragma unroll 4
;     for (int kk = 0; kk < 32; kk++) {
;       const int k0 = kk * 32;
;       float x[8], g[8], s1[8], s0[8];
;       *(float4*)&x[0] = *(const float4*)(xm + k0); *(float4*)&x[4] = *(const float4*)(xm + k0 + 4);
;       *(float4*)&g[0] = *(const float4*)(gam + fq * 8 + k0); *(float4*)&g[4] = *(const float4*)(gam + fq * 8 + k0 + 4);
;       *(float4*)&s1[0] = *(const float4*)(sc + k0); *(float4*)&s1[4] = *(const float4*)(sc + k0 + 4);
;       *(float4*)&s0[0] = *(const float4*)(sh + k0); *(float4*)&s0[4] = *(const float4*)(sh + k0 + 4);
;       h8 hi, lo;
; #pragma unroll
;       for (int i = 0; i < 8; i++) {
;         float v = x[i] * rstd * g[i] * (1.f + s1[i]) + s0[i];
;         hi[i] = (half_t)v; lo[i] = (half_t)(v - (float)hi[i]);
;       }
;       *(h8*)(hxo + k0) = hi;
; #pragma unroll
;       for (int n3 = 0; n3 < 3; n3++) {
;         h8 bh = *(const h8*)(Whi + (size_t)(n3 * 16 + fr) * 1024 + k0 + fq * 8);
;         h8 bl = *(const h8*)(Wlo + (size_t)(n3 * 16 + fr) * 1024 + k0 + fq * 8);
;         acc[n3] = mfma16(hi, bh, acc[n3]); acc[n3] = mfma16(lo, bh, acc[n3]); acc[n3] = mfma16(hi, bl, acc[n3]);
;       }
;     }
	v_pk_mul_f32 v[0:1], v[0:1], v[32:33]
	v_pk_mul_f32 v[2:3], v[2:3], v[34:35]
	v_pk_mul_f32 v[4:5], v[4:5], v[36:37]
	v_pk_mul_f32 v[6:7], v[6:7], v[38:39]
	v_pk_add_f32 v[40:41], v[40:41], 1.0 op_sel_hi:[1,0]
	v_pk_add_f32 v[42:43], v[42:43], 1.0 op_sel_hi:[1,0]
	v_pk_add_f32 v[44:45], v[44:45], 1.0 op_sel_hi:[1,0]
	v_pk_add_f32 v[46:47], v[46:47], 1.0 op_sel_hi:[1,0]
	v_pk_fma_f32 v[0:1], v[0:1], v[40:41], v[58:59]
	v_pk_fma_f32 v[2:3], v[2:3], v[42:43], v[60:61]
	v_pk_fma_f32 v[4:5], v[4:5], v[44:45], v[62:63]
	v_pk_fma_f32 v[6:7], v[6:7], v[46:47], v[64:65]
	v_cvt_pk_f16_f32 v74, v0, v1
	v_cvt_pk_f16_f32 v75, v2, v3
	v_cvt_pk_f16_f32 v76, v4, v5
	v_cvt_pk_f16_f32 v77, v6, v7
	v_cvt_f32_f16_e32 v66, v74
	v_cvt_f32_f16_sdwa v67, v74 dst_sel:DWORD dst_unused:UNUSED_PAD src0_sel:WORD_1
	v_cvt_f32_f16_e32 v68, v75
	v_cvt_f32_f16_sdwa v69, v75 dst_sel:DWORD dst_unused:UNUSED_PAD src0_sel:WORD_1
	v_cvt_f32_f16_e32 v70, v76
	v_cvt_f32_f16_sdwa v71, v76 dst_sel:DWORD dst_unused:UNUSED_PAD src0_sel:WORD_1
	v_cvt_f32_f16_e32 v72, v77
	v_cvt_f32_f16_sdwa v73, v77 dst_sel:DWORD dst_unused:UNUSED_PAD src0_sel:WORD_1
	v_pk_add_f32 v[0:1], v[0:1], v[66:67] neg_lo:[0,1] neg_hi:[0,1]
	v_pk_add_f32 v[2:3], v[2:3], v[68:69] neg_lo:[0,1] neg_hi:[0,1]
	v_pk_add_f32 v[4:5], v[4:5], v[70:71] neg_lo:[0,1] neg_hi:[0,1]
	v_pk_add_f32 v[6:7], v[6:7], v[72:73] neg_lo:[0,1] neg_hi:[0,1]
	s_nop 0
	v_cvt_pk_f16_f32 v78, v0, v1
	v_cvt_pk_f16_f32 v79, v2, v3
	v_cvt_pk_f16_f32 v80, v4, v5
	v_cvt_pk_f16_f32 v81, v6, v7
	global_store_dwordx4 v[88:89], v[74:77], off offset:1216
	s_waitcnt vmcnt(39)
	v_mfma_f32_16x16x32_f16 a[8:11], v[74:77], a[152:155], a[8:11]
	v_mfma_f32_16x16x32_f16 a[8:11], v[78:81], a[152:155], a[8:11]
	v_mfma_f32_16x16x32_f16 a[8:11], v[74:77], a[156:159], a[8:11]
	v_mfma_f32_16x16x32_f16 a[4:7], v[74:77], a[160:163], a[4:7]
	v_mfma_f32_16x16x32_f16 a[4:7], v[78:81], a[160:163], a[4:7]
	v_mfma_f32_16x16x32_f16 a[4:7], v[74:77], a[164:167], a[4:7]
	v_mfma_f32_16x16x32_f16 a[0:3], v[74:77], a[168:171], a[0:3]
	v_mfma_f32_16x16x32_f16 a[0:3], v[78:81], a[168:171], a[0:3]
	v_mfma_f32_16x16x32_f16 a[0:3], v[74:77], a[172:175], a[0:3]
	global_load_dwordx4 a[152:155], v[90:91], off offset:1408
	global_load_dwordx4 a[156:159], v[92:93], off offset:1408
	global_load_dwordx4 a[160:163], v[94:95], off offset:1408
	global_load_dwordx4 a[164:167], v[96:97], off offset:1408
	global_load_dwordx4 a[168:171], v[98:99], off offset:1408
	global_load_dwordx4 a[172:175], v[100:101], off offset:1408
	s_waitcnt vmcnt(37)
	v_accvgpr_read_b32 v0, a48
	v_accvgpr_read_b32 v1, a49
	v_accvgpr_read_b32 v2, a50
	v_accvgpr_read_b32 v3, a51
	v_accvgpr_read_b32 v4, a52
	v_accvgpr_read_b32 v5, a53
	v_accvgpr_read_b32 v6, a54
	v_accvgpr_read_b32 v7, a55
	v_accvgpr_read_b32 v32, a204
	v_accvgpr_read_b32 v33, a205
	v_accvgpr_read_b32 v34, a206
	v_accvgpr_read_b32 v35, a207
	v_accvgpr_read_b32 v36, a208
	v_accvgpr_read_b32 v37, a209
	v_accvgpr_read_b32 v38, a210
	v_accvgpr_read_b32 v39, a211
	v_accvgpr_read_b32 v40, a212
	v_accvgpr_read_b32 v41, a213
	v_accvgpr_read_b32 v42, a214
	v_accvgpr_read_b32 v43, a215
	v_accvgpr_read_b32 v44, a216
	v_accvgpr_read_b32 v45, a217
	v_accvgpr_read_b32 v46, a218
	v_accvgpr_read_b32 v47, a219
	v_accvgpr_read_b32 v58, a220
	v_accvgpr_read_b32 v59, a221
	v_accvgpr_read_b32 v60, a222
	v_accvgpr_read_b32 v61, a223
	v_accvgpr_read_b32 v62, a224
	v_accvgpr_read_b32 v63, a225
	v_accvgpr_read_b32 v64, a226
	v_accvgpr_read_b32 v65, a227
	global_load_dwordx4 a[48:51], v[22:23], off offset:3584
	global_load_dwordx4 a[52:55], v[22:23], off offset:3600
	global_load_dwordx4 a[204:207], v[14:15], off offset:2944
	global_load_dwordx4 a[208:211], v[14:15], off offset:2960
	global_load_dwordx4 a[212:215], v[84:85], off offset:2944
	global_load_dwordx4 a[216:219], v[84:85], off offset:2960
	global_load_dwordx4 a[220:223], v[86:87], off offset:2944
	global_load_dwordx4 a[224:227], v[86:87], off offset:2960
	v_pk_mul_f32 v[0:1], v[28:29], v[0:1]
	v_pk_mul_f32 v[2:3], v[28:29], v[2:3]
	v_pk_mul_f32 v[4:5], v[28:29], v[4:5]
	v_pk_mul_f32 v[6:7], v[28:29], v[6:7]
	v_pk_mul_f32 v[0:1], v[0:1], v[32:33]
	v_pk_mul_f32 v[2:3], v[2:3], v[34:35]
	v_pk_mul_f32 v[4:5], v[4:5], v[36:37]
	v_pk_mul_f32 v[6:7], v[6:7], v[38:39]
	v_pk_add_f32 v[40:41], v[40:41], 1.0 op_sel_hi:[1,0]
	v_pk_add_f32 v[42:43], v[42:43], 1.0 op_sel_hi:[1,0]
	v_pk_add_f32 v[44:45], v[44:45], 1.0 op_sel_hi:[1,0]
	v_pk_add_f32 v[46:47], v[46:47], 1.0 op_sel_hi:[1,0]
	v_pk_fma_f32 v[0:1], v[0:1], v[40:41], v[58:59]
	v_pk_fma_f32 v[2:3], v[2:3], v[42:43], v[60:61]
	v_pk_fma_f32 v[4:5], v[4:5], v[44:45], v[62:63]
	v_pk_fma_f32 v[6:7], v[6:7], v[46:47], v[64:65]
	v_cvt_pk_f16_f32 v74, v0, v1
	v_cvt_pk_f16_f32 v75, v2, v3
	v_cvt_pk_f16_f32 v76, v4, v5
	v_cvt_pk_f16_f32 v77, v6, v7
	v_cvt_f32_f16_e32 v66, v74
	v_cvt_f32_f16_sdwa v67, v74 dst_sel:DWORD dst_unused:UNUSED_PAD src0_sel:WORD_1
	v_cvt_f32_f16_e32 v68, v75
	v_cvt_f32_f16_sdwa v69, v75 dst_sel:DWORD dst_unused:UNUSED_PAD src0_sel:WORD_1
	v_cvt_f32_f16_e32 v70, v76
	v_cvt_f32_f16_sdwa v71, v76 dst_sel:DWORD dst_unused:UNUSED_PAD src0_sel:WORD_1
	v_cvt_f32_f16_e32 v72, v77
	v_cvt_f32_f16_sdwa v73, v77 dst_sel:DWORD dst_unused:UNUSED_PAD src0_sel:WORD_1
	v_pk_add_f32 v[0:1], v[0:1], v[66:67] neg_lo:[0,1] neg_hi:[0,1]
	v_pk_add_f32 v[2:3], v[2:3], v[68:69] neg_lo:[0,1] neg_hi:[0,1]
	v_pk_add_f32 v[4:5], v[4:5], v[70:71] neg_lo:[0,1] neg_hi:[0,1]
	v_pk_add_f32 v[6:7], v[6:7], v[72:73] neg_lo:[0,1] neg_hi:[0,1]
	s_nop 0
	v_cvt_pk_f16_f32 v78, v0, v1
	v_cvt_pk_f16_f32 v79, v2, v3
	v_cvt_pk_f16_f32 v80, v4, v5
	v_cvt_pk_f16_f32 v81, v6, v7
	global_store_dwordx4 v[88:89], v[74:77], off offset:1280
	s_waitcnt vmcnt(39)
; DI f4 mfma16(h8 a, h8 b, f4 c) { return __builtin_amdgcn_mfma_f32_16x16x32_f16(a, b, c, 0, 0, 0); }
; DI void row2_phase(const Params& P, int l, int r_begin, char* smem) {
;     ...
; #pragma unroll 4
;     for (int kk = 0; kk < 32; kk++) {
;       const int k0 = kk * 32;
;       float x[8], g[8], s1[8], s0[8];
;       *(float4*)&x[0] = *(const float4*)(xm + k0); *(float4*)&x[4] = *(const float4*)(xm + k0 + 4);
;       *(float4*)&g[0] = *(const float4*)(gam + fq * 8 + k0); *(float4*)&g[4] = *(const float4*)(gam + fq * 8 + k0 + 4);
;       *(float4*)&s1[0] = *(const float4*)(sc + k0); *(float4*)&s1[4] = *(const float4*)(sc + k0 + 4);
;       *(float4*)&s0[0] = *(const float4*)(sh + k0); *(float4*)&s0[4] = *(const float4*)(sh + k0 + 4);
;       h8 hi, lo;
; #pragma unroll
;       for (int i = 0; i < 8; i++) {
;         float v = x[i] * rstd * g[i] * (1.f + s1[i]) + s0[i];
;         hi[i] = (half_t)v; lo[i] = (half_t)(v - (float)hi[i]);
;       }
;       *(h8*)(hxo + k0) = hi;
; #pragma unroll
;       for (int n3 = 0; n3 < 3; n3++) {
;         h8 bh = *(const h8*)(Whi + (size_t)(n3 * 16 + fr) * 1024 + k0 + fq * 8);
;         h8 bl = *(const h8*)(Wlo + (size_t)(n3 * 16 + fr) * 1024 + k0 + fq * 8);
;         acc[n3] = mfma16(hi, bh, acc[n3]); acc[n3] = mfma16(lo, bh, acc[n3]); acc[n3] = mfma16(hi, bl, acc[n3]);
;       }
;     }
	v_mfma_f32_16x16x32_f16 a[8:11], v[74:77], a[228:231], a[8:11]
	v_mfma_f32_16x16x32_f16 a[8:11], v[78:81], a[228:231], a[8:11]
	v_mfma_f32_16x16x32_f16 a[8:11], v[74:77], a[232:235], a[8:11]
	v_mfma_f32_16x16x32_f16 a[4:7], v[74:77], a[236:239], a[4:7]
	v_mfma_f32_16x16x32_f16 a[4:7], v[78:81], a[236:239], a[4:7]
	v_mfma_f32_16x16x32_f16 a[4:7], v[74:77], a[240:243], a[4:7]
	v_mfma_f32_16x16x32_f16 a[0:3], v[74:77], a[244:247], a[0:3]
	v_mfma_f32_16x16x32_f16 a[0:3], v[78:81], a[244:247], a[0:3]
	v_mfma_f32_16x16x32_f16 a[0:3], v[74:77], a[248:251], a[0:3]
	global_load_dwordx4 a[228:231], v[90:91], off offset:1472
	global_load_dwordx4 a[232:235], v[92:93], off offset:1472
	global_load_dwordx4 a[236:239], v[94:95], off offset:1472
	global_load_dwordx4 a[240:243], v[96:97], off offset:1472
	global_load_dwordx4 a[244:247], v[98:99], off offset:1472
	global_load_dwordx4 a[248:251], v[100:101], off offset:1472
	s_waitcnt vmcnt(37)
	v_accvgpr_read_b32 v0, a56
	v_accvgpr_read_b32 v1, a57
	v_accvgpr_read_b32 v2, a58
	v_accvgpr_read_b32 v3, a59
	v_accvgpr_read_b32 v4, a60
	v_accvgpr_read_b32 v5, a61
	v_accvgpr_read_b32 v6, a62
	v_accvgpr_read_b32 v7, a63
	v_accvgpr_read_b32 v32, a80
	v_accvgpr_read_b32 v33, a81
	v_accvgpr_read_b32 v34, a82
	v_accvgpr_read_b32 v35, a83
	v_accvgpr_read_b32 v36, a84
	v_accvgpr_read_b32 v37, a85
	v_accvgpr_read_b32 v38, a86
	v_accvgpr_read_b32 v39, a87
	v_accvgpr_read_b32 v40, a88
	v_accvgpr_read_b32 v41, a89
	v_accvgpr_read_b32 v42, a90
	v_accvgpr_read_b32 v43, a91
	v_accvgpr_read_b32 v44, a92
	v_accvgpr_read_b32 v45, a93
	v_accvgpr_read_b32 v46, a94
	v_accvgpr_read_b32 v47, a95
	v_accvgpr_read_b32 v58, a96
	v_accvgpr_read_b32 v59, a97
	v_accvgpr_read_b32 v60, a98
	v_accvgpr_read_b32 v61, a99
	v_accvgpr_read_b32 v62, a100
	v_accvgpr_read_b32 v63, a101
	v_accvgpr_read_b32 v64, a102
	v_accvgpr_read_b32 v65, a103
	global_load_dwordx4 a[56:59], v[22:23], off offset:3712
	global_load_dwordx4 a[60:63], v[22:23], off offset:3728
	global_load_dwordx4 a[80:83], v[14:15], off offset:3072
	global_load_dwordx4 a[84:87], v[14:15], off offset:3088
	global_load_dwordx4 a[88:91], v[84:85], off offset:3072
	global_load_dwordx4 a[92:95], v[84:85], off offset:3088
	global_load_dwordx4 a[96:99], v[86:87], off offset:3072
	global_load_dwordx4 a[100:103], v[86:87], off offset:3088
	v_pk_mul_f32 v[0:1], v[28:29], v[0:1]
	v_pk_mul_f32 v[2:3], v[28:29], v[2:3]
	v_pk_mul_f32 v[4:5], v[28:29], v[4:5]
	v_pk_mul_f32 v[6:7], v[28:29], v[6:7]
	v_pk_mul_f32 v[0:1], v[0:1], v[32:33]
	v_pk_mul_f32 v[2:3], v[2:3], v[34:35]
	v_pk_mul_f32 v[4:5], v[4:5], v[36:37]
	v_pk_mul_f32 v[6:7], v[6:7], v[38:39]
	v_pk_add_f32 v[40:41], v[40:41], 1.0 op_sel_hi:[1,0]
	v_pk_add_f32 v[42:43], v[42:43], 1.0 op_sel_hi:[1,0]
	v_pk_add_f32 v[44:45], v[44:45], 1.0 op_sel_hi:[1,0]
	v_pk_add_f32 v[46:47], v[46:47], 1.0 op_sel_hi:[1,0]
	v_pk_fma_f32 v[0:1], v[0:1], v[40:41], v[58:59]
	v_pk_fma_f32 v[2:3], v[2:3], v[42:43], v[60:61]
	v_pk_fma_f32 v[4:5], v[4:5], v[44:45], v[62:63]
	v_pk_fma_f32 v[6:7], v[6:7], v[46:47], v[64:65]
	v_cvt_pk_f16_f32 v74, v0, v1
	v_cvt_pk_f16_f32 v75, v2, v3
	v_cvt_pk_f16_f32 v76, v4, v5
	v_cvt_pk_f16_f32 v77, v6, v7
	v_cvt_f32_f16_e32 v66, v74
	v_cvt_f32_f16_sdwa v67, v74 dst_sel:DWORD dst_unused:UNUSED_PAD src0_sel:WORD_1
	v_cvt_f32_f16_e32 v68, v75
	v_cvt_f32_f16_sdwa v69, v75 dst_sel:DWORD dst_unused:UNUSED_PAD src0_sel:WORD_1
	v_cvt_f32_f16_e32 v70, v76
	v_cvt_f32_f16_sdwa v71, v76 dst_sel:DWORD dst_unused:UNUSED_PAD src0_sel:WORD_1
	v_cvt_f32_f16_e32 v72, v77
	v_cvt_f32_f16_sdwa v73, v77 dst_sel:DWORD dst_unused:UNUSED_PAD src0_sel:WORD_1
	v_pk_add_f32 v[0:1], v[0:1], v[66:67] neg_lo:[0,1] neg_hi:[0,1]
	v_pk_add_f32 v[2:3], v[2:3], v[68:69] neg_lo:[0,1] neg_hi:[0,1]
	v_pk_add_f32 v[4:5], v[4:5], v[70:71] neg_lo:[0,1] neg_hi:[0,1]
	v_pk_add_f32 v[6:7], v[6:7], v[72:73] neg_lo:[0,1] neg_hi:[0,1]
	s_nop 0
	v_cvt_pk_f16_f32 v78, v0, v1
	v_cvt_pk_f16_f32 v79, v2, v3
	v_cvt_pk_f16_f32 v80, v4, v5
	v_cvt_pk_f16_f32 v81, v6, v7
	global_store_dwordx4 v[88:89], v[74:77], off offset:1344
	s_waitcnt vmcnt(39)
	v_mfma_f32_16x16x32_f16 a[8:11], v[74:77], a[104:107], a[8:11]
	v_mfma_f32_16x16x32_f16 a[8:11], v[78:81], a[104:107], a[8:11]
	v_mfma_f32_16x16x32_f16 a[8:11], v[74:77], a[108:111], a[8:11]
	v_mfma_f32_16x16x32_f16 a[4:7], v[74:77], a[112:115], a[4:7]
	v_mfma_f32_16x16x32_f16 a[4:7], v[78:81], a[112:115], a[4:7]
	v_mfma_f32_16x16x32_f16 a[4:7], v[74:77], a[116:119], a[4:7]
	v_mfma_f32_16x16x32_f16 a[0:3], v[74:77], a[120:123], a[0:3]
	v_mfma_f32_16x16x32_f16 a[0:3], v[78:81], a[120:123], a[0:3]
	v_mfma_f32_16x16x32_f16 a[0:3], v[74:77], a[124:127], a[0:3]
	global_load_dwordx4 a[104:107], v[90:91], off offset:1536
	global_load_dwordx4 a[108:111], v[92:93], off offset:1536
	global_load_dwordx4 a[112:115], v[94:95], off offset:1536
	global_load_dwordx4 a[116:119], v[96:97], off offset:1536
	global_load_dwordx4 a[120:123], v[98:99], off offset:1536
	global_load_dwordx4 a[124:127], v[100:101], off offset:1536
	s_waitcnt vmcnt(37)
; DI f4 mfma16(h8 a, h8 b, f4 c) { return __builtin_amdgcn_mfma_f32_16x16x32_f16(a, b, c, 0, 0, 0); }
; DI void row2_phase(const Params& P, int l, int r_begin, char* smem) {
;     ...
; #pragma unroll 4
;     for (int kk = 0; kk < 32; kk++) {
;       const int k0 = kk * 32;
;       float x[8], g[8], s1[8], s0[8];
;       *(float4*)&x[0] = *(const float4*)(xm + k0); *(float4*)&x[4] = *(const float4*)(xm + k0 + 4);
;       *(float4*)&g[0] = *(const float4*)(gam + fq * 8 + k0); *(float4*)&g[4] = *(const float4*)(gam + fq * 8 + k0 + 4);
;       *(float4*)&s1[0] = *(const float4*)(sc + k0); *(float4*)&s1[4] = *(const float4*)(sc + k0 + 4);
;       *(float4*)&s0[0] = *(const float4*)(sh + k0); *(float4*)&s0[4] = *(const float4*)(sh + k0 + 4);
;       h8 hi, lo;
; #pragma unroll
;       for (int i = 0; i < 8; i++) {
;         float v = x[i] * rstd * g[i] * (1.f + s1[i]) + s0[i];
;         hi[i] = (half_t)v; lo[i] = (half_t)(v - (float)hi[i]);
;       }
;       *(h8*)(hxo + k0) = hi;
; #pragma unroll
;       for (int n3 = 0; n3 < 3; n3++) {
;         h8 bh = *(const h8*)(Whi + (size_t)(n3 * 16 + fr) * 1024 + k0 + fq * 8);
;         h8 bl = *(const h8*)(Wlo + (size_t)(n3 * 16 + fr) * 1024 + k0 + fq * 8);
;         acc[n3] = mfma16(hi, bh, acc[n3]); acc[n3] = mfma16(lo, bh, acc[n3]); acc[n3] = mfma16(hi, bl, acc[n3]);
;       }
;     }
	v_accvgpr_read_b32 v0, a64
	v_accvgpr_read_b32 v1, a65
	v_accvgpr_read_b32 v2, a66
	v_accvgpr_read_b32 v3, a67
	v_accvgpr_read_b32 v4, a68
	v_accvgpr_read_b32 v5, a69
	v_accvgpr_read_b32 v6, a70
	v_accvgpr_read_b32 v7, a71
	v_accvgpr_read_b32 v32, a128
	v_accvgpr_read_b32 v33, a129
	v_accvgpr_read_b32 v34, a130
	v_accvgpr_read_b32 v35, a131
	v_accvgpr_read_b32 v36, a132
	v_accvgpr_read_b32 v37, a133
	v_accvgpr_read_b32 v38, a134
	v_accvgpr_read_b32 v39, a135
	v_accvgpr_read_b32 v40, a136
	v_accvgpr_read_b32 v41, a137
	v_accvgpr_read_b32 v42, a138
	v_accvgpr_read_b32 v43, a139
	v_accvgpr_read_b32 v44, a140
	v_accvgpr_read_b32 v45, a141
	v_accvgpr_read_b32 v46, a142
	v_accvgpr_read_b32 v47, a143
	v_accvgpr_read_b32 v58, a144
	v_accvgpr_read_b32 v59, a145
	v_accvgpr_read_b32 v60, a146
	v_accvgpr_read_b32 v61, a147
	v_accvgpr_read_b32 v62, a148
	v_accvgpr_read_b32 v63, a149
	v_accvgpr_read_b32 v64, a150
	v_accvgpr_read_b32 v65, a151
	global_load_dwordx4 a[64:67], v[22:23], off offset:3840
	global_load_dwordx4 a[68:71], v[22:23], off offset:3856
	global_load_dwordx4 a[128:131], v[14:15], off offset:3200
	global_load_dwordx4 a[132:135], v[14:15], off offset:3216
	global_load_dwordx4 a[136:139], v[84:85], off offset:3200
	global_load_dwordx4 a[140:143], v[84:85], off offset:3216
	global_load_dwordx4 a[144:147], v[86:87], off offset:3200
	global_load_dwordx4 a[148:151], v[86:87], off offset:3216
	v_pk_mul_f32 v[0:1], v[28:29], v[0:1]
	v_pk_mul_f32 v[2:3], v[28:29], v[2:3]
	v_pk_mul_f32 v[4:5], v[28:29], v[4:5]
	v_pk_mul_f32 v[6:7], v[28:29], v[6:7]
	v_pk_mul_f32 v[0:1], v[0:1], v[32:33]
	v_pk_mul_f32 v[2:3], v[2:3], v[34:35]
	v_pk_mul_f32 v[4:5], v[4:5], v[36:37]
	v_pk_mul_f32 v[6:7], v[6:7], v[38:39]
	v_pk_add_f32 v[40:41], v[40:41], 1.0 op_sel_hi:[1,0]
	v_pk_add_f32 v[42:43], v[42:43], 1.0 op_sel_hi:[1,0]
	v_pk_add_f32 v[44:45], v[44:45], 1.0 op_sel_hi:[1,0]
	v_pk_add_f32 v[46:47], v[46:47], 1.0 op_sel_hi:[1,0]
	v_pk_fma_f32 v[0:1], v[0:1], v[40:41], v[58:59]
	v_pk_fma_f32 v[2:3], v[2:3], v[42:43], v[60:61]
	v_pk_fma_f32 v[4:5], v[4:5], v[44:45], v[62:63]
	v_pk_fma_f32 v[6:7], v[6:7], v[46:47], v[64:65]
	v_cvt_pk_f16_f32 v74, v0, v1
	v_cvt_pk_f16_f32 v75, v2, v3
	v_cvt_pk_f16_f32 v76, v4, v5
	v_cvt_pk_f16_f32 v77, v6, v7
	v_cvt_f32_f16_e32 v66, v74
	v_cvt_f32_f16_sdwa v67, v74 dst_sel:DWORD dst_unused:UNUSED_PAD src0_sel:WORD_1
	v_cvt_f32_f16_e32 v68, v75
	v_cvt_f32_f16_sdwa v69, v75 dst_sel:DWORD dst_unused:UNUSED_PAD src0_sel:WORD_1
	v_cvt_f32_f16_e32 v70, v76
	v_cvt_f32_f16_sdwa v71, v76 dst_sel:DWORD dst_unused:UNUSED_PAD src0_sel:WORD_1
	v_cvt_f32_f16_e32 v72, v77
	v_cvt_f32_f16_sdwa v73, v77 dst_sel:DWORD dst_unused:UNUSED_PAD src0_sel:WORD_1
	v_pk_add_f32 v[0:1], v[0:1], v[66:67] neg_lo:[0,1] neg_hi:[0,1]
	v_pk_add_f32 v[2:3], v[2:3], v[68:69] neg_lo:[0,1] neg_hi:[0,1]
	v_pk_add_f32 v[4:5], v[4:5], v[70:71] neg_lo:[0,1] neg_hi:[0,1]
	v_pk_add_f32 v[6:7], v[6:7], v[72:73] neg_lo:[0,1] neg_hi:[0,1]
	s_nop 0
	v_cvt_pk_f16_f32 v78, v0, v1
	v_cvt_pk_f16_f32 v79, v2, v3
	v_cvt_pk_f16_f32 v80, v4, v5
	v_cvt_pk_f16_f32 v81, v6, v7
	global_store_dwordx4 v[88:89], v[74:77], off offset:1408
	s_waitcnt vmcnt(39)
	v_mfma_f32_16x16x32_f16 a[8:11], v[74:77], a[152:155], a[8:11]
	v_mfma_f32_16x16x32_f16 a[8:11], v[78:81], a[152:155], a[8:11]
	v_mfma_f32_16x16x32_f16 a[8:11], v[74:77], a[156:159], a[8:11]
	v_mfma_f32_16x16x32_f16 a[4:7], v[74:77], a[160:163], a[4:7]
	v_mfma_f32_16x16x32_f16 a[4:7], v[78:81], a[160:163], a[4:7]
	v_mfma_f32_16x16x32_f16 a[4:7], v[74:77], a[164:167], a[4:7]
	v_mfma_f32_16x16x32_f16 a[0:3], v[74:77], a[168:171], a[0:3]
	v_mfma_f32_16x16x32_f16 a[0:3], v[78:81], a[168:171], a[0:3]
	v_mfma_f32_16x16x32_f16 a[0:3], v[74:77], a[172:175], a[0:3]
	global_load_dwordx4 a[152:155], v[90:91], off offset:1600
	global_load_dwordx4 a[156:159], v[92:93], off offset:1600
	global_load_dwordx4 a[160:163], v[94:95], off offset:1600
	global_load_dwordx4 a[164:167], v[96:97], off offset:1600
	global_load_dwordx4 a[168:171], v[98:99], off offset:1600
	global_load_dwordx4 a[172:175], v[100:101], off offset:1600
	s_waitcnt vmcnt(37)
	v_accvgpr_read_b32 v0, a72
	v_accvgpr_read_b32 v1, a73
	v_accvgpr_read_b32 v2, a74
	v_accvgpr_read_b32 v3, a75
	v_accvgpr_read_b32 v4, a76
	v_accvgpr_read_b32 v5, a77
	v_accvgpr_read_b32 v6, a78
	v_accvgpr_read_b32 v7, a79
	v_accvgpr_read_b32 v32, a204
	v_accvgpr_read_b32 v33, a205
	v_accvgpr_read_b32 v34, a206
	v_accvgpr_read_b32 v35, a207
	v_accvgpr_read_b32 v36, a208
	v_accvgpr_read_b32 v37, a209
	v_accvgpr_read_b32 v38, a210
	v_accvgpr_read_b32 v39, a211
	v_accvgpr_read_b32 v40, a212
	v_accvgpr_read_b32 v41, a213
	v_accvgpr_read_b32 v42, a214
	v_accvgpr_read_b32 v43, a215
	v_accvgpr_read_b32 v44, a216
	v_accvgpr_read_b32 v45, a217
	v_accvgpr_read_b32 v46, a218
	v_accvgpr_read_b32 v47, a219
	v_accvgpr_read_b32 v58, a220
	v_accvgpr_read_b32 v59, a221
	v_accvgpr_read_b32 v60, a222
	v_accvgpr_read_b32 v61, a223
	v_accvgpr_read_b32 v62, a224
	v_accvgpr_read_b32 v63, a225
	v_accvgpr_read_b32 v64, a226
	v_accvgpr_read_b32 v65, a227
	global_load_dwordx4 a[72:75], v[22:23], off offset:3968
	global_load_dwordx4 a[76:79], v[22:23], off offset:3984
	global_load_dwordx4 a[204:207], v[14:15], off offset:3328
	global_load_dwordx4 a[208:211], v[14:15], off offset:3344
	global_load_dwordx4 a[212:215], v[84:85], off offset:3328
	global_load_dwordx4 a[216:219], v[84:85], off offset:3344
	global_load_dwordx4 a[220:223], v[86:87], off offset:3328
	global_load_dwordx4 a[224:227], v[86:87], off offset:3344
	v_pk_mul_f32 v[0:1], v[28:29], v[0:1]
	v_pk_mul_f32 v[2:3], v[28:29], v[2:3]
	v_pk_mul_f32 v[4:5], v[28:29], v[4:5]
; DI f4 mfma16(h8 a, h8 b, f4 c) { return __builtin_amdgcn_mfma_f32_16x16x32_f16(a, b, c, 0, 0, 0); }
; DI void row2_phase(const Params& P, int l, int r_begin, char* smem) {
;     ...
; #pragma unroll 4
;     for (int kk = 0; kk < 32; kk++) {
;       const int k0 = kk * 32;
;       float x[8], g[8], s1[8], s0[8];
;       *(float4*)&x[0] = *(const float4*)(xm + k0); *(float4*)&x[4] = *(const float4*)(xm + k0 + 4);
;       *(float4*)&g[0] = *(const float4*)(gam + fq * 8 + k0); *(float4*)&g[4] = *(const float4*)(gam + fq * 8 + k0 + 4);
;       *(float4*)&s1[0] = *(const float4*)(sc + k0); *(float4*)&s1[4] = *(const float4*)(sc + k0 + 4);
;       *(float4*)&s0[0] = *(const float4*)(sh + k0); *(float4*)&s0[4] = *(const float4*)(sh + k0 + 4);
;       h8 hi, lo;
; #pragma unroll
;       for (int i = 0; i < 8; i++) {
;         float v = x[i] * rstd * g[i] * (1.f + s1[i]) + s0[i];
;         hi[i] = (half_t)v; lo[i] = (half_t)(v - (float)hi[i]);
;       }
;       *(h8*)(hxo + k0) = hi;
; #pragma unroll
;       for (int n3 = 0; n3 < 3; n3++) {
;         h8 bh = *(const h8*)(Whi + (size_t)(n3 * 16 + fr) * 1024 + k0 + fq * 8);
;         h8 bl = *(const h8*)(Wlo + (size_t)(n3 * 16 + fr) * 1024 + k0 + fq * 8);
;         acc[n3] = mfma16(hi, bh, acc[n3]); acc[n3] = mfma16(lo, bh, acc[n3]); acc[n3] = mfma16(hi, bl, acc[n3]);
;       }
;     }
	v_pk_mul_f32 v[6:7], v[28:29], v[6:7]
	v_pk_mul_f32 v[0:1], v[0:1], v[32:33]
	v_pk_mul_f32 v[2:3], v[2:3], v[34:35]
	v_pk_mul_f32 v[4:5], v[4:5], v[36:37]
	v_pk_mul_f32 v[6:7], v[6:7], v[38:39]
	v_pk_add_f32 v[40:41], v[40:41], 1.0 op_sel_hi:[1,0]
	v_pk_add_f32 v[42:43], v[42:43], 1.0 op_sel_hi:[1,0]
	v_pk_add_f32 v[44:45], v[44:45], 1.0 op_sel_hi:[1,0]
	v_pk_add_f32 v[46:47], v[46:47], 1.0 op_sel_hi:[1,0]
	v_pk_fma_f32 v[0:1], v[0:1], v[40:41], v[58:59]
	v_pk_fma_f32 v[2:3], v[2:3], v[42:43], v[60:61]
	v_pk_fma_f32 v[4:5], v[4:5], v[44:45], v[62:63]
	v_pk_fma_f32 v[6:7], v[6:7], v[46:47], v[64:65]
	v_cvt_pk_f16_f32 v74, v0, v1
	v_cvt_pk_f16_f32 v75, v2, v3
	v_cvt_pk_f16_f32 v76, v4, v5
	v_cvt_pk_f16_f32 v77, v6, v7
	v_cvt_f32_f16_e32 v66, v74
	v_cvt_f32_f16_sdwa v67, v74 dst_sel:DWORD dst_unused:UNUSED_PAD src0_sel:WORD_1
	v_cvt_f32_f16_e32 v68, v75
	v_cvt_f32_f16_sdwa v69, v75 dst_sel:DWORD dst_unused:UNUSED_PAD src0_sel:WORD_1
	v_cvt_f32_f16_e32 v70, v76
	v_cvt_f32_f16_sdwa v71, v76 dst_sel:DWORD dst_unused:UNUSED_PAD src0_sel:WORD_1
	v_cvt_f32_f16_e32 v72, v77
	v_cvt_f32_f16_sdwa v73, v77 dst_sel:DWORD dst_unused:UNUSED_PAD src0_sel:WORD_1
	v_pk_add_f32 v[0:1], v[0:1], v[66:67] neg_lo:[0,1] neg_hi:[0,1]
	v_pk_add_f32 v[2:3], v[2:3], v[68:69] neg_lo:[0,1] neg_hi:[0,1]
	v_pk_add_f32 v[4:5], v[4:5], v[70:71] neg_lo:[0,1] neg_hi:[0,1]
	v_pk_add_f32 v[6:7], v[6:7], v[72:73] neg_lo:[0,1] neg_hi:[0,1]
	s_nop 0
	v_cvt_pk_f16_f32 v78, v0, v1
	v_cvt_pk_f16_f32 v79, v2, v3
	v_cvt_pk_f16_f32 v80, v4, v5
	v_cvt_pk_f16_f32 v81, v6, v7
	global_store_dwordx4 v[88:89], v[74:77], off offset:1472
	s_waitcnt vmcnt(39)
	v_mfma_f32_16x16x32_f16 a[8:11], v[74:77], a[228:231], a[8:11]
	v_mfma_f32_16x16x32_f16 a[8:11], v[78:81], a[228:231], a[8:11]
	v_mfma_f32_16x16x32_f16 a[8:11], v[74:77], a[232:235], a[8:11]
	v_mfma_f32_16x16x32_f16 a[4:7], v[74:77], a[236:239], a[4:7]
	v_mfma_f32_16x16x32_f16 a[4:7], v[78:81], a[236:239], a[4:7]
	v_mfma_f32_16x16x32_f16 a[4:7], v[74:77], a[240:243], a[4:7]
	v_mfma_f32_16x16x32_f16 a[0:3], v[74:77], a[244:247], a[0:3]
	v_mfma_f32_16x16x32_f16 a[0:3], v[78:81], a[244:247], a[0:3]
	v_mfma_f32_16x16x32_f16 a[0:3], v[74:77], a[248:251], a[0:3]
	global_load_dwordx4 a[228:231], v[90:91], off offset:1664
	global_load_dwordx4 a[232:235], v[92:93], off offset:1664
	global_load_dwordx4 a[236:239], v[94:95], off offset:1664
	global_load_dwordx4 a[240:243], v[96:97], off offset:1664
	global_load_dwordx4 a[244:247], v[98:99], off offset:1664
	global_load_dwordx4 a[248:251], v[100:101], off offset:1664
	s_waitcnt vmcnt(37)
	v_accvgpr_read_b32 v0, a16
	v_accvgpr_read_b32 v1, a17
	v_accvgpr_read_b32 v2, a18
	v_accvgpr_read_b32 v3, a19
	v_accvgpr_read_b32 v4, a20
	v_accvgpr_read_b32 v5, a21
	v_accvgpr_read_b32 v6, a22
	v_accvgpr_read_b32 v7, a23
	v_accvgpr_read_b32 v32, a80
	v_accvgpr_read_b32 v33, a81
	v_accvgpr_read_b32 v34, a82
	v_accvgpr_read_b32 v35, a83
	v_accvgpr_read_b32 v36, a84
	v_accvgpr_read_b32 v37, a85
	v_accvgpr_read_b32 v38, a86
	v_accvgpr_read_b32 v39, a87
	v_accvgpr_read_b32 v40, a88
	v_accvgpr_read_b32 v41, a89
	v_accvgpr_read_b32 v42, a90
	v_accvgpr_read_b32 v43, a91
	v_accvgpr_read_b32 v44, a92
	v_accvgpr_read_b32 v45, a93
	v_accvgpr_read_b32 v46, a94
	v_accvgpr_read_b32 v47, a95
	v_accvgpr_read_b32 v58, a96
	v_accvgpr_read_b32 v59, a97
	v_accvgpr_read_b32 v60, a98
	v_accvgpr_read_b32 v61, a99
	v_accvgpr_read_b32 v62, a100
	v_accvgpr_read_b32 v63, a101
	v_accvgpr_read_b32 v64, a102
	v_accvgpr_read_b32 v65, a103
	global_load_dwordx4 a[80:83], v[14:15], off offset:3456
	global_load_dwordx4 a[84:87], v[14:15], off offset:3472
	global_load_dwordx4 a[88:91], v[84:85], off offset:3456
	global_load_dwordx4 a[92:95], v[84:85], off offset:3472
	global_load_dwordx4 a[96:99], v[86:87], off offset:3456
	global_load_dwordx4 a[100:103], v[86:87], off offset:3472
	v_pk_mul_f32 v[0:1], v[28:29], v[0:1]
	v_pk_mul_f32 v[2:3], v[28:29], v[2:3]
	v_pk_mul_f32 v[4:5], v[28:29], v[4:5]
	v_pk_mul_f32 v[6:7], v[28:29], v[6:7]
	v_pk_mul_f32 v[0:1], v[0:1], v[32:33]
	v_pk_mul_f32 v[2:3], v[2:3], v[34:35]
	v_pk_mul_f32 v[4:5], v[4:5], v[36:37]
	v_pk_mul_f32 v[6:7], v[6:7], v[38:39]
	v_pk_add_f32 v[40:41], v[40:41], 1.0 op_sel_hi:[1,0]
	v_pk_add_f32 v[42:43], v[42:43], 1.0 op_sel_hi:[1,0]
	v_pk_add_f32 v[44:45], v[44:45], 1.0 op_sel_hi:[1,0]
	v_pk_add_f32 v[46:47], v[46:47], 1.0 op_sel_hi:[1,0]
	v_pk_fma_f32 v[0:1], v[0:1], v[40:41], v[58:59]
	v_pk_fma_f32 v[2:3], v[2:3], v[42:43], v[60:61]
	v_pk_fma_f32 v[4:5], v[4:5], v[44:45], v[62:63]
	v_pk_fma_f32 v[6:7], v[6:7], v[46:47], v[64:65]
	v_cvt_pk_f16_f32 v74, v0, v1
	v_cvt_pk_f16_f32 v75, v2, v3
	v_cvt_pk_f16_f32 v76, v4, v5
	v_cvt_pk_f16_f32 v77, v6, v7
	v_cvt_f32_f16_e32 v66, v74
	v_cvt_f32_f16_sdwa v67, v74 dst_sel:DWORD dst_unused:UNUSED_PAD src0_sel:WORD_1
	v_cvt_f32_f16_e32 v68, v75
	v_cvt_f32_f16_sdwa v69, v75 dst_sel:DWORD dst_unused:UNUSED_PAD src0_sel:WORD_1
	v_cvt_f32_f16_e32 v70, v76
	v_cvt_f32_f16_sdwa v71, v76 dst_sel:DWORD dst_unused:UNUSED_PAD src0_sel:WORD_1
	v_cvt_f32_f16_e32 v72, v77
	v_cvt_f32_f16_sdwa v73, v77 dst_sel:DWORD dst_unused:UNUSED_PAD src0_sel:WORD_1
	v_pk_add_f32 v[0:1], v[0:1], v[66:67] neg_lo:[0,1] neg_hi:[0,1]
	v_pk_add_f32 v[2:3], v[2:3], v[68:69] neg_lo:[0,1] neg_hi:[0,1]
	v_pk_add_f32 v[4:5], v[4:5], v[70:71] neg_lo:[0,1] neg_hi:[0,1]
	v_pk_add_f32 v[6:7], v[6:7], v[72:73] neg_lo:[0,1] neg_hi:[0,1]
	s_nop 0
	v_cvt_pk_f16_f32 v78, v0, v1
	v_cvt_pk_f16_f32 v79, v2, v3
	v_cvt_pk_f16_f32 v80, v4, v5
	v_cvt_pk_f16_f32 v81, v6, v7
	global_store_dwordx4 v[88:89], v[74:77], off offset:1536
	s_waitcnt vmcnt(37)
; DI f4 mfma16(h8 a, h8 b, f4 c) { return __builtin_amdgcn_mfma_f32_16x16x32_f16(a, b, c, 0, 0, 0); }
; DI void row2_phase(const Params& P, int l, int r_begin, char* smem) {
;     ...
; #pragma unroll 4
;     for (int kk = 0; kk < 32; kk++) {
;       const int k0 = kk * 32;
;       float x[8], g[8], s1[8], s0[8];
;       *(float4*)&x[0] = *(const float4*)(xm + k0); *(float4*)&x[4] = *(const float4*)(xm + k0 + 4);
;       *(float4*)&g[0] = *(const float4*)(gam + fq * 8 + k0); *(float4*)&g[4] = *(const float4*)(gam + fq * 8 + k0 + 4);
;       *(float4*)&s1[0] = *(const float4*)(sc + k0); *(float4*)&s1[4] = *(const float4*)(sc + k0 + 4);
;       *(float4*)&s0[0] = *(const float4*)(sh + k0); *(float4*)&s0[4] = *(const float4*)(sh + k0 + 4);
;       h8 hi, lo;
; #pragma unroll
;       for (int i = 0; i < 8; i++) {
;         float v = x[i] * rstd * g[i] * (1.f + s1[i]) + s0[i];
;         hi[i] = (half_t)v; lo[i] = (half_t)(v - (float)hi[i]);
;       }
;       *(h8*)(hxo + k0) = hi;
; #pragma unroll
;       for (int n3 = 0; n3 < 3; n3++) {
;         h8 bh = *(const h8*)(Whi + (size_t)(n3 * 16 + fr) * 1024 + k0 + fq * 8);
;         h8 bl = *(const h8*)(Wlo + (size_t)(n3 * 16 + fr) * 1024 + k0 + fq * 8);
;         acc[n3] = mfma16(hi, bh, acc[n3]); acc[n3] = mfma16(lo, bh, acc[n3]); acc[n3] = mfma16(hi, bl, acc[n3]);
;       }
;     }
	v_mfma_f32_16x16x32_f16 a[8:11], v[74:77], a[104:107], a[8:11]
	v_mfma_f32_16x16x32_f16 a[8:11], v[78:81], a[104:107], a[8:11]
	v_mfma_f32_16x16x32_f16 a[8:11], v[74:77], a[108:111], a[8:11]
	v_mfma_f32_16x16x32_f16 a[4:7], v[74:77], a[112:115], a[4:7]
	v_mfma_f32_16x16x32_f16 a[4:7], v[78:81], a[112:115], a[4:7]
	v_mfma_f32_16x16x32_f16 a[4:7], v[74:77], a[116:119], a[4:7]
	v_mfma_f32_16x16x32_f16 a[0:3], v[74:77], a[120:123], a[0:3]
	v_mfma_f32_16x16x32_f16 a[0:3], v[78:81], a[120:123], a[0:3]
	v_mfma_f32_16x16x32_f16 a[0:3], v[74:77], a[124:127], a[0:3]
	global_load_dwordx4 a[104:107], v[90:91], off offset:1728
	global_load_dwordx4 a[108:111], v[92:93], off offset:1728
	global_load_dwordx4 a[112:115], v[94:95], off offset:1728
	global_load_dwordx4 a[116:119], v[96:97], off offset:1728
	global_load_dwordx4 a[120:123], v[98:99], off offset:1728
	global_load_dwordx4 a[124:127], v[100:101], off offset:1728
	s_waitcnt vmcnt(35)
	v_accvgpr_read_b32 v0, a24
	v_accvgpr_read_b32 v1, a25
	v_accvgpr_read_b32 v2, a26
	v_accvgpr_read_b32 v3, a27
	v_accvgpr_read_b32 v4, a28
	v_accvgpr_read_b32 v5, a29
	v_accvgpr_read_b32 v6, a30
	v_accvgpr_read_b32 v7, a31
	v_accvgpr_read_b32 v32, a128
	v_accvgpr_read_b32 v33, a129
	v_accvgpr_read_b32 v34, a130
	v_accvgpr_read_b32 v35, a131
	v_accvgpr_read_b32 v36, a132
	v_accvgpr_read_b32 v37, a133
	v_accvgpr_read_b32 v38, a134
	v_accvgpr_read_b32 v39, a135
	v_accvgpr_read_b32 v40, a136
	v_accvgpr_read_b32 v41, a137
	v_accvgpr_read_b32 v42, a138
	v_accvgpr_read_b32 v43, a139
	v_accvgpr_read_b32 v44, a140
	v_accvgpr_read_b32 v45, a141
	v_accvgpr_read_b32 v46, a142
	v_accvgpr_read_b32 v47, a143
	v_accvgpr_read_b32 v58, a144
	v_accvgpr_read_b32 v59, a145
	v_accvgpr_read_b32 v60, a146
	v_accvgpr_read_b32 v61, a147
	v_accvgpr_read_b32 v62, a148
	v_accvgpr_read_b32 v63, a149
	v_accvgpr_read_b32 v64, a150
	v_accvgpr_read_b32 v65, a151
	global_load_dwordx4 a[128:131], v[14:15], off offset:3584
	global_load_dwordx4 a[132:135], v[14:15], off offset:3600
	global_load_dwordx4 a[136:139], v[84:85], off offset:3584
	global_load_dwordx4 a[140:143], v[84:85], off offset:3600
	global_load_dwordx4 a[144:147], v[86:87], off offset:3584
	global_load_dwordx4 a[148:151], v[86:87], off offset:3600
	v_pk_mul_f32 v[0:1], v[28:29], v[0:1]
	v_pk_mul_f32 v[2:3], v[28:29], v[2:3]
	v_pk_mul_f32 v[4:5], v[28:29], v[4:5]
	v_pk_mul_f32 v[6:7], v[28:29], v[6:7]
	v_pk_mul_f32 v[0:1], v[0:1], v[32:33]
	v_pk_mul_f32 v[2:3], v[2:3], v[34:35]
	v_pk_mul_f32 v[4:5], v[4:5], v[36:37]
	v_pk_mul_f32 v[6:7], v[6:7], v[38:39]
	v_pk_add_f32 v[40:41], v[40:41], 1.0 op_sel_hi:[1,0]
	v_pk_add_f32 v[42:43], v[42:43], 1.0 op_sel_hi:[1,0]
	v_pk_add_f32 v[44:45], v[44:45], 1.0 op_sel_hi:[1,0]
	v_pk_add_f32 v[46:47], v[46:47], 1.0 op_sel_hi:[1,0]
	v_pk_fma_f32 v[0:1], v[0:1], v[40:41], v[58:59]
	v_pk_fma_f32 v[2:3], v[2:3], v[42:43], v[60:61]
	v_pk_fma_f32 v[4:5], v[4:5], v[44:45], v[62:63]
	v_pk_fma_f32 v[6:7], v[6:7], v[46:47], v[64:65]
	v_cvt_pk_f16_f32 v74, v0, v1
	v_cvt_pk_f16_f32 v75, v2, v3
	v_cvt_pk_f16_f32 v76, v4, v5
	v_cvt_pk_f16_f32 v77, v6, v7
	v_cvt_f32_f16_e32 v66, v74
	v_cvt_f32_f16_sdwa v67, v74 dst_sel:DWORD dst_unused:UNUSED_PAD src0_sel:WORD_1
	v_cvt_f32_f16_e32 v68, v75
	v_cvt_f32_f16_sdwa v69, v75 dst_sel:DWORD dst_unused:UNUSED_PAD src0_sel:WORD_1
	v_cvt_f32_f16_e32 v70, v76
	v_cvt_f32_f16_sdwa v71, v76 dst_sel:DWORD dst_unused:UNUSED_PAD src0_sel:WORD_1
	v_cvt_f32_f16_e32 v72, v77
	v_cvt_f32_f16_sdwa v73, v77 dst_sel:DWORD dst_unused:UNUSED_PAD src0_sel:WORD_1
	v_pk_add_f32 v[0:1], v[0:1], v[66:67] neg_lo:[0,1] neg_hi:[0,1]
	v_pk_add_f32 v[2:3], v[2:3], v[68:69] neg_lo:[0,1] neg_hi:[0,1]
	v_pk_add_f32 v[4:5], v[4:5], v[70:71] neg_lo:[0,1] neg_hi:[0,1]
	v_pk_add_f32 v[6:7], v[6:7], v[72:73] neg_lo:[0,1] neg_hi:[0,1]
	s_nop 0
	v_cvt_pk_f16_f32 v78, v0, v1
	v_cvt_pk_f16_f32 v79, v2, v3
	v_cvt_pk_f16_f32 v80, v4, v5
	v_cvt_pk_f16_f32 v81, v6, v7
	global_store_dwordx4 v[88:89], v[74:77], off offset:1600
	s_waitcnt vmcnt(35)
	v_mfma_f32_16x16x32_f16 a[8:11], v[74:77], a[152:155], a[8:11]
	v_mfma_f32_16x16x32_f16 a[8:11], v[78:81], a[152:155], a[8:11]
	v_mfma_f32_16x16x32_f16 a[8:11], v[74:77], a[156:159], a[8:11]
	v_mfma_f32_16x16x32_f16 a[4:7], v[74:77], a[160:163], a[4:7]
	v_mfma_f32_16x16x32_f16 a[4:7], v[78:81], a[160:163], a[4:7]
	v_mfma_f32_16x16x32_f16 a[4:7], v[74:77], a[164:167], a[4:7]
	v_mfma_f32_16x16x32_f16 a[0:3], v[74:77], a[168:171], a[0:3]
	v_mfma_f32_16x16x32_f16 a[0:3], v[78:81], a[168:171], a[0:3]
	v_mfma_f32_16x16x32_f16 a[0:3], v[74:77], a[172:175], a[0:3]
	global_load_dwordx4 a[152:155], v[90:91], off offset:1792
	global_load_dwordx4 a[156:159], v[92:93], off offset:1792
	global_load_dwordx4 a[160:163], v[94:95], off offset:1792
	global_load_dwordx4 a[164:167], v[96:97], off offset:1792
	global_load_dwordx4 a[168:171], v[98:99], off offset:1792
	global_load_dwordx4 a[172:175], v[100:101], off offset:1792
	s_waitcnt vmcnt(33)
; DI f4 mfma16(h8 a, h8 b, f4 c) { return __builtin_amdgcn_mfma_f32_16x16x32_f16(a, b, c, 0, 0, 0); }
; DI void row2_phase(const Params& P, int l, int r_begin, char* smem) {
;     ...
; #pragma unroll 4
;     for (int kk = 0; kk < 32; kk++) {
;       const int k0 = kk * 32;
;       float x[8], g[8], s1[8], s0[8];
;       *(float4*)&x[0] = *(const float4*)(xm + k0); *(float4*)&x[4] = *(const float4*)(xm + k0 + 4);
;       *(float4*)&g[0] = *(const float4*)(gam + fq * 8 + k0); *(float4*)&g[4] = *(const float4*)(gam + fq * 8 + k0 + 4);
;       *(float4*)&s1[0] = *(const float4*)(sc + k0); *(float4*)&s1[4] = *(const float4*)(sc + k0 + 4);
;       *(float4*)&s0[0] = *(const float4*)(sh + k0); *(float4*)&s0[4] = *(const float4*)(sh + k0 + 4);
;       h8 hi, lo;
; #pragma unroll
;       for (int i = 0; i < 8; i++) {
;         float v = x[i] * rstd * g[i] * (1.f + s1[i]) + s0[i];
;         hi[i] = (half_t)v; lo[i] = (half_t)(v - (float)hi[i]);
;       }
;       *(h8*)(hxo + k0) = hi;
; #pragma unroll
;       for (int n3 = 0; n3 < 3; n3++) {
;         h8 bh = *(const h8*)(Whi + (size_t)(n3 * 16 + fr) * 1024 + k0 + fq * 8);
;         h8 bl = *(const h8*)(Wlo + (size_t)(n3 * 16 + fr) * 1024 + k0 + fq * 8);
;         acc[n3] = mfma16(hi, bh, acc[n3]); acc[n3] = mfma16(lo, bh, acc[n3]); acc[n3] = mfma16(hi, bl, acc[n3]);
;       }
;     }
	v_accvgpr_read_b32 v0, a32
	v_accvgpr_read_b32 v1, a33
	v_accvgpr_read_b32 v2, a34
	v_accvgpr_read_b32 v3, a35
	v_accvgpr_read_b32 v4, a36
	v_accvgpr_read_b32 v5, a37
	v_accvgpr_read_b32 v6, a38
	v_accvgpr_read_b32 v7, a39
	v_accvgpr_read_b32 v32, a204
	v_accvgpr_read_b32 v33, a205
	v_accvgpr_read_b32 v34, a206
	v_accvgpr_read_b32 v35, a207
	v_accvgpr_read_b32 v36, a208
	v_accvgpr_read_b32 v37, a209
	v_accvgpr_read_b32 v38, a210
	v_accvgpr_read_b32 v39, a211
	v_accvgpr_read_b32 v40, a212
	v_accvgpr_read_b32 v41, a213
	v_accvgpr_read_b32 v42, a214
	v_accvgpr_read_b32 v43, a215
	v_accvgpr_read_b32 v44, a216
	v_accvgpr_read_b32 v45, a217
	v_accvgpr_read_b32 v46, a218
	v_accvgpr_read_b32 v47, a219
	v_accvgpr_read_b32 v58, a220
	v_accvgpr_read_b32 v59, a221
	v_accvgpr_read_b32 v60, a222
	v_accvgpr_read_b32 v61, a223
	v_accvgpr_read_b32 v62, a224
	v_accvgpr_read_b32 v63, a225
	v_accvgpr_read_b32 v64, a226
	v_accvgpr_read_b32 v65, a227
	global_load_dwordx4 a[204:207], v[14:15], off offset:3712
	global_load_dwordx4 a[208:211], v[14:15], off offset:3728
	global_load_dwordx4 a[212:215], v[84:85], off offset:3712
	global_load_dwordx4 a[216:219], v[84:85], off offset:3728
	global_load_dwordx4 a[220:223], v[86:87], off offset:3712
	global_load_dwordx4 a[224:227], v[86:87], off offset:3728
	v_pk_mul_f32 v[0:1], v[28:29], v[0:1]
	v_pk_mul_f32 v[2:3], v[28:29], v[2:3]
	v_pk_mul_f32 v[4:5], v[28:29], v[4:5]
	v_pk_mul_f32 v[6:7], v[28:29], v[6:7]
	v_pk_mul_f32 v[0:1], v[0:1], v[32:33]
	v_pk_mul_f32 v[2:3], v[2:3], v[34:35]
	v_pk_mul_f32 v[4:5], v[4:5], v[36:37]
	v_pk_mul_f32 v[6:7], v[6:7], v[38:39]
	v_pk_add_f32 v[40:41], v[40:41], 1.0 op_sel_hi:[1,0]
	v_pk_add_f32 v[42:43], v[42:43], 1.0 op_sel_hi:[1,0]
	v_pk_add_f32 v[44:45], v[44:45], 1.0 op_sel_hi:[1,0]
	v_pk_add_f32 v[46:47], v[46:47], 1.0 op_sel_hi:[1,0]
	v_pk_fma_f32 v[0:1], v[0:1], v[40:41], v[58:59]
	v_pk_fma_f32 v[2:3], v[2:3], v[42:43], v[60:61]
	v_pk_fma_f32 v[4:5], v[4:5], v[44:45], v[62:63]
	v_pk_fma_f32 v[6:7], v[6:7], v[46:47], v[64:65]
	v_cvt_pk_f16_f32 v74, v0, v1
	v_cvt_pk_f16_f32 v75, v2, v3
	v_cvt_pk_f16_f32 v76, v4, v5
	v_cvt_pk_f16_f32 v77, v6, v7
	v_cvt_f32_f16_e32 v66, v74
	v_cvt_f32_f16_sdwa v67, v74 dst_sel:DWORD dst_unused:UNUSED_PAD src0_sel:WORD_1
	v_cvt_f32_f16_e32 v68, v75
	v_cvt_f32_f16_sdwa v69, v75 dst_sel:DWORD dst_unused:UNUSED_PAD src0_sel:WORD_1
	v_cvt_f32_f16_e32 v70, v76
	v_cvt_f32_f16_sdwa v71, v76 dst_sel:DWORD dst_unused:UNUSED_PAD src0_sel:WORD_1
	v_cvt_f32_f16_e32 v72, v77
	v_cvt_f32_f16_sdwa v73, v77 dst_sel:DWORD dst_unused:UNUSED_PAD src0_sel:WORD_1
	v_pk_add_f32 v[0:1], v[0:1], v[66:67] neg_lo:[0,1] neg_hi:[0,1]
	v_pk_add_f32 v[2:3], v[2:3], v[68:69] neg_lo:[0,1] neg_hi:[0,1]
	v_pk_add_f32 v[4:5], v[4:5], v[70:71] neg_lo:[0,1] neg_hi:[0,1]
	v_pk_add_f32 v[6:7], v[6:7], v[72:73] neg_lo:[0,1] neg_hi:[0,1]
	s_nop 0
	v_cvt_pk_f16_f32 v78, v0, v1
	v_cvt_pk_f16_f32 v79, v2, v3
	v_cvt_pk_f16_f32 v80, v4, v5
	v_cvt_pk_f16_f32 v81, v6, v7
	global_store_dwordx4 v[88:89], v[74:77], off offset:1664
	s_waitcnt vmcnt(33)
	v_mfma_f32_16x16x32_f16 a[8:11], v[74:77], a[228:231], a[8:11]
	v_mfma_f32_16x16x32_f16 a[8:11], v[78:81], a[228:231], a[8:11]
	v_mfma_f32_16x16x32_f16 a[8:11], v[74:77], a[232:235], a[8:11]
	v_mfma_f32_16x16x32_f16 a[4:7], v[74:77], a[236:239], a[4:7]
	v_mfma_f32_16x16x32_f16 a[4:7], v[78:81], a[236:239], a[4:7]
	v_mfma_f32_16x16x32_f16 a[4:7], v[74:77], a[240:243], a[4:7]
	v_mfma_f32_16x16x32_f16 a[0:3], v[74:77], a[244:247], a[0:3]
	v_mfma_f32_16x16x32_f16 a[0:3], v[78:81], a[244:247], a[0:3]
	v_mfma_f32_16x16x32_f16 a[0:3], v[74:77], a[248:251], a[0:3]
	global_load_dwordx4 a[228:231], v[90:91], off offset:1856
	global_load_dwordx4 a[232:235], v[92:93], off offset:1856
	global_load_dwordx4 a[236:239], v[94:95], off offset:1856
	global_load_dwordx4 a[240:243], v[96:97], off offset:1856
	global_load_dwordx4 a[244:247], v[98:99], off offset:1856
	global_load_dwordx4 a[248:251], v[100:101], off offset:1856
	s_waitcnt vmcnt(33)
	v_accvgpr_read_b32 v0, a40
	v_accvgpr_read_b32 v1, a41
	v_accvgpr_read_b32 v2, a42
	v_accvgpr_read_b32 v3, a43
	v_accvgpr_read_b32 v4, a44
	v_accvgpr_read_b32 v5, a45
	v_accvgpr_read_b32 v6, a46
	v_accvgpr_read_b32 v7, a47
	v_accvgpr_read_b32 v32, a80
	v_accvgpr_read_b32 v33, a81
	v_accvgpr_read_b32 v34, a82
	v_accvgpr_read_b32 v35, a83
	v_accvgpr_read_b32 v36, a84
	v_accvgpr_read_b32 v37, a85
	v_accvgpr_read_b32 v38, a86
	v_accvgpr_read_b32 v39, a87
	v_accvgpr_read_b32 v40, a88
	v_accvgpr_read_b32 v41, a89
	v_accvgpr_read_b32 v42, a90
	v_accvgpr_read_b32 v43, a91
	v_accvgpr_read_b32 v44, a92
	v_accvgpr_read_b32 v45, a93
	v_accvgpr_read_b32 v46, a94
	v_accvgpr_read_b32 v47, a95
	v_accvgpr_read_b32 v58, a96
	v_accvgpr_read_b32 v59, a97
	v_accvgpr_read_b32 v60, a98
	v_accvgpr_read_b32 v61, a99
	v_accvgpr_read_b32 v62, a100
	v_accvgpr_read_b32 v63, a101
	v_accvgpr_read_b32 v64, a102
	v_accvgpr_read_b32 v65, a103
	global_load_dwordx4 a[80:83], v[14:15], off offset:3840
	global_load_dwordx4 a[84:87], v[14:15], off offset:3856
	global_load_dwordx4 a[88:91], v[84:85], off offset:3840
	global_load_dwordx4 a[92:95], v[84:85], off offset:3856
	global_load_dwordx4 a[96:99], v[86:87], off offset:3840
	global_load_dwordx4 a[100:103], v[86:87], off offset:3856
	v_pk_mul_f32 v[0:1], v[28:29], v[0:1]
	v_pk_mul_f32 v[2:3], v[28:29], v[2:3]
	v_pk_mul_f32 v[4:5], v[28:29], v[4:5]
	v_pk_mul_f32 v[6:7], v[28:29], v[6:7]
	v_pk_mul_f32 v[0:1], v[0:1], v[32:33]
	v_pk_mul_f32 v[2:3], v[2:3], v[34:35]
	v_pk_mul_f32 v[4:5], v[4:5], v[36:37]
	v_pk_mul_f32 v[6:7], v[6:7], v[38:39]
	v_pk_add_f32 v[40:41], v[40:41], 1.0 op_sel_hi:[1,0]
	v_pk_add_f32 v[42:43], v[42:43], 1.0 op_sel_hi:[1,0]
	v_pk_add_f32 v[44:45], v[44:45], 1.0 op_sel_hi:[1,0]
	v_pk_add_f32 v[46:47], v[46:47], 1.0 op_sel_hi:[1,0]
	v_pk_fma_f32 v[0:1], v[0:1], v[40:41], v[58:59]
	v_pk_fma_f32 v[2:3], v[2:3], v[42:43], v[60:61]
	v_pk_fma_f32 v[4:5], v[4:5], v[44:45], v[62:63]
	v_pk_fma_f32 v[6:7], v[6:7], v[46:47], v[64:65]
	v_cvt_pk_f16_f32 v74, v0, v1
	v_cvt_pk_f16_f32 v75, v2, v3
	v_cvt_pk_f16_f32 v76, v4, v5
	v_cvt_pk_f16_f32 v77, v6, v7
	v_cvt_f32_f16_e32 v66, v74
	v_cvt_f32_f16_sdwa v67, v74 dst_sel:DWORD dst_unused:UNUSED_PAD src0_sel:WORD_1
	v_cvt_f32_f16_e32 v68, v75
	v_cvt_f32_f16_sdwa v69, v75 dst_sel:DWORD dst_unused:UNUSED_PAD src0_sel:WORD_1
	v_cvt_f32_f16_e32 v70, v76
	v_cvt_f32_f16_sdwa v71, v76 dst_sel:DWORD dst_unused:UNUSED_PAD src0_sel:WORD_1
	v_cvt_f32_f16_e32 v72, v77
	v_cvt_f32_f16_sdwa v73, v77 dst_sel:DWORD dst_unused:UNUSED_PAD src0_sel:WORD_1
	v_pk_add_f32 v[0:1], v[0:1], v[66:67] neg_lo:[0,1] neg_hi:[0,1]
	v_pk_add_f32 v[2:3], v[2:3], v[68:69] neg_lo:[0,1] neg_hi:[0,1]
	v_pk_add_f32 v[4:5], v[4:5], v[70:71] neg_lo:[0,1] neg_hi:[0,1]
	v_pk_add_f32 v[6:7], v[6:7], v[72:73] neg_lo:[0,1] neg_hi:[0,1]
	s_nop 0
	v_cvt_pk_f16_f32 v78, v0, v1
	v_cvt_pk_f16_f32 v79, v2, v3
	v_cvt_pk_f16_f32 v80, v4, v5
	v_cvt_pk_f16_f32 v81, v6, v7
	global_store_dwordx4 v[88:89], v[74:77], off offset:1728
	s_waitcnt vmcnt(33)
; DI f4 mfma16(h8 a, h8 b, f4 c) { return __builtin_amdgcn_mfma_f32_16x16x32_f16(a, b, c, 0, 0, 0); }
; DI void row2_phase(const Params& P, int l, int r_begin, char* smem) {
;     ...
; #pragma unroll 4
;     for (int kk = 0; kk < 32; kk++) {
;       const int k0 = kk * 32;
;       float x[8], g[8], s1[8], s0[8];
;       *(float4*)&x[0] = *(const float4*)(xm + k0); *(float4*)&x[4] = *(const float4*)(xm + k0 + 4);
;       *(float4*)&g[0] = *(const float4*)(gam + fq * 8 + k0); *(float4*)&g[4] = *(const float4*)(gam + fq * 8 + k0 + 4);
;       *(float4*)&s1[0] = *(const float4*)(sc + k0); *(float4*)&s1[4] = *(const float4*)(sc + k0 + 4);
;       *(float4*)&s0[0] = *(const float4*)(sh + k0); *(float4*)&s0[4] = *(const float4*)(sh + k0 + 4);
;       h8 hi, lo;
; #pragma unroll
;       for (int i = 0; i < 8; i++) {
;         float v = x[i] * rstd * g[i] * (1.f + s1[i]) + s0[i];
;         hi[i] = (half_t)v; lo[i] = (half_t)(v - (float)hi[i]);
;       }
;       *(h8*)(hxo + k0) = hi;
; #pragma unroll
;       for (int n3 = 0; n3 < 3; n3++) {
;         h8 bh = *(const h8*)(Whi + (size_t)(n3 * 16 + fr) * 1024 + k0 + fq * 8);
;         h8 bl = *(const h8*)(Wlo + (size_t)(n3 * 16 + fr) * 1024 + k0 + fq * 8);
;         acc[n3] = mfma16(hi, bh, acc[n3]); acc[n3] = mfma16(lo, bh, acc[n3]); acc[n3] = mfma16(hi, bl, acc[n3]);
;       }
;     }
	v_mfma_f32_16x16x32_f16 a[8:11], v[74:77], a[104:107], a[8:11]
	v_mfma_f32_16x16x32_f16 a[8:11], v[78:81], a[104:107], a[8:11]
	v_mfma_f32_16x16x32_f16 a[8:11], v[74:77], a[108:111], a[8:11]
	v_mfma_f32_16x16x32_f16 a[4:7], v[74:77], a[112:115], a[4:7]
	v_mfma_f32_16x16x32_f16 a[4:7], v[78:81], a[112:115], a[4:7]
	v_mfma_f32_16x16x32_f16 a[4:7], v[74:77], a[116:119], a[4:7]
	v_mfma_f32_16x16x32_f16 a[0:3], v[74:77], a[120:123], a[0:3]
	v_mfma_f32_16x16x32_f16 a[0:3], v[78:81], a[120:123], a[0:3]
	v_mfma_f32_16x16x32_f16 a[0:3], v[74:77], a[124:127], a[0:3]
	global_load_dwordx4 a[104:107], v[90:91], off offset:1920
	global_load_dwordx4 a[108:111], v[92:93], off offset:1920
	global_load_dwordx4 a[112:115], v[94:95], off offset:1920
	global_load_dwordx4 a[116:119], v[96:97], off offset:1920
	global_load_dwordx4 a[120:123], v[98:99], off offset:1920
	global_load_dwordx4 a[124:127], v[100:101], off offset:1920
	s_waitcnt vmcnt(33)
	v_accvgpr_read_b32 v0, a48
	v_accvgpr_read_b32 v1, a49
	v_accvgpr_read_b32 v2, a50
	v_accvgpr_read_b32 v3, a51
	v_accvgpr_read_b32 v4, a52
	v_accvgpr_read_b32 v5, a53
	v_accvgpr_read_b32 v6, a54
	v_accvgpr_read_b32 v7, a55
	v_accvgpr_read_b32 v32, a128
	v_accvgpr_read_b32 v33, a129
	v_accvgpr_read_b32 v34, a130
	v_accvgpr_read_b32 v35, a131
	v_accvgpr_read_b32 v36, a132
	v_accvgpr_read_b32 v37, a133
	v_accvgpr_read_b32 v38, a134
	v_accvgpr_read_b32 v39, a135
	v_accvgpr_read_b32 v40, a136
	v_accvgpr_read_b32 v41, a137
	v_accvgpr_read_b32 v42, a138
	v_accvgpr_read_b32 v43, a139
	v_accvgpr_read_b32 v44, a140
	v_accvgpr_read_b32 v45, a141
	v_accvgpr_read_b32 v46, a142
	v_accvgpr_read_b32 v47, a143
	v_accvgpr_read_b32 v58, a144
	v_accvgpr_read_b32 v59, a145
	v_accvgpr_read_b32 v60, a146
	v_accvgpr_read_b32 v61, a147
	v_accvgpr_read_b32 v62, a148
	v_accvgpr_read_b32 v63, a149
	v_accvgpr_read_b32 v64, a150
	v_accvgpr_read_b32 v65, a151
	global_load_dwordx4 a[128:131], v[14:15], off offset:3968
	global_load_dwordx4 a[132:135], v[14:15], off offset:3984
	global_load_dwordx4 a[136:139], v[84:85], off offset:3968
	global_load_dwordx4 a[140:143], v[84:85], off offset:3984
	global_load_dwordx4 a[144:147], v[86:87], off offset:3968
	global_load_dwordx4 a[148:151], v[86:87], off offset:3984
	v_pk_mul_f32 v[0:1], v[28:29], v[0:1]
	v_pk_mul_f32 v[2:3], v[28:29], v[2:3]
	v_pk_mul_f32 v[4:5], v[28:29], v[4:5]
	v_pk_mul_f32 v[6:7], v[28:29], v[6:7]
	v_pk_mul_f32 v[0:1], v[0:1], v[32:33]
	v_pk_mul_f32 v[2:3], v[2:3], v[34:35]
	v_pk_mul_f32 v[4:5], v[4:5], v[36:37]
	v_pk_mul_f32 v[6:7], v[6:7], v[38:39]
	v_pk_add_f32 v[40:41], v[40:41], 1.0 op_sel_hi:[1,0]
	v_pk_add_f32 v[42:43], v[42:43], 1.0 op_sel_hi:[1,0]
	v_pk_add_f32 v[44:45], v[44:45], 1.0 op_sel_hi:[1,0]
	v_pk_add_f32 v[46:47], v[46:47], 1.0 op_sel_hi:[1,0]
	v_pk_fma_f32 v[0:1], v[0:1], v[40:41], v[58:59]
	v_pk_fma_f32 v[2:3], v[2:3], v[42:43], v[60:61]
	v_pk_fma_f32 v[4:5], v[4:5], v[44:45], v[62:63]
	v_pk_fma_f32 v[6:7], v[6:7], v[46:47], v[64:65]
	v_cvt_pk_f16_f32 v74, v0, v1
	v_cvt_pk_f16_f32 v75, v2, v3
	v_cvt_pk_f16_f32 v76, v4, v5
	v_cvt_pk_f16_f32 v77, v6, v7
	v_cvt_f32_f16_e32 v66, v74
	v_cvt_f32_f16_sdwa v67, v74 dst_sel:DWORD dst_unused:UNUSED_PAD src0_sel:WORD_1
	v_cvt_f32_f16_e32 v68, v75
	v_cvt_f32_f16_sdwa v69, v75 dst_sel:DWORD dst_unused:UNUSED_PAD src0_sel:WORD_1
	v_cvt_f32_f16_e32 v70, v76
	v_cvt_f32_f16_sdwa v71, v76 dst_sel:DWORD dst_unused:UNUSED_PAD src0_sel:WORD_1
	v_cvt_f32_f16_e32 v72, v77
	v_cvt_f32_f16_sdwa v73, v77 dst_sel:DWORD dst_unused:UNUSED_PAD src0_sel:WORD_1
	v_pk_add_f32 v[0:1], v[0:1], v[66:67] neg_lo:[0,1] neg_hi:[0,1]
	v_pk_add_f32 v[2:3], v[2:3], v[68:69] neg_lo:[0,1] neg_hi:[0,1]
	v_pk_add_f32 v[4:5], v[4:5], v[70:71] neg_lo:[0,1] neg_hi:[0,1]
	v_pk_add_f32 v[6:7], v[6:7], v[72:73] neg_lo:[0,1] neg_hi:[0,1]
	s_nop 0
	v_cvt_pk_f16_f32 v78, v0, v1
	v_cvt_pk_f16_f32 v79, v2, v3
	v_cvt_pk_f16_f32 v80, v4, v5
	v_cvt_pk_f16_f32 v81, v6, v7
	global_store_dwordx4 v[88:89], v[74:77], off offset:1792
	s_waitcnt vmcnt(33)
	v_mfma_f32_16x16x32_f16 a[8:11], v[74:77], a[152:155], a[8:11]
	v_mfma_f32_16x16x32_f16 a[8:11], v[78:81], a[152:155], a[8:11]
	v_mfma_f32_16x16x32_f16 a[8:11], v[74:77], a[156:159], a[8:11]
	v_mfma_f32_16x16x32_f16 a[4:7], v[74:77], a[160:163], a[4:7]
	v_mfma_f32_16x16x32_f16 a[4:7], v[78:81], a[160:163], a[4:7]
	v_mfma_f32_16x16x32_f16 a[4:7], v[74:77], a[164:167], a[4:7]
	v_mfma_f32_16x16x32_f16 a[0:3], v[74:77], a[168:171], a[0:3]
	v_mfma_f32_16x16x32_f16 a[0:3], v[78:81], a[168:171], a[0:3]
	v_mfma_f32_16x16x32_f16 a[0:3], v[74:77], a[172:175], a[0:3]
	global_load_dwordx4 a[152:155], v[90:91], off offset:1984
	global_load_dwordx4 a[156:159], v[92:93], off offset:1984
	global_load_dwordx4 a[160:163], v[94:95], off offset:1984
	global_load_dwordx4 a[164:167], v[96:97], off offset:1984
	global_load_dwordx4 a[168:171], v[98:99], off offset:1984
	global_load_dwordx4 a[172:175], v[100:101], off offset:1984
	s_waitcnt vmcnt(33)
; DI f4 mfma16(h8 a, h8 b, f4 c) { return __builtin_amdgcn_mfma_f32_16x16x32_f16(a, b, c, 0, 0, 0); }
; DI void row2_phase(const Params& P, int l, int r_begin, char* smem) {
;     ...
; #pragma unroll 4
;     for (int kk = 0; kk < 32; kk++) {
;       const int k0 = kk * 32;
;       float x[8], g[8], s1[8], s0[8];
;       *(float4*)&x[0] = *(const float4*)(xm + k0); *(float4*)&x[4] = *(const float4*)(xm + k0 + 4);
;       *(float4*)&g[0] = *(const float4*)(gam + fq * 8 + k0); *(float4*)&g[4] = *(const float4*)(gam + fq * 8 + k0 + 4);
;       *(float4*)&s1[0] = *(const float4*)(sc + k0); *(float4*)&s1[4] = *(const float4*)(sc + k0 + 4);
;       *(float4*)&s0[0] = *(const float4*)(sh + k0); *(float4*)&s0[4] = *(const float4*)(sh + k0 + 4);
;       h8 hi, lo;
; #pragma unroll
;       for (int i = 0; i < 8; i++) {
;         float v = x[i] * rstd * g[i] * (1.f + s1[i]) + s0[i];
;         hi[i] = (half_t)v; lo[i] = (half_t)(v - (float)hi[i]);
;       }
;       *(h8*)(hxo + k0) = hi;
; #pragma unroll
;       for (int n3 = 0; n3 < 3; n3++) {
;         h8 bh = *(const h8*)(Whi + (size_t)(n3 * 16 + fr) * 1024 + k0 + fq * 8);
;         h8 bl = *(const h8*)(Wlo + (size_t)(n3 * 16 + fr) * 1024 + k0 + fq * 8);
;         acc[n3] = mfma16(hi, bh, acc[n3]); acc[n3] = mfma16(lo, bh, acc[n3]); acc[n3] = mfma16(hi, bl, acc[n3]);
;       }
;     }
	v_accvgpr_read_b32 v0, a56
	v_accvgpr_read_b32 v1, a57
	v_accvgpr_read_b32 v2, a58
	v_accvgpr_read_b32 v3, a59
	v_accvgpr_read_b32 v4, a60
	v_accvgpr_read_b32 v5, a61
	v_accvgpr_read_b32 v6, a62
	v_accvgpr_read_b32 v7, a63
	v_accvgpr_read_b32 v32, a204
	v_accvgpr_read_b32 v33, a205
	v_accvgpr_read_b32 v34, a206
	v_accvgpr_read_b32 v35, a207
	v_accvgpr_read_b32 v36, a208
	v_accvgpr_read_b32 v37, a209
	v_accvgpr_read_b32 v38, a210
	v_accvgpr_read_b32 v39, a211
	v_accvgpr_read_b32 v40, a212
	v_accvgpr_read_b32 v41, a213
	v_accvgpr_read_b32 v42, a214
	v_accvgpr_read_b32 v43, a215
	v_accvgpr_read_b32 v44, a216
	v_accvgpr_read_b32 v45, a217
	v_accvgpr_read_b32 v46, a218
	v_accvgpr_read_b32 v47, a219
	v_accvgpr_read_b32 v58, a220
	v_accvgpr_read_b32 v59, a221
	v_accvgpr_read_b32 v60, a222
	v_accvgpr_read_b32 v61, a223
	v_accvgpr_read_b32 v62, a224
	v_accvgpr_read_b32 v63, a225
	v_accvgpr_read_b32 v64, a226
	v_accvgpr_read_b32 v65, a227
	v_pk_mul_f32 v[0:1], v[28:29], v[0:1]
	v_pk_mul_f32 v[2:3], v[28:29], v[2:3]
	v_pk_mul_f32 v[4:5], v[28:29], v[4:5]
	v_pk_mul_f32 v[6:7], v[28:29], v[6:7]
	v_pk_mul_f32 v[0:1], v[0:1], v[32:33]
	v_pk_mul_f32 v[2:3], v[2:3], v[34:35]
	v_pk_mul_f32 v[4:5], v[4:5], v[36:37]
	v_pk_mul_f32 v[6:7], v[6:7], v[38:39]
	v_pk_add_f32 v[40:41], v[40:41], 1.0 op_sel_hi:[1,0]
	v_pk_add_f32 v[42:43], v[42:43], 1.0 op_sel_hi:[1,0]
	v_pk_add_f32 v[44:45], v[44:45], 1.0 op_sel_hi:[1,0]
	v_pk_add_f32 v[46:47], v[46:47], 1.0 op_sel_hi:[1,0]
	v_pk_fma_f32 v[0:1], v[0:1], v[40:41], v[58:59]
	v_pk_fma_f32 v[2:3], v[2:3], v[42:43], v[60:61]
	v_pk_fma_f32 v[4:5], v[4:5], v[44:45], v[62:63]
	v_pk_fma_f32 v[6:7], v[6:7], v[46:47], v[64:65]
	v_cvt_pk_f16_f32 v74, v0, v1
	v_cvt_pk_f16_f32 v75, v2, v3
	v_cvt_pk_f16_f32 v76, v4, v5
	v_cvt_pk_f16_f32 v77, v6, v7
	v_cvt_f32_f16_e32 v66, v74
	v_cvt_f32_f16_sdwa v67, v74 dst_sel:DWORD dst_unused:UNUSED_PAD src0_sel:WORD_1
	v_cvt_f32_f16_e32 v68, v75
	v_cvt_f32_f16_sdwa v69, v75 dst_sel:DWORD dst_unused:UNUSED_PAD src0_sel:WORD_1
	v_cvt_f32_f16_e32 v70, v76
	v_cvt_f32_f16_sdwa v71, v76 dst_sel:DWORD dst_unused:UNUSED_PAD src0_sel:WORD_1
	v_cvt_f32_f16_e32 v72, v77
	v_cvt_f32_f16_sdwa v73, v77 dst_sel:DWORD dst_unused:UNUSED_PAD src0_sel:WORD_1
	v_pk_add_f32 v[0:1], v[0:1], v[66:67] neg_lo:[0,1] neg_hi:[0,1]
	v_pk_add_f32 v[2:3], v[2:3], v[68:69] neg_lo:[0,1] neg_hi:[0,1]
	v_pk_add_f32 v[4:5], v[4:5], v[70:71] neg_lo:[0,1] neg_hi:[0,1]
	v_pk_add_f32 v[6:7], v[6:7], v[72:73] neg_lo:[0,1] neg_hi:[0,1]
	s_nop 0
	v_cvt_pk_f16_f32 v78, v0, v1
	v_cvt_pk_f16_f32 v79, v2, v3
	v_cvt_pk_f16_f32 v80, v4, v5
	v_cvt_pk_f16_f32 v81, v6, v7
	global_store_dwordx4 v[88:89], v[74:77], off offset:1856
	s_waitcnt vmcnt(27)
	v_mfma_f32_16x16x32_f16 a[8:11], v[74:77], a[228:231], a[8:11]
	v_mfma_f32_16x16x32_f16 a[8:11], v[78:81], a[228:231], a[8:11]
	v_mfma_f32_16x16x32_f16 a[8:11], v[74:77], a[232:235], a[8:11]
	v_mfma_f32_16x16x32_f16 a[4:7], v[74:77], a[236:239], a[4:7]
	v_mfma_f32_16x16x32_f16 a[4:7], v[78:81], a[236:239], a[4:7]
	v_mfma_f32_16x16x32_f16 a[4:7], v[74:77], a[240:243], a[4:7]
	v_mfma_f32_16x16x32_f16 a[0:3], v[74:77], a[244:247], a[0:3]
	v_mfma_f32_16x16x32_f16 a[0:3], v[78:81], a[244:247], a[0:3]
	v_mfma_f32_16x16x32_f16 a[0:3], v[74:77], a[248:251], a[0:3]
	s_waitcnt vmcnt(21)
	v_accvgpr_read_b32 v0, a64
	v_accvgpr_read_b32 v1, a65
	v_accvgpr_read_b32 v2, a66
	v_accvgpr_read_b32 v3, a67
	v_accvgpr_read_b32 v4, a68
	v_accvgpr_read_b32 v5, a69
	v_accvgpr_read_b32 v6, a70
	v_accvgpr_read_b32 v7, a71
	v_accvgpr_read_b32 v32, a80
	v_accvgpr_read_b32 v33, a81
	v_accvgpr_read_b32 v34, a82
	v_accvgpr_read_b32 v35, a83
	v_accvgpr_read_b32 v36, a84
	v_accvgpr_read_b32 v37, a85
	v_accvgpr_read_b32 v38, a86
	v_accvgpr_read_b32 v39, a87
	v_accvgpr_read_b32 v40, a88
	v_accvgpr_read_b32 v41, a89
	v_accvgpr_read_b32 v42, a90
	v_accvgpr_read_b32 v43, a91
	v_accvgpr_read_b32 v44, a92
	v_accvgpr_read_b32 v45, a93
	v_accvgpr_read_b32 v46, a94
	v_accvgpr_read_b32 v47, a95
	v_accvgpr_read_b32 v58, a96
	v_accvgpr_read_b32 v59, a97
	v_accvgpr_read_b32 v60, a98
	v_accvgpr_read_b32 v61, a99
	v_accvgpr_read_b32 v62, a100
	v_accvgpr_read_b32 v63, a101
	v_accvgpr_read_b32 v64, a102
	v_accvgpr_read_b32 v65, a103
	v_pk_mul_f32 v[0:1], v[28:29], v[0:1]
	v_pk_mul_f32 v[2:3], v[28:29], v[2:3]
	v_pk_mul_f32 v[4:5], v[28:29], v[4:5]
	v_pk_mul_f32 v[6:7], v[28:29], v[6:7]
	v_pk_mul_f32 v[0:1], v[0:1], v[32:33]
	v_pk_mul_f32 v[2:3], v[2:3], v[34:35]
	v_pk_mul_f32 v[4:5], v[4:5], v[36:37]
	v_pk_mul_f32 v[6:7], v[6:7], v[38:39]
	v_pk_add_f32 v[40:41], v[40:41], 1.0 op_sel_hi:[1,0]
	v_pk_add_f32 v[42:43], v[42:43], 1.0 op_sel_hi:[1,0]
	v_pk_add_f32 v[44:45], v[44:45], 1.0 op_sel_hi:[1,0]
	v_pk_add_f32 v[46:47], v[46:47], 1.0 op_sel_hi:[1,0]
	v_pk_fma_f32 v[0:1], v[0:1], v[40:41], v[58:59]
	v_pk_fma_f32 v[2:3], v[2:3], v[42:43], v[60:61]
	v_pk_fma_f32 v[4:5], v[4:5], v[44:45], v[62:63]
	v_pk_fma_f32 v[6:7], v[6:7], v[46:47], v[64:65]
	v_cvt_pk_f16_f32 v74, v0, v1
	v_cvt_pk_f16_f32 v75, v2, v3
	v_cvt_pk_f16_f32 v76, v4, v5
	v_cvt_pk_f16_f32 v77, v6, v7
	v_cvt_f32_f16_e32 v66, v74
	v_cvt_f32_f16_sdwa v67, v74 dst_sel:DWORD dst_unused:UNUSED_PAD src0_sel:WORD_1
	v_cvt_f32_f16_e32 v68, v75
	v_cvt_f32_f16_sdwa v69, v75 dst_sel:DWORD dst_unused:UNUSED_PAD src0_sel:WORD_1
	v_cvt_f32_f16_e32 v70, v76
	v_cvt_f32_f16_sdwa v71, v76 dst_sel:DWORD dst_unused:UNUSED_PAD src0_sel:WORD_1
	v_cvt_f32_f16_e32 v72, v77
	v_cvt_f32_f16_sdwa v73, v77 dst_sel:DWORD dst_unused:UNUSED_PAD src0_sel:WORD_1
	v_pk_add_f32 v[0:1], v[0:1], v[66:67] neg_lo:[0,1] neg_hi:[0,1]
	v_pk_add_f32 v[2:3], v[2:3], v[68:69] neg_lo:[0,1] neg_hi:[0,1]
	v_pk_add_f32 v[4:5], v[4:5], v[70:71] neg_lo:[0,1] neg_hi:[0,1]
	v_pk_add_f32 v[6:7], v[6:7], v[72:73] neg_lo:[0,1] neg_hi:[0,1]
	s_nop 0
	v_cvt_pk_f16_f32 v78, v0, v1
	v_cvt_pk_f16_f32 v79, v2, v3
	v_cvt_pk_f16_f32 v80, v4, v5
	v_cvt_pk_f16_f32 v81, v6, v7
	global_store_dwordx4 v[88:89], v[74:77], off offset:1920
	s_waitcnt vmcnt(15)
; DI f4 mfma16(h8 a, h8 b, f4 c) { return __builtin_amdgcn_mfma_f32_16x16x32_f16(a, b, c, 0, 0, 0); }
; DI void row2_phase(const Params& P, int l, int r_begin, char* smem) {
;     ...
; #pragma unroll 4
;     for (int kk = 0; kk < 32; kk++) {
;       const int k0 = kk * 32;
;       float x[8], g[8], s1[8], s0[8];
;       *(float4*)&x[0] = *(const float4*)(xm + k0); *(float4*)&x[4] = *(const float4*)(xm + k0 + 4);
;       *(float4*)&g[0] = *(const float4*)(gam + fq * 8 + k0); *(float4*)&g[4] = *(const float4*)(gam + fq * 8 + k0 + 4);
;       *(float4*)&s1[0] = *(const float4*)(sc + k0); *(float4*)&s1[4] = *(const float4*)(sc + k0 + 4);
;       *(float4*)&s0[0] = *(const float4*)(sh + k0); *(float4*)&s0[4] = *(const float4*)(sh + k0 + 4);
;       h8 hi, lo;
; #pragma unroll
;       for (int i = 0; i < 8; i++) {
;         float v = x[i] * rstd * g[i] * (1.f + s1[i]) + s0[i];
;         hi[i] = (half_t)v; lo[i] = (half_t)(v - (float)hi[i]);
;       }
;       *(h8*)(hxo + k0) = hi;
; #pragma unroll
;       for (int n3 = 0; n3 < 3; n3++) {
;         h8 bh = *(const h8*)(Whi + (size_t)(n3 * 16 + fr) * 1024 + k0 + fq * 8);
;         h8 bl = *(const h8*)(Wlo + (size_t)(n3 * 16 + fr) * 1024 + k0 + fq * 8);
;         acc[n3] = mfma16(hi, bh, acc[n3]); acc[n3] = mfma16(lo, bh, acc[n3]); acc[n3] = mfma16(hi, bl, acc[n3]);
;       }
;     }
;     __builtin_amdgcn_wave_barrier();
; #pragma unroll
;     for (int n3 = 0; n3 < 3; n3++)
; #pragma unroll
;       for (int j = 0; j < 4; j++) lg[(fq * 4 + j) * 48 + n3 * 16 + fr] = acc[n3][j];
;     __builtin_amdgcn_wave_barrier();
	v_mfma_f32_16x16x32_f16 a[8:11], v[74:77], a[104:107], a[8:11]
	v_mfma_f32_16x16x32_f16 a[8:11], v[78:81], a[104:107], a[8:11]
	v_mfma_f32_16x16x32_f16 a[8:11], v[74:77], a[108:111], a[8:11]
	v_mfma_f32_16x16x32_f16 a[4:7], v[74:77], a[112:115], a[4:7]
	v_mfma_f32_16x16x32_f16 a[4:7], v[78:81], a[112:115], a[4:7]
	v_mfma_f32_16x16x32_f16 a[4:7], v[74:77], a[116:119], a[4:7]
	v_mfma_f32_16x16x32_f16 a[0:3], v[74:77], a[120:123], a[0:3]
	v_mfma_f32_16x16x32_f16 a[0:3], v[78:81], a[120:123], a[0:3]
	v_mfma_f32_16x16x32_f16 a[0:3], v[74:77], a[124:127], a[0:3]
	s_waitcnt vmcnt(9)
	v_accvgpr_read_b32 v0, a72
	v_accvgpr_read_b32 v1, a73
	v_accvgpr_read_b32 v2, a74
	v_accvgpr_read_b32 v3, a75
	v_accvgpr_read_b32 v4, a76
	v_accvgpr_read_b32 v5, a77
	v_accvgpr_read_b32 v6, a78
	v_accvgpr_read_b32 v7, a79
	v_accvgpr_read_b32 v32, a128
	v_accvgpr_read_b32 v33, a129
	v_accvgpr_read_b32 v34, a130
	v_accvgpr_read_b32 v35, a131
	v_accvgpr_read_b32 v36, a132
	v_accvgpr_read_b32 v37, a133
	v_accvgpr_read_b32 v38, a134
	v_accvgpr_read_b32 v39, a135
	v_accvgpr_read_b32 v40, a136
	v_accvgpr_read_b32 v41, a137
	v_accvgpr_read_b32 v42, a138
	v_accvgpr_read_b32 v43, a139
	v_accvgpr_read_b32 v44, a140
	v_accvgpr_read_b32 v45, a141
	v_accvgpr_read_b32 v46, a142
	v_accvgpr_read_b32 v47, a143
	v_accvgpr_read_b32 v58, a144
	v_accvgpr_read_b32 v59, a145
	v_accvgpr_read_b32 v60, a146
	v_accvgpr_read_b32 v61, a147
	v_accvgpr_read_b32 v62, a148
	v_accvgpr_read_b32 v63, a149
	v_accvgpr_read_b32 v64, a150
	v_accvgpr_read_b32 v65, a151
	v_pk_mul_f32 v[0:1], v[28:29], v[0:1]
	v_pk_mul_f32 v[2:3], v[28:29], v[2:3]
	v_pk_mul_f32 v[4:5], v[28:29], v[4:5]
	v_pk_mul_f32 v[6:7], v[28:29], v[6:7]
	v_pk_mul_f32 v[0:1], v[0:1], v[32:33]
	v_pk_mul_f32 v[2:3], v[2:3], v[34:35]
	v_pk_mul_f32 v[4:5], v[4:5], v[36:37]
	v_pk_mul_f32 v[6:7], v[6:7], v[38:39]
	v_pk_add_f32 v[40:41], v[40:41], 1.0 op_sel_hi:[1,0]
	v_pk_add_f32 v[42:43], v[42:43], 1.0 op_sel_hi:[1,0]
	v_pk_add_f32 v[44:45], v[44:45], 1.0 op_sel_hi:[1,0]
	v_pk_add_f32 v[46:47], v[46:47], 1.0 op_sel_hi:[1,0]
	v_pk_fma_f32 v[0:1], v[0:1], v[40:41], v[58:59]
	v_pk_fma_f32 v[2:3], v[2:3], v[42:43], v[60:61]
	v_pk_fma_f32 v[4:5], v[4:5], v[44:45], v[62:63]
	v_pk_fma_f32 v[6:7], v[6:7], v[46:47], v[64:65]
	v_cvt_pk_f16_f32 v74, v0, v1
	v_cvt_pk_f16_f32 v75, v2, v3
	v_cvt_pk_f16_f32 v76, v4, v5
	v_cvt_pk_f16_f32 v77, v6, v7
	v_cvt_f32_f16_e32 v66, v74
	v_cvt_f32_f16_sdwa v67, v74 dst_sel:DWORD dst_unused:UNUSED_PAD src0_sel:WORD_1
	v_cvt_f32_f16_e32 v68, v75
	v_cvt_f32_f16_sdwa v69, v75 dst_sel:DWORD dst_unused:UNUSED_PAD src0_sel:WORD_1
	v_cvt_f32_f16_e32 v70, v76
	v_cvt_f32_f16_sdwa v71, v76 dst_sel:DWORD dst_unused:UNUSED_PAD src0_sel:WORD_1
	v_cvt_f32_f16_e32 v72, v77
	v_cvt_f32_f16_sdwa v73, v77 dst_sel:DWORD dst_unused:UNUSED_PAD src0_sel:WORD_1
	v_pk_add_f32 v[0:1], v[0:1], v[66:67] neg_lo:[0,1] neg_hi:[0,1]
	v_pk_add_f32 v[2:3], v[2:3], v[68:69] neg_lo:[0,1] neg_hi:[0,1]
	v_pk_add_f32 v[4:5], v[4:5], v[70:71] neg_lo:[0,1] neg_hi:[0,1]
	v_pk_add_f32 v[6:7], v[6:7], v[72:73] neg_lo:[0,1] neg_hi:[0,1]
	s_nop 0
	v_cvt_pk_f16_f32 v78, v0, v1
	v_cvt_pk_f16_f32 v79, v2, v3
	v_cvt_pk_f16_f32 v80, v4, v5
	v_cvt_pk_f16_f32 v81, v6, v7
	global_store_dwordx4 v[88:89], v[74:77], off offset:1984
	s_waitcnt vmcnt(3)
	v_mfma_f32_16x16x32_f16 a[8:11], v[74:77], a[152:155], a[8:11]
	v_mfma_f32_16x16x32_f16 a[8:11], v[78:81], a[152:155], a[8:11]
	v_mfma_f32_16x16x32_f16 a[8:11], v[74:77], a[156:159], a[8:11]
	v_mfma_f32_16x16x32_f16 a[4:7], v[74:77], a[160:163], a[4:7]
	v_mfma_f32_16x16x32_f16 a[4:7], v[78:81], a[160:163], a[4:7]
	v_mfma_f32_16x16x32_f16 a[4:7], v[74:77], a[164:167], a[4:7]
	v_mfma_f32_16x16x32_f16 a[0:3], v[74:77], a[168:171], a[0:3]
	v_mfma_f32_16x16x32_f16 a[0:3], v[78:81], a[168:171], a[0:3]
	v_mfma_f32_16x16x32_f16 a[0:3], v[74:77], a[172:175], a[0:3]
	s_nop 7
	s_nop 6
	v_accvgpr_read_b32 v0, a0
	v_accvgpr_read_b32 v4, a4
	v_accvgpr_read_b32 v8, a8
	v_accvgpr_read_b32 v1, a1
	v_accvgpr_read_b32 v2, a2
	v_accvgpr_read_b32 v3, a3
	v_accvgpr_read_b32 v5, a5
	v_accvgpr_read_b32 v6, a6
	v_accvgpr_read_b32 v7, a7
	v_accvgpr_read_b32 v9, a9
	v_accvgpr_read_b32 v10, a10
	v_accvgpr_read_b32 v11, a11
	ds_write2_b32 v55, v8, v4 offset1:16
	ds_write2_b32 v55, v10, v6 offset0:96 offset1:112
	ds_write2_b32 v55, v0, v9 offset0:32 offset1:48
	ds_write2_b32 v55, v5, v1 offset0:64 offset1:80
	ds_write2_b32 v55, v2, v11 offset0:128 offset1:144
	ds_write2_b32 v55, v7, v3 offset0:160 offset1:176
	s_and_saveexec_b64 s[34:35], s[2:3]
	s_cbranch_execz .LBB0_544
; DI void row2_phase(const Params& P, int l, int r_begin, char* smem) {
;     ...
;     if (lane < 16) {
;       const int r = r0 + lane;
;       const float* L = lg + lane * 48;
;       float gl[4]; int gi = 0;
; #pragma unroll
;       for (int j = 0; j < 4; j++) gl[j] = L[j] + P.b_group[l * 4 + j];
;       float gm = gl[0];
; #pragma unroll
;       for (int j = 1; j < 4; j++) if (gl[j] > gm) { gm = gl[j]; gi = j; }
;       float gs = 0.f;
; #pragma unroll
;       for (int j = 0; j < 4; j++) gs += expf(gl[j] - gm);
;       const float pg = 1.f / gs;
;       float el[8];
; #pragma unroll
;       for (int j = 0; j < 8; j++) el[j] = L[4 + gi * 8 + j] + P.b_router[l * 32 + gi * 8 + j];
;       int i0 = 0; float v0 = el[0];
; #pragma unroll
;       for (int j = 1; j < 8; j++) if (el[j] > v0) { v0 = el[j]; i0 = j; }
;       int i1 = -1; float v1 = -3.0e38f;
; #pragma unroll
;       for (int j = 0; j < 8; j++) if (j != i0 && el[j] > v1) { v1 = el[j]; i1 = j; }
	global_load_dwordx4 v[4:7], v149, s[8:9]
	ds_read_b128 v[0:3], v13
	s_mov_b32 s28, 0x3fb8aa3b
	s_mov_b32 s38, 0xc2ce8ed0
	s_mov_b32 s39, 0x42b17218
	v_mov_b32_e32 v33, 0x7f800000
	v_readlane_b32 s48, v253, 35
	v_readlane_b32 s54, v253, 41
	v_readlane_b32 s55, v253, 42
	v_readlane_b32 s49, v253, 36
	v_readlane_b32 s50, v253, 37
	v_readlane_b32 s51, v253, 38
	v_readlane_b32 s52, v253, 39
	v_readlane_b32 s53, v253, 40
	v_readlane_b32 s56, v253, 43
	v_readlane_b32 s57, v253, 44
	v_readlane_b32 s58, v253, 45
	v_readlane_b32 s59, v253, 46
	v_readlane_b32 s60, v253, 47
	v_readlane_b32 s61, v253, 48
	v_readlane_b32 s62, v253, 49
	v_readlane_b32 s63, v253, 50
	s_waitcnt vmcnt(0) lgkmcnt(0)
	v_pk_add_f32 v[0:1], v[0:1], v[4:5]
	s_nop 0
	v_cmp_gt_f32_e32 vcc, v1, v0
	v_add_f32_e32 v2, v2, v6
	v_add_f32_e32 v3, v3, v7
	v_cndmask_b32_e32 v4, v0, v1, vcc
	v_cmp_gt_f32_e64 s[0:1], v2, v4
	s_nop 1
	v_cndmask_b32_e64 v4, v4, v2, s[0:1]
	v_cmp_gt_f32_e64 s[4:5], v3, v4
	s_nop 1
	v_cndmask_b32_e64 v4, v4, v3, s[4:5]
	v_sub_f32_e32 v5, v0, v4
	v_sub_f32_e32 v0, v1, v4
	v_mul_f32_e32 v1, 0x3fb8aa3b, v0
	v_fma_f32 v6, v0, s28, -v1
	v_rndne_f32_e32 v7, v1
	v_fmac_f32_e32 v6, 0x32a5705f, v0
	v_sub_f32_e32 v1, v1, v7
	v_add_f32_e32 v1, v1, v6
	v_exp_f32_e32 v1, v1
	v_cvt_i32_f32_e32 v6, v7
	v_cmp_ngt_f32_e64 s[6:7], s38, v0
	v_ldexp_f32 v1, v1, v6
	s_nop 0
	v_cndmask_b32_e64 v1, 0, v1, s[6:7]
	v_cmp_nlt_f32_e64 s[6:7], s39, v0
	v_sub_f32_e32 v0, v2, v4
	s_nop 0
	v_cndmask_b32_e64 v21, v33, v1, s[6:7]
	v_mul_f32_e32 v1, 0x3fb8aa3b, v0
	v_fma_f32 v2, v0, s28, -v1
	v_rndne_f32_e32 v6, v1
	v_fmac_f32_e32 v2, 0x32a5705f, v0
	v_sub_f32_e32 v1, v1, v6
	v_add_f32_e32 v1, v1, v2
	v_exp_f32_e32 v1, v1
	v_cvt_i32_f32_e32 v2, v6
	v_cmp_ngt_f32_e64 s[6:7], s38, v0
	v_ldexp_f32 v1, v1, v2
	s_nop 0
	v_cndmask_b32_e64 v1, 0, v1, s[6:7]
	v_cmp_nlt_f32_e64 s[6:7], s39, v0
	v_sub_f32_e32 v0, v3, v4
	v_or_b32_e32 v4, v56, v53
	v_cndmask_b32_e64 v30, v33, v1, s[6:7]
	v_mul_f32_e32 v1, 0x3fb8aa3b, v0
	v_fma_f32 v2, v0, s28, -v1
	v_rndne_f32_e32 v3, v1
	v_fmac_f32_e32 v2, 0x32a5705f, v0
	v_sub_f32_e32 v1, v1, v3
	v_add_f32_e32 v1, v1, v2
	v_exp_f32_e32 v1, v1
	v_cvt_i32_f32_e32 v2, v3
	v_cmp_ngt_f32_e64 s[6:7], s38, v0
	v_ldexp_f32 v1, v1, v2
	s_nop 0
	v_cndmask_b32_e64 v1, 0, v1, s[6:7]
	v_cmp_nlt_f32_e64 s[6:7], s39, v0
	v_cndmask_b32_e64 v0, 0, 8, vcc
	v_cndmask_b32_e64 v0, v0, 16, s[0:1]
	v_cndmask_b32_e64 v32, v0, 24, s[4:5]
	v_cndmask_b32_e64 v31, v33, v1, s[6:7]
	v_or_b32_e32 v0, s23, v32
	v_mov_b32_e32 v1, v149
	v_lshl_add_u32 v6, v32, 2, v13
	v_lshl_add_u64 v[10:11], v[0:1], 2, s[54:55]
	ds_read_b128 v[0:3], v6 offset:16
	ds_read_b128 v[6:9], v6 offset:32
	global_load_dwordx4 v[22:25], v[10:11], off offset:16
	global_load_dwordx4 v[26:29], v[10:11], off
	v_mul_f32_e32 v10, 0x3fb8aa3b, v5
	v_fma_f32 v11, v5, s28, -v10
	v_fmac_f32_e32 v11, 0x32a5705f, v5
	v_cmp_ngt_f32_e32 vcc, s38, v5
	s_mov_b32 s6, 0xff61b1e6
	s_waitcnt vmcnt(1) lgkmcnt(0)
	v_add_f32_e32 v6, v6, v22
	v_rndne_f32_e32 v22, v10
	v_sub_f32_e32 v10, v10, v22
	v_add_f32_e32 v10, v10, v11
	v_exp_f32_e32 v10, v10
	v_cvt_i32_f32_e32 v11, v22
	s_waitcnt vmcnt(0)
	v_pk_add_f32 v[0:1], v[0:1], v[26:27]
	v_add_f32_e32 v2, v2, v28
	v_add_f32_e32 v3, v3, v29
	v_ldexp_f32 v10, v10, v11
	v_cndmask_b32_e32 v10, 0, v10, vcc
	v_cmp_nlt_f32_e32 vcc, s39, v5
	v_add_f32_e32 v7, v7, v23
	v_add_f32_e32 v8, v8, v24
	v_cndmask_b32_e32 v5, v33, v10, vcc
	v_cmp_gt_f32_e32 vcc, v1, v0
	v_add_f32_e32 v9, v9, v25
	v_cmp_nlt_f32_e64 s[6:7], s6, v0
	v_cndmask_b32_e32 v11, v0, v1, vcc
	v_cndmask_b32_e64 v10, 0, 1, vcc
	v_cmp_gt_f32_e32 vcc, v2, v11
	v_mov_b32_e32 v22, 0xff61b1e6
	v_add_f32_e32 v5, v5, v21
	v_cndmask_b32_e32 v11, v11, v2, vcc
	v_cndmask_b32_e64 v10, v10, 2, vcc
	v_cmp_gt_f32_e32 vcc, v3, v11
	v_add_f32_e32 v5, v30, v5
	v_add_f32_e32 v5, v31, v5
	v_cndmask_b32_e32 v11, v11, v3, vcc
	v_cndmask_b32_e64 v10, v10, 3, vcc
	v_cmp_gt_f32_e32 vcc, v6, v11
	s_nop 1
	v_cndmask_b32_e32 v11, v11, v6, vcc
	v_cndmask_b32_e64 v10, v10, 4, vcc
	v_cmp_gt_f32_e32 vcc, v7, v11
	s_nop 1
	v_cndmask_b32_e32 v11, v11, v7, vcc
	v_cndmask_b32_e64 v10, v10, 5, vcc
	v_cmp_gt_f32_e32 vcc, v8, v11
	s_nop 1
	v_cndmask_b32_e32 v11, v11, v8, vcc
	v_cndmask_b32_e64 v10, v10, 6, vcc
	v_cmp_ngt_f32_e64 s[0:1], v9, v11
	s_nop 1
	v_cndmask_b32_e64 v10, 7, v10, s[0:1]
	v_cmp_eq_u32_e64 s[4:5], 0, v10
	s_or_b64 s[4:5], s[4:5], s[6:7]
	v_cndmask_b32_e64 v11, v9, v11, s[0:1]
	v_cndmask_b32_e64 v0, v0, v22, s[4:5]
	v_cndmask_b32_e64 v21, 0, -1, s[4:5]
	v_cmp_ne_u32_e64 s[4:5], 1, v10
	v_cmp_gt_f32_e64 s[6:7], v1, v0
	s_and_b64 s[4:5], s[4:5], s[6:7]
	v_cndmask_b32_e64 v0, v0, v1, s[4:5]
	v_cndmask_b32_e64 v21, v21, 1, s[4:5]
	v_cmp_ne_u32_e64 s[4:5], 2, v10
	v_cmp_gt_f32_e64 s[6:7], v2, v0
	s_and_b64 s[4:5], s[4:5], s[6:7]
	v_cndmask_b32_e64 v0, v0, v2, s[4:5]
	v_cndmask_b32_e64 v1, v21, 2, s[4:5]
	v_cmp_ne_u32_e64 s[4:5], 3, v10
	v_cmp_gt_f32_e64 s[6:7], v3, v0
	s_and_b64 s[4:5], s[4:5], s[6:7]
	v_cndmask_b32_e64 v0, v0, v3, s[4:5]
	v_cndmask_b32_e64 v1, v1, 3, s[4:5]
	v_cmp_ne_u32_e64 s[4:5], 4, v10
	v_cmp_gt_f32_e64 s[6:7], v6, v0
	s_and_b64 s[4:5], s[4:5], s[6:7]
	v_cndmask_b32_e64 v0, v0, v6, s[4:5]
	v_cndmask_b32_e64 v1, v1, 4, s[4:5]
	v_cmp_ne_u32_e64 s[4:5], 5, v10
	v_cmp_gt_f32_e64 s[6:7], v7, v0
	s_and_b64 s[4:5], s[4:5], s[6:7]
	v_cndmask_b32_e64 v0, v0, v7, s[4:5]
	v_cndmask_b32_e64 v1, v1, 5, s[4:5]
; DI void row2_phase(const Params& P, int l, int r_begin, char* smem) {
;     ...
;       const float ex = expf(v1 - v0);
;       const float w0 = pg / (1.f + ex), w1 = pg * ex / (1.f + ex);
;       const int e0 = gi * 8 + i0, e1 = gi * 8 + i1;
;       int p0 = atomicAdd(&P.cnt[l * 32 + e0], 1); P.list[(size_t)e0 * LCAP + p0] = 2 * r; P.listW[(size_t)e0 * LCAP + p0] = w0;
;       int p1 = atomicAdd(&P.cnt[l * 32 + e1], 1); P.list[(size_t)e1 * LCAP + p1] = 2 * r + 1; P.listW[(size_t)e1 * LCAP + p1] = w1;
;     }
;     __builtin_amdgcn_wave_barrier();
;   }
	s_and_b64 s[4:5], vcc, s[0:1]
	v_cmp_ngt_f32_e32 vcc, v8, v0
	s_or_b64 vcc, s[4:5], vcc
	v_readlane_b32 s4, v255, 24
	v_cndmask_b32_e32 v0, v8, v0, vcc
	v_cndmask_b32_e32 v1, 6, v1, vcc
	v_cmp_gt_f32_e32 vcc, v9, v0
	s_and_b64 vcc, s[0:1], vcc
	v_div_scale_f32 v2, s[0:1], v5, v5, 1.0
	v_rcp_f32_e32 v3, v2
	v_cndmask_b32_e64 v1, v1, 7, vcc
	v_cndmask_b32_e32 v0, v0, v9, vcc
	v_sub_f32_e32 v0, v0, v11
	v_fma_f32 v6, -v2, v3, 1.0
	v_fmac_f32_e32 v3, v6, v3
	v_div_scale_f32 v6, vcc, 1.0, v5, 1.0
	v_mul_f32_e32 v7, v6, v3
	v_fma_f32 v8, -v2, v7, v6
	v_fmac_f32_e32 v7, v8, v3
	v_fma_f32 v2, -v2, v7, v6
	v_div_fmas_f32 v2, v2, v3, v7
	v_mul_f32_e32 v3, 0x3fb8aa3b, v0
	v_div_fixup_f32 v2, v2, v5, 1.0
	v_fma_f32 v5, v0, s28, -v3
	v_rndne_f32_e32 v6, v3
	v_fmac_f32_e32 v5, 0x32a5705f, v0
	v_sub_f32_e32 v3, v3, v6
	v_add_f32_e32 v3, v3, v5
	v_exp_f32_e32 v3, v3
	v_cvt_i32_f32_e32 v5, v6
	v_cmp_ngt_f32_e32 vcc, s38, v0
	s_mov_b32 s28, 0x21000
	v_readlane_b32 s6, v254, 0
	v_ldexp_f32 v3, v3, v5
	v_cndmask_b32_e32 v3, 0, v3, vcc
	v_cmp_nlt_f32_e32 vcc, s39, v0
	v_readlane_b32 s5, v255, 25
	v_readlane_b32 s7, v254, 1
	v_cndmask_b32_e32 v0, v33, v3, vcc
	v_add_f32_e32 v3, 1.0, v0
	v_div_scale_f32 v5, s[0:1], v3, v3, v2
	v_rcp_f32_e32 v6, v5
	v_mul_f32_e32 v0, v2, v0
	v_fma_f32 v7, -v5, v6, 1.0
	v_fmac_f32_e32 v6, v7, v6
	v_div_scale_f32 v7, vcc, v2, v3, v2
	v_mul_f32_e32 v8, v7, v6
	v_fma_f32 v9, -v5, v8, v7
	v_fmac_f32_e32 v8, v9, v6
	v_fma_f32 v5, -v5, v8, v7
	v_div_fmas_f32 v5, v5, v6, v8
	v_div_fixup_f32 v8, v5, v3, v2
	v_div_scale_f32 v2, s[0:1], v3, v3, v0
	v_rcp_f32_e32 v5, v2
	v_readlane_b32 s0, v253, 63
	v_readlane_b32 s1, v255, 0
	v_fma_f32 v6, -v2, v5, 1.0
	v_fmac_f32_e32 v5, v6, v5
	v_div_scale_f32 v6, vcc, v0, v3, v0
	v_mul_f32_e32 v7, v6, v5
	v_fma_f32 v9, -v2, v7, v6
	v_fmac_f32_e32 v7, v9, v5
	v_fma_f32 v2, -v2, v7, v6
	v_div_fmas_f32 v2, v2, v5, v7
	v_or_b32_e32 v5, v10, v32
	v_div_fixup_f32 v2, v2, v3, v0
	v_add_u32_e32 v3, v1, v32
	v_or_b32_e32 v0, s23, v5
	v_mov_b32_e32 v1, v149
	v_mov_b32_e32 v9, 1
	v_mov_b32_e32 v6, 2
	v_mov_b32_e32 v7, 0x3080
	ds_add_rtn_u32 v7, v7, v6
	v_lshlrev_b32_e32 v0, 2, v5
	v_add_u32_e32 v0, 0x3000, v0
	ds_add_rtn_u32 v0, v0, v9
	v_lshlrev_b32_e32 v1, 2, v3
	v_add_u32_e32 v1, 0x3000, v1
	ds_add_rtn_u32 v1, v1, v9
	v_lshlrev_b32_e32 v6, 1, v4
	v_or_b32_e32 v9, 1, v6
	s_waitcnt lgkmcnt(0)
	v_lshl_or_b32 v0, v0, 5, v5
	v_lshl_or_b32 v1, v1, 5, v3
	v_lshlrev_b32_e32 v7, 4, v7
	v_add_u32_e32 v7, 0x10000, v7
	ds_write_b32 v7, v0
	ds_write_b32 v7, v6 offset:4
	ds_write_b32 v7, v8 offset:8
	ds_write_b32 v7, v1 offset:16
	ds_write_b32 v7, v9 offset:20
	ds_write_b32 v7, v2 offset:24
	s_branch .LBB0_544
.LBB0_551:
	s_or_b64 exec, exec, s[10:11]
	s_waitcnt vmcnt(0)
	s_waitcnt lgkmcnt(0)
	s_barrier
	v_readlane_b32 s0, v253, 63
	v_readlane_b32 s1, v255, 0
	v_readlane_b32 s4, v255, 24
	v_readlane_b32 s5, v255, 25
	v_readlane_b32 s6, v254, 0
	v_readlane_b32 s7, v254, 1
	v_readlane_b32 s8, v255, 26
	v_mov_b32_e32 v84, v172
	v_lshlrev_b32_e32 v85, 2, v84
	s_lshl_b32 s8, s8, 7
	v_cmp_gt_u32_e32 vcc, 32, v84
	s_and_saveexec_b64 s[100:101], vcc
	s_cbranch_execz .Lr2a_skip
	v_add_u32_e32 v86, 0x3000, v85
	ds_read_b32 v87, v86
	v_add_u32_e32 v88, s8, v85
	s_waitcnt lgkmcnt(0)
	global_atomic_add v89, v88, v87, s[0:1] sc0
	v_add_u32_e32 v86, 0x3100, v85
	s_waitcnt vmcnt(0)
	ds_write_b32 v86, v89
	s_waitcnt lgkmcnt(0)
.Lr2a_skip:
	s_or_b64 exec, exec, s[100:101]
	s_barrier
	v_mov_b32_e32 v85, 0x3080
	ds_read_b32 v85, v85
	s_waitcnt lgkmcnt(0)
	v_readfirstlane_b32 s2, v85
	s_mov_b32 s3, 0
.Lr2a_loop:
	s_cmp_lt_u32 s3, s2
	s_cbranch_scc0 .Lr2a_done
	v_add_u32_e32 v86, s3, v84
	v_cmp_gt_u32_e32 vcc, s2, v86
	s_and_saveexec_b64 s[100:101], vcc
	s_cbranch_execz .Lr2a_next
	v_lshlrev_b32_e32 v86, 4, v86
	v_add_u32_e32 v86, 0x10000, v86
	ds_read_b32 v87, v86
	ds_read_b32 v88, v86 offset:4
	ds_read_b32 v89, v86 offset:8
	s_waitcnt lgkmcnt(0)
	v_and_b32_e32 v90, 31, v87
	v_lshrrev_b32_e32 v91, 5, v87
	v_lshlrev_b32_e32 v92, 2, v90
	v_add_u32_e32 v92, 0x3100, v92
	ds_read_b32 v92, v92
	v_mul_u32_u24_e32 v90, 0x21000, v90
	s_waitcnt lgkmcnt(0)
	v_add3_u32 v90, v90, v91, v92
	v_lshlrev_b32_e32 v90, 2, v90
	global_store_dword v90, v88, s[4:5]
	global_store_dword v90, v89, s[6:7]
.Lr2a_next:
	s_or_b64 exec, exec, s[100:101]
	s_add_u32 s3, s3, 0x100
	s_branch .Lr2a_loop
.Lr2a_done:
	s_waitcnt vmcnt(0)
	s_barrier
	v_and_b32_e32 v84, 0xff, v172
	v_lshlrev_b32_e32 v84, 4, v84
	v_add_u32_e32 v84, 0x4000, v84
	ds_read_b128 v[100:103], v84 offset:16384
	ds_read_b128 v[96:99], v84 offset:12288
	ds_read_b128 v[92:95], v84 offset:8192
	ds_read_b128 v[88:91], v84 offset:4096
	ds_read_b128 v[84:87], v84 offset:0
	s_waitcnt lgkmcnt(0)
	s_mov_b64 s[0:1], exec
	v_readlane_b32 s2, v253, 17
	v_readlane_b32 s3, v253, 18
	s_and_b64 s[2:3], s[0:1], s[2:3]
	v_readlane_b32 s22, v255, 26
	v_readlane_b32 s23, v255, 27
	s_mov_b64 exec, s[2:3]
	s_cbranch_execz .LBB0_560
	s_mov_b64 s[4:5], exec
	v_mbcnt_lo_u32_b32 v0, s4, 0
	v_mbcnt_hi_u32_b32 v0, s5, v0
	s_getreg_b32 s6, hwreg(HW_REG_XCC_ID, 0, 4)
	v_cmp_eq_u32_e32 vcc, 0, v0
	s_and_saveexec_b64 s[2:3], vcc
	s_cbranch_execz .LBB0_554
	s_lshl_b32 s6, s6, 6
	s_bcnt1_i32_b64 s4, s[4:5]
	s_and_b32 s6, s6, 0x1c0
	v_mov_b32_e32 v2, s4
	v_readlane_b32 s4, v254, 6
	v_mov_b32_e32 v1, s6
	v_readlane_b32 s5, v254, 7
	s_nop 4
	global_atomic_add v1, v1, v2, s[4:5] sc0

; __global__ void __launch_bounds__(256, 1) fwd_megakernel(Params Pin) {
;   Params P = Pin; bind_ws(P);
;   __shared__ __attribute__((aligned(16))) char smem[147456 + 8192];
	.amdhsa_kernel _Z14fwd_megakernel6Params
		.amdhsa_group_segment_fixed_size 155784
		.amdhsa_private_segment_fixed_size 0
		.amdhsa_kernarg_size 776
		.amdhsa_user_sgpr_count 2
		.amdhsa_user_sgpr_dispatch_ptr 0
		.amdhsa_user_sgpr_queue_ptr 0
		.amdhsa_user_sgpr_kernarg_segment_ptr 1
		.amdhsa_user_sgpr_dispatch_id 0
		.amdhsa_user_sgpr_kernarg_preload_length 0
		.amdhsa_user_sgpr_kernarg_preload_offset 0
		.amdhsa_user_sgpr_private_segment_size 0
		.amdhsa_uses_dynamic_stack 0
		.amdhsa_enable_private_segment 0
		.amdhsa_system_sgpr_workgroup_id_x 1
		.amdhsa_system_sgpr_workgroup_id_y 0
		.amdhsa_system_sgpr_workgroup_id_z 0
		.amdhsa_system_sgpr_workgroup_info 0
		.amdhsa_system_vgpr_workitem_id 2
		.amdhsa_next_free_vgpr 512
		.amdhsa_next_free_sgpr 102
		.amdhsa_accum_offset 256
		.amdhsa_reserve_vcc 1
		.amdhsa_float_round_mode_32 0
		.amdhsa_float_round_mode_16_64 0
		.amdhsa_float_denorm_mode_32 3
		.amdhsa_float_denorm_mode_16_64 3
		.amdhsa_dx10_clamp 1
		.amdhsa_ieee_mode 1
		.amdhsa_fp16_overflow 0
		.amdhsa_tg_split 0
		.amdhsa_exception_fp_ieee_invalid_op 0
		.amdhsa_exception_fp_denorm_src 0
		.amdhsa_exception_fp_ieee_div_zero 0
		.amdhsa_exception_fp_ieee_overflow 0
		.amdhsa_exception_fp_ieee_underflow 0
		.amdhsa_exception_fp_ieee_inexact 0
		.amdhsa_exception_int_div_zero 0
	.end_amdhsa_kernel

; __global__ void __launch_bounds__(256, 1) fwd_megakernel(Params Pin) {
;   Params P = Pin; bind_ws(P);
;   __shared__ __attribute__((aligned(16))) char smem[147456 + 8192];
amdhsa.kernels:
  - .agpr_count:     256
    .args:
      - .offset:         0
        .size:           520
        .value_kind:     by_value
      - .offset:         520
        .size:           4
        .value_kind:     hidden_block_count_x
      - .offset:         524
        .size:           4
        .value_kind:     hidden_block_count_y
      - .offset:         528
        .size:           4
        .value_kind:     hidden_block_count_z
      - .offset:         532
        .size:           2
        .value_kind:     hidden_group_size_x
      - .offset:         534
        .size:           2
        .value_kind:     hidden_group_size_y
      - .offset:         536
        .size:           2
        .value_kind:     hidden_group_size_z
      - .offset:         538
        .size:           2
        .value_kind:     hidden_remainder_x
      - .offset:         540
        .size:           2
        .value_kind:     hidden_remainder_y
      - .offset:         542
        .size:           2
        .value_kind:     hidden_remainder_z
      - .offset:         560
        .size:           8
        .value_kind:     hidden_global_offset_x
      - .offset:         568
        .size:           8
        .value_kind:     hidden_global_offset_y
      - .offset:         576
        .size:           8
        .value_kind:     hidden_global_offset_z
      - .offset:         584
        .size:           2
        .value_kind:     hidden_grid_dims
      - .offset:         608
        .size:           8
        .value_kind:     hidden_multigrid_sync_arg
    .group_segment_fixed_size: 155784
    .kernarg_segment_align: 8
    .kernarg_segment_size: 776
    .language:       OpenCL C
    .language_version:
      - 2
      - 0
    .max_flat_workgroup_size: 256
    .name:           _Z14fwd_megakernel6Params
    .private_segment_fixed_size: 0
    .sgpr_count:     108
    .sgpr_spill_count: 209
    .symbol:         _Z14fwd_megakernel6Params.kd
    .uniform_work_group_size: 1
    .uses_dynamic_stack: false
    .vgpr_count:     512
    .vgpr_spill_count: 0
    .wavefront_size: 64
